# FFN-up K-loop: all six LDS-DMA loads of a k-step issued right after the barrier (first six MFMA slots) instead of spread over the step, for a longer lead on every load
# baseline (speedup 1.0000x reference)
;     ...
;   if (PART != 2) {
;     GEMM_ISSUE(0, 0);
;     if (nk > 1) GEMM_ISSUE(1, 1);
;   }
;   if (PART == 1) return;
;   int st = 0;
;   for (int kt = 0; kt < nk; ++kt) {
;     if (kt + 1 < nk) asm volatile("s_waitcnt vmcnt(6)" ::: "memory");
;     else asm volatile("s_waitcnt vmcnt(0)" ::: "memory");
;     __builtin_amdgcn_s_barrier();
;     asm volatile("" ::: "memory");
;     if (kt + 2 < nk) { const int st2 = (st >= 1) ? st - 1 : 2; GEMM_ISSUE(kt + 2, st2); }
;     const char* la = lds + st * STAGE_B;
;     const char* lb = la + 32768;
;     const unsigned sa_u = (unsigned)(size_t)la + arow_u, sb_u = (unsigned)(size_t)lb + brow_u;
;     const unsigned a0 = sa_u + co0, a1 = sa_u + co1, a2 = sa_u + co2, a3 = sa_u + co3;
;     const unsigned b0 = sb_u + co0, b1 = sb_u + co1, b2 = sb_u + co2, b3 = sb_u + co3;
;     {
;       bf16x8 p0, p1, q0, q1, u0, u1, w0, w1;
;       asm volatile(
;         "ds_read_b128 %4, %12\n\tds_read_b128 %5, %12 offset:4096\n\tds_read_b128 %6, %16\n\tds_read_b128 %7, %16 offset:4096\n\t"
;         "ds_read_b128 %8, %13\n\tds_read_b128 %9, %13 offset:4096\n\tds_read_b128 %10, %17\n\tds_read_b128 %11, %17 offset:4096\n\t"
;         "s_waitcnt lgkmcnt(4)\n\t"
;         "v_mfma_f32_32x32x16_bf16 %0, %4, %6, %0\n\tv_mfma_f32_32x32x16_bf16 %1, %4, %7, %1\n\tv_mfma_f32_32x32x16_bf16 %2, %5, %6, %2\n\tv_mfma_f32_32x32x16_bf16 %3, %5, %7, %3\n\t"
;         "ds_read_b128 %4, %14\n\tds_read_b128 %5, %14 offset:4096\n\tds_read_b128 %6, %18\n\tds_read_b128 %7, %18 offset:4096\n\t"
;         "s_waitcnt lgkmcnt(4)\n\t"
;         "v_mfma_f32_32x32x16_bf16 %0, %8, %10, %0\n\tv_mfma_f32_32x32x16_bf16 %1, %8, %11, %1\n\tv_mfma_f32_32x32x16_bf16 %2, %9, %10, %2\n\tv_mfma_f32_32x32x16_bf16 %3, %9, %11, %3\n\t"
;         "ds_read_b128 %8, %15\n\tds_read_b128 %9, %15 offset:4096\n\tds_read_b128 %10, %19\n\tds_read_b128 %11, %19 offset:4096\n\t"
;         "s_waitcnt lgkmcnt(4)\n\t"
;         "v_mfma_f32_32x32x16_bf16 %0, %4, %6, %0\n\tv_mfma_f32_32x32x16_bf16 %1, %4, %7, %1\n\tv_mfma_f32_32x32x16_bf16 %2, %5, %6, %2\n\tv_mfma_f32_32x32x16_bf16 %3, %5, %7, %3\n\t"
;         "s_waitcnt lgkmcnt(0)\n\t"
;         "v_mfma_f32_32x32x16_bf16 %0, %8, %10, %0\n\tv_mfma_f32_32x32x16_bf16 %1, %8, %11, %1\n\tv_mfma_f32_32x32x16_bf16 %2, %9, %10, %2\n\tv_mfma_f32_32x32x16_bf16 %3, %9, %11, %3"
.Ly11_w0:
	s_barrier
	s_cmp_eq_u32 s100, 1
	s_cbranch_scc1 .Ly11_v1
	s_cmp_eq_u32 s100, 2
	s_cbranch_scc1 .Ly11_v2
	ds_read_b128 v[84:87], v76
	ds_read_b128 v[88:91], v76 offset:2048
	ds_read_b128 v[92:95], v76 offset:4096
	ds_read_b128 v[96:99], v76 offset:6144
	ds_read_b128 v[100:103], v78
	ds_read_b128 v[104:107], v78 offset:2048
	ds_read_b128 v[108:111], v78 offset:4096
	ds_read_b128 v[112:115], v78 offset:6144
	s_mov_b32 s24, 0x100
	s_mov_b32 s25, 0
	s_add_u32 m0, s30, 0x18000
	v_lshl_add_u64 v[124:125], v[64:65], 0, s[24:25]
	global_load_lds_dwordx4 v[124:125], off
	s_add_u32 m0, s30, 0x1a000
	v_lshl_add_u64 v[126:127], v[66:67], 0, s[24:25]
	global_load_lds_dwordx4 v[126:127], off
	s_add_u32 m0, s30, 0x1c000
	v_lshl_add_u64 v[124:125], v[68:69], 0, s[24:25]
	global_load_lds_dwordx4 v[124:125], off
	s_add_u32 m0, s30, 0x1e000
	v_lshl_add_u64 v[126:127], v[70:71], 0, s[24:25]
	global_load_lds_dwordx4 v[126:127], off
	s_add_u32 m0, s30, 0x20000
	v_lshl_add_u64 v[124:125], v[72:73], 0, s[24:25]
	global_load_lds_dwordx4 v[124:125], off
	s_add_u32 m0, s30, 0x22000
	v_lshl_add_u64 v[126:127], v[74:75], 0, s[24:25]
	global_load_lds_dwordx4 v[126:127], off
	ds_read_b128 v[136:139], v77
	ds_read_b128 v[140:143], v77 offset:2048
	ds_read_b128 v[144:147], v77 offset:4096
	ds_read_b128 v[148:151], v77 offset:6144
	ds_read_b128 v[152:155], v79
	ds_read_b128 v[156:159], v79 offset:2048
	ds_read_b128 v[160:163], v79 offset:4096
	ds_read_b128 v[164:167], v79 offset:6144
	s_waitcnt lgkmcnt(8)
	v_mfma_f32_16x16x32_bf16 v[0:3], v[84:87], v[100:103], v[0:3]
	v_mfma_f32_16x16x32_bf16 v[4:7], v[84:87], v[104:107], v[4:7]
	v_mfma_f32_16x16x32_bf16 v[8:11], v[84:87], v[108:111], v[8:11]
	v_mfma_f32_16x16x32_bf16 v[12:15], v[84:87], v[112:115], v[12:15]
	v_mfma_f32_16x16x32_bf16 v[16:19], v[88:91], v[100:103], v[16:19]
	v_mfma_f32_16x16x32_bf16 v[20:23], v[88:91], v[104:107], v[20:23]
	v_mfma_f32_16x16x32_bf16 v[24:27], v[88:91], v[108:111], v[24:27]
	v_mfma_f32_16x16x32_bf16 v[28:31], v[88:91], v[112:115], v[28:31]
	v_mfma_f32_16x16x32_bf16 v[32:35], v[92:95], v[100:103], v[32:35]
	v_mfma_f32_16x16x32_bf16 v[36:39], v[92:95], v[104:107], v[36:39]
	v_mfma_f32_16x16x32_bf16 v[40:43], v[92:95], v[108:111], v[40:43]
	v_mfma_f32_16x16x32_bf16 v[44:47], v[92:95], v[112:115], v[44:47]
	v_mfma_f32_16x16x32_bf16 v[48:51], v[96:99], v[100:103], v[48:51]
	v_mfma_f32_16x16x32_bf16 v[52:55], v[96:99], v[104:107], v[52:55]
	v_mfma_f32_16x16x32_bf16 v[56:59], v[96:99], v[108:111], v[56:59]
	v_mfma_f32_16x16x32_bf16 v[60:63], v[96:99], v[112:115], v[60:63]
	s_waitcnt vmcnt(6) lgkmcnt(0)
	s_barrier
	ds_read_b128 v[84:87], v76 offset:49152
	ds_read_b128 v[88:91], v76 offset:51200
	ds_read_b128 v[92:95], v76 offset:53248
	ds_read_b128 v[96:99], v76 offset:55296
	ds_read_b128 v[100:103], v78 offset:49152
	ds_read_b128 v[104:107], v78 offset:51200
	ds_read_b128 v[108:111], v78 offset:53248
	ds_read_b128 v[112:115], v78 offset:55296
	v_mfma_f32_16x16x32_bf16 v[0:3], v[136:139], v[152:155], v[0:3]
	s_mov_b32 s24, 0x180
	s_mov_b32 s25, 0
	s_mov_b32 m0, s30
	v_lshl_add_u64 v[124:125], v[64:65], 0, s[24:25]
	global_load_lds_dwordx4 v[124:125], off
	v_mfma_f32_16x16x32_bf16 v[4:7], v[136:139], v[156:159], v[4:7]
	s_add_u32 m0, s30, 0x2000
	v_lshl_add_u64 v[126:127], v[66:67], 0, s[24:25]
	global_load_lds_dwordx4 v[126:127], off
	v_mfma_f32_16x16x32_bf16 v[8:11], v[136:139], v[160:163], v[8:11]
	s_add_u32 m0, s30, 0x4000
	v_lshl_add_u64 v[124:125], v[68:69], 0, s[24:25]
	global_load_lds_dwordx4 v[124:125], off
	v_mfma_f32_16x16x32_bf16 v[12:15], v[136:139], v[164:167], v[12:15]
	s_add_u32 m0, s30, 0x6000
	v_lshl_add_u64 v[126:127], v[70:71], 0, s[24:25]
	global_load_lds_dwordx4 v[126:127], off
	v_mfma_f32_16x16x32_bf16 v[16:19], v[140:143], v[152:155], v[16:19]
	s_add_u32 m0, s30, 0x8000
	v_lshl_add_u64 v[124:125], v[72:73], 0, s[24:25]
	global_load_lds_dwordx4 v[124:125], off
	v_mfma_f32_16x16x32_bf16 v[20:23], v[140:143], v[156:159], v[20:23]
	s_add_u32 m0, s30, 0xa000
	v_lshl_add_u64 v[126:127], v[74:75], 0, s[24:25]
	global_load_lds_dwordx4 v[126:127], off
	v_mfma_f32_16x16x32_bf16 v[24:27], v[140:143], v[160:163], v[24:27]
	v_mfma_f32_16x16x32_bf16 v[28:31], v[140:143], v[164:167], v[28:31]
	v_mfma_f32_16x16x32_bf16 v[32:35], v[144:147], v[152:155], v[32:35]
	v_mfma_f32_16x16x32_bf16 v[36:39], v[144:147], v[156:159], v[36:39]
	v_mfma_f32_16x16x32_bf16 v[40:43], v[144:147], v[160:163], v[40:43]
	v_mfma_f32_16x16x32_bf16 v[44:47], v[144:147], v[164:167], v[44:47]
	v_mfma_f32_16x16x32_bf16 v[48:51], v[148:151], v[152:155], v[48:51]
	v_mfma_f32_16x16x32_bf16 v[52:55], v[148:151], v[156:159], v[52:55]
	v_mfma_f32_16x16x32_bf16 v[56:59], v[148:151], v[160:163], v[56:59]
	v_mfma_f32_16x16x32_bf16 v[60:63], v[148:151], v[164:167], v[60:63]
	ds_read_b128 v[136:139], v77 offset:49152
	ds_read_b128 v[140:143], v77 offset:51200
	ds_read_b128 v[144:147], v77 offset:53248
	ds_read_b128 v[148:151], v77 offset:55296
	ds_read_b128 v[152:155], v79 offset:49152
	ds_read_b128 v[156:159], v79 offset:51200
	ds_read_b128 v[160:163], v79 offset:53248
	ds_read_b128 v[164:167], v79 offset:55296
	s_waitcnt lgkmcnt(8)
	v_mfma_f32_16x16x32_bf16 v[0:3], v[84:87], v[100:103], v[0:3]
	v_mfma_f32_16x16x32_bf16 v[4:7], v[84:87], v[104:107], v[4:7]
	v_mfma_f32_16x16x32_bf16 v[8:11], v[84:87], v[108:111], v[8:11]
	v_mfma_f32_16x16x32_bf16 v[12:15], v[84:87], v[112:115], v[12:15]
	v_mfma_f32_16x16x32_bf16 v[16:19], v[88:91], v[100:103], v[16:19]
	v_mfma_f32_16x16x32_bf16 v[20:23], v[88:91], v[104:107], v[20:23]
	v_mfma_f32_16x16x32_bf16 v[24:27], v[88:91], v[108:111], v[24:27]
	v_mfma_f32_16x16x32_bf16 v[28:31], v[88:91], v[112:115], v[28:31]
	v_mfma_f32_16x16x32_bf16 v[32:35], v[92:95], v[100:103], v[32:35]
	v_mfma_f32_16x16x32_bf16 v[36:39], v[92:95], v[104:107], v[36:39]
	v_mfma_f32_16x16x32_bf16 v[40:43], v[92:95], v[108:111], v[40:43]
	v_mfma_f32_16x16x32_bf16 v[44:47], v[92:95], v[112:115], v[44:47]
	v_mfma_f32_16x16x32_bf16 v[48:51], v[96:99], v[100:103], v[48:51]
	v_mfma_f32_16x16x32_bf16 v[52:55], v[96:99], v[104:107], v[52:55]
	v_mfma_f32_16x16x32_bf16 v[56:59], v[96:99], v[108:111], v[56:59]
	v_mfma_f32_16x16x32_bf16 v[60:63], v[96:99], v[112:115], v[60:63]
	s_waitcnt vmcnt(6) lgkmcnt(0)
	s_barrier
;     ...
;   for (int kt = 0; kt < nk; ++kt) {
;     if (kt + 1 < nk) asm volatile("s_waitcnt vmcnt(6)" ::: "memory");
;     else asm volatile("s_waitcnt vmcnt(0)" ::: "memory");
;     __builtin_amdgcn_s_barrier();
;     asm volatile("" ::: "memory");
;     if (kt + 2 < nk) { const int st2 = (st >= 1) ? st - 1 : 2; GEMM_ISSUE(kt + 2, st2); }
;     const char* la = lds + st * STAGE_B;
;     const char* lb = la + 32768;
;     const unsigned sa_u = (unsigned)(size_t)la + arow_u, sb_u = (unsigned)(size_t)lb + brow_u;
;     const unsigned a0 = sa_u + co0, a1 = sa_u + co1, a2 = sa_u + co2, a3 = sa_u + co3;
;     const unsigned b0 = sb_u + co0, b1 = sb_u + co1, b2 = sb_u + co2, b3 = sb_u + co3;
;     {
;       bf16x8 p0, p1, q0, q1, u0, u1, w0, w1;
;       asm volatile(
;         "ds_read_b128 %4, %12\n\tds_read_b128 %5, %12 offset:4096\n\tds_read_b128 %6, %16\n\tds_read_b128 %7, %16 offset:4096\n\t"
;         "ds_read_b128 %8, %13\n\tds_read_b128 %9, %13 offset:4096\n\tds_read_b128 %10, %17\n\tds_read_b128 %11, %17 offset:4096\n\t"
;         "s_waitcnt lgkmcnt(4)\n\t"
;         "v_mfma_f32_32x32x16_bf16 %0, %4, %6, %0\n\tv_mfma_f32_32x32x16_bf16 %1, %4, %7, %1\n\tv_mfma_f32_32x32x16_bf16 %2, %5, %6, %2\n\tv_mfma_f32_32x32x16_bf16 %3, %5, %7, %3\n\t"
;         "ds_read_b128 %4, %14\n\tds_read_b128 %5, %14 offset:4096\n\tds_read_b128 %6, %18\n\tds_read_b128 %7, %18 offset:4096\n\t"
;         "s_waitcnt lgkmcnt(4)\n\t"
;         "v_mfma_f32_32x32x16_bf16 %0, %8, %10, %0\n\tv_mfma_f32_32x32x16_bf16 %1, %8, %11, %1\n\tv_mfma_f32_32x32x16_bf16 %2, %9, %10, %2\n\tv_mfma_f32_32x32x16_bf16 %3, %9, %11, %3\n\t"
;         "ds_read_b128 %8, %15\n\tds_read_b128 %9, %15 offset:4096\n\tds_read_b128 %10, %19\n\tds_read_b128 %11, %19 offset:4096\n\t"
;         "s_waitcnt lgkmcnt(4)\n\t"
;         "v_mfma_f32_32x32x16_bf16 %0, %4, %6, %0\n\tv_mfma_f32_32x32x16_bf16 %1, %4, %7, %1\n\tv_mfma_f32_32x32x16_bf16 %2, %5, %6, %2\n\tv_mfma_f32_32x32x16_bf16 %3, %5, %7, %3\n\t"
;         "s_waitcnt lgkmcnt(0)\n\t"
;         "v_mfma_f32_32x32x16_bf16 %0, %8, %10, %0\n\tv_mfma_f32_32x32x16_bf16 %1, %8, %11, %1\n\tv_mfma_f32_32x32x16_bf16 %2, %9, %10, %2\n\tv_mfma_f32_32x32x16_bf16 %3, %9, %11, %3"
;         : "+v"(acc[0][0]), "+v"(acc[0][1]), "+v"(acc[1][0]), "+v"(acc[1][1]),
;           "=&v"(p0), "=&v"(p1), "=&v"(q0), "=&v"(q1), "=&v"(u0), "=&v"(u1), "=&v"(w0), "=&v"(w1)
	ds_read_b128 v[84:87], v80
	ds_read_b128 v[88:91], v80 offset:2048
	ds_read_b128 v[92:95], v80 offset:4096
	ds_read_b128 v[96:99], v80 offset:6144
	ds_read_b128 v[100:103], v82
	ds_read_b128 v[104:107], v82 offset:2048
	ds_read_b128 v[108:111], v82 offset:4096
	ds_read_b128 v[112:115], v82 offset:6144
	v_mfma_f32_16x16x32_bf16 v[0:3], v[136:139], v[152:155], v[0:3]
	s_mov_b32 s24, 0x200
	s_mov_b32 s25, 0
	s_add_u32 m0, s30, 0xc000
	v_lshl_add_u64 v[124:125], v[64:65], 0, s[24:25]
	global_load_lds_dwordx4 v[124:125], off
	v_mfma_f32_16x16x32_bf16 v[4:7], v[136:139], v[156:159], v[4:7]
	s_add_u32 m0, s30, 0xe000
	v_lshl_add_u64 v[126:127], v[66:67], 0, s[24:25]
	global_load_lds_dwordx4 v[126:127], off
	v_mfma_f32_16x16x32_bf16 v[8:11], v[136:139], v[160:163], v[8:11]
	s_add_u32 m0, s30, 0x10000
	v_lshl_add_u64 v[124:125], v[68:69], 0, s[24:25]
	global_load_lds_dwordx4 v[124:125], off
	v_mfma_f32_16x16x32_bf16 v[12:15], v[136:139], v[164:167], v[12:15]
	s_add_u32 m0, s30, 0x12000
	v_lshl_add_u64 v[126:127], v[70:71], 0, s[24:25]
	global_load_lds_dwordx4 v[126:127], off
	v_mfma_f32_16x16x32_bf16 v[16:19], v[140:143], v[152:155], v[16:19]
	s_add_u32 m0, s30, 0x14000
	v_lshl_add_u64 v[124:125], v[72:73], 0, s[24:25]
	global_load_lds_dwordx4 v[124:125], off
	v_mfma_f32_16x16x32_bf16 v[20:23], v[140:143], v[156:159], v[20:23]
	s_add_u32 m0, s30, 0x16000
	v_lshl_add_u64 v[126:127], v[74:75], 0, s[24:25]
	global_load_lds_dwordx4 v[126:127], off
	v_mfma_f32_16x16x32_bf16 v[24:27], v[140:143], v[160:163], v[24:27]
	v_mfma_f32_16x16x32_bf16 v[28:31], v[140:143], v[164:167], v[28:31]
	v_mfma_f32_16x16x32_bf16 v[32:35], v[144:147], v[152:155], v[32:35]
	v_mfma_f32_16x16x32_bf16 v[36:39], v[144:147], v[156:159], v[36:39]
	v_mfma_f32_16x16x32_bf16 v[40:43], v[144:147], v[160:163], v[40:43]
	v_mfma_f32_16x16x32_bf16 v[44:47], v[144:147], v[164:167], v[44:47]
	v_mfma_f32_16x16x32_bf16 v[48:51], v[148:151], v[152:155], v[48:51]
	v_mfma_f32_16x16x32_bf16 v[52:55], v[148:151], v[156:159], v[52:55]
	v_mfma_f32_16x16x32_bf16 v[56:59], v[148:151], v[160:163], v[56:59]
	v_mfma_f32_16x16x32_bf16 v[60:63], v[148:151], v[164:167], v[60:63]
	ds_read_b128 v[136:139], v81
	ds_read_b128 v[140:143], v81 offset:2048
	ds_read_b128 v[144:147], v81 offset:4096
	ds_read_b128 v[148:151], v81 offset:6144
	ds_read_b128 v[152:155], v83
	ds_read_b128 v[156:159], v83 offset:2048
	ds_read_b128 v[160:163], v83 offset:4096
	ds_read_b128 v[164:167], v83 offset:6144
	s_waitcnt lgkmcnt(8)
	v_mfma_f32_16x16x32_bf16 v[0:3], v[84:87], v[100:103], v[0:3]
	v_mfma_f32_16x16x32_bf16 v[4:7], v[84:87], v[104:107], v[4:7]
	v_mfma_f32_16x16x32_bf16 v[8:11], v[84:87], v[108:111], v[8:11]
	v_mfma_f32_16x16x32_bf16 v[12:15], v[84:87], v[112:115], v[12:15]
	v_mfma_f32_16x16x32_bf16 v[16:19], v[88:91], v[100:103], v[16:19]
	v_mfma_f32_16x16x32_bf16 v[20:23], v[88:91], v[104:107], v[20:23]
	v_mfma_f32_16x16x32_bf16 v[24:27], v[88:91], v[108:111], v[24:27]
	v_mfma_f32_16x16x32_bf16 v[28:31], v[88:91], v[112:115], v[28:31]
	v_mfma_f32_16x16x32_bf16 v[32:35], v[92:95], v[100:103], v[32:35]
	v_mfma_f32_16x16x32_bf16 v[36:39], v[92:95], v[104:107], v[36:39]
	v_mfma_f32_16x16x32_bf16 v[40:43], v[92:95], v[108:111], v[40:43]
	v_mfma_f32_16x16x32_bf16 v[44:47], v[92:95], v[112:115], v[44:47]
	v_mfma_f32_16x16x32_bf16 v[48:51], v[96:99], v[100:103], v[48:51]
	v_mfma_f32_16x16x32_bf16 v[52:55], v[96:99], v[104:107], v[52:55]
	v_mfma_f32_16x16x32_bf16 v[56:59], v[96:99], v[108:111], v[56:59]
	v_mfma_f32_16x16x32_bf16 v[60:63], v[96:99], v[112:115], v[60:63]
	s_waitcnt vmcnt(6) lgkmcnt(0)
	s_barrier
	ds_read_b128 v[84:87], v76
	ds_read_b128 v[88:91], v76 offset:2048
	ds_read_b128 v[92:95], v76 offset:4096
	ds_read_b128 v[96:99], v76 offset:6144
	ds_read_b128 v[100:103], v78
	ds_read_b128 v[104:107], v78 offset:2048
	ds_read_b128 v[108:111], v78 offset:4096
	ds_read_b128 v[112:115], v78 offset:6144
	v_mfma_f32_16x16x32_bf16 v[0:3], v[136:139], v[152:155], v[0:3]
	s_mov_b32 s24, 0x280
	s_mov_b32 s25, 0
	s_add_u32 m0, s30, 0x18000
	v_lshl_add_u64 v[124:125], v[64:65], 0, s[24:25]
	global_load_lds_dwordx4 v[124:125], off
	v_mfma_f32_16x16x32_bf16 v[4:7], v[136:139], v[156:159], v[4:7]
	s_add_u32 m0, s30, 0x1a000
	v_lshl_add_u64 v[126:127], v[66:67], 0, s[24:25]
	global_load_lds_dwordx4 v[126:127], off
	v_mfma_f32_16x16x32_bf16 v[8:11], v[136:139], v[160:163], v[8:11]
	s_add_u32 m0, s30, 0x1c000
	v_lshl_add_u64 v[124:125], v[68:69], 0, s[24:25]
	global_load_lds_dwordx4 v[124:125], off
	v_mfma_f32_16x16x32_bf16 v[12:15], v[136:139], v[164:167], v[12:15]
	s_add_u32 m0, s30, 0x1e000
	v_lshl_add_u64 v[126:127], v[70:71], 0, s[24:25]
	global_load_lds_dwordx4 v[126:127], off
	v_mfma_f32_16x16x32_bf16 v[16:19], v[140:143], v[152:155], v[16:19]
	s_add_u32 m0, s30, 0x20000
	v_lshl_add_u64 v[124:125], v[72:73], 0, s[24:25]
	global_load_lds_dwordx4 v[124:125], off
	v_mfma_f32_16x16x32_bf16 v[20:23], v[140:143], v[156:159], v[20:23]
	s_add_u32 m0, s30, 0x22000
	v_lshl_add_u64 v[126:127], v[74:75], 0, s[24:25]
	global_load_lds_dwordx4 v[126:127], off
	v_mfma_f32_16x16x32_bf16 v[24:27], v[140:143], v[160:163], v[24:27]
	v_mfma_f32_16x16x32_bf16 v[28:31], v[140:143], v[164:167], v[28:31]
	v_mfma_f32_16x16x32_bf16 v[32:35], v[144:147], v[152:155], v[32:35]
	v_mfma_f32_16x16x32_bf16 v[36:39], v[144:147], v[156:159], v[36:39]
	v_mfma_f32_16x16x32_bf16 v[40:43], v[144:147], v[160:163], v[40:43]
	v_mfma_f32_16x16x32_bf16 v[44:47], v[144:147], v[164:167], v[44:47]
	v_mfma_f32_16x16x32_bf16 v[48:51], v[148:151], v[152:155], v[48:51]
	v_mfma_f32_16x16x32_bf16 v[52:55], v[148:151], v[156:159], v[52:55]
	v_mfma_f32_16x16x32_bf16 v[56:59], v[148:151], v[160:163], v[56:59]
	v_mfma_f32_16x16x32_bf16 v[60:63], v[148:151], v[164:167], v[60:63]
	ds_read_b128 v[136:139], v77
	ds_read_b128 v[140:143], v77 offset:2048
	ds_read_b128 v[144:147], v77 offset:4096
	ds_read_b128 v[148:151], v77 offset:6144
	ds_read_b128 v[152:155], v79
	ds_read_b128 v[156:159], v79 offset:2048
	ds_read_b128 v[160:163], v79 offset:4096
	ds_read_b128 v[164:167], v79 offset:6144
	s_waitcnt lgkmcnt(8)
;     ...
;   for (int kt = 0; kt < nk; ++kt) {
;     if (kt + 1 < nk) asm volatile("s_waitcnt vmcnt(6)" ::: "memory");
;     else asm volatile("s_waitcnt vmcnt(0)" ::: "memory");
;     __builtin_amdgcn_s_barrier();
;     asm volatile("" ::: "memory");
;     if (kt + 2 < nk) { const int st2 = (st >= 1) ? st - 1 : 2; GEMM_ISSUE(kt + 2, st2); }
;     const char* la = lds + st * STAGE_B;
;     const char* lb = la + 32768;
;     const unsigned sa_u = (unsigned)(size_t)la + arow_u, sb_u = (unsigned)(size_t)lb + brow_u;
;     const unsigned a0 = sa_u + co0, a1 = sa_u + co1, a2 = sa_u + co2, a3 = sa_u + co3;
;     const unsigned b0 = sb_u + co0, b1 = sb_u + co1, b2 = sb_u + co2, b3 = sb_u + co3;
;     {
;       bf16x8 p0, p1, q0, q1, u0, u1, w0, w1;
;       asm volatile(
;         "ds_read_b128 %4, %12\n\tds_read_b128 %5, %12 offset:4096\n\tds_read_b128 %6, %16\n\tds_read_b128 %7, %16 offset:4096\n\t"
;         "ds_read_b128 %8, %13\n\tds_read_b128 %9, %13 offset:4096\n\tds_read_b128 %10, %17\n\tds_read_b128 %11, %17 offset:4096\n\t"
;         "s_waitcnt lgkmcnt(4)\n\t"
;         "v_mfma_f32_32x32x16_bf16 %0, %4, %6, %0\n\tv_mfma_f32_32x32x16_bf16 %1, %4, %7, %1\n\tv_mfma_f32_32x32x16_bf16 %2, %5, %6, %2\n\tv_mfma_f32_32x32x16_bf16 %3, %5, %7, %3\n\t"
;         "ds_read_b128 %4, %14\n\tds_read_b128 %5, %14 offset:4096\n\tds_read_b128 %6, %18\n\tds_read_b128 %7, %18 offset:4096\n\t"
;         "s_waitcnt lgkmcnt(4)\n\t"
;         "v_mfma_f32_32x32x16_bf16 %0, %8, %10, %0\n\tv_mfma_f32_32x32x16_bf16 %1, %8, %11, %1\n\tv_mfma_f32_32x32x16_bf16 %2, %9, %10, %2\n\tv_mfma_f32_32x32x16_bf16 %3, %9, %11, %3\n\t"
;         "ds_read_b128 %8, %15\n\tds_read_b128 %9, %15 offset:4096\n\tds_read_b128 %10, %19\n\tds_read_b128 %11, %19 offset:4096\n\t"
;         "s_waitcnt lgkmcnt(4)\n\t"
;         "v_mfma_f32_32x32x16_bf16 %0, %4, %6, %0\n\tv_mfma_f32_32x32x16_bf16 %1, %4, %7, %1\n\tv_mfma_f32_32x32x16_bf16 %2, %5, %6, %2\n\tv_mfma_f32_32x32x16_bf16 %3, %5, %7, %3\n\t"
;         "s_waitcnt lgkmcnt(0)\n\t"
;         "v_mfma_f32_32x32x16_bf16 %0, %8, %10, %0\n\tv_mfma_f32_32x32x16_bf16 %1, %8, %11, %1\n\tv_mfma_f32_32x32x16_bf16 %2, %9, %10, %2\n\tv_mfma_f32_32x32x16_bf16 %3, %9, %11, %3"
;         : "+v"(acc[0][0]), "+v"(acc[0][1]), "+v"(acc[1][0]), "+v"(acc[1][1]),
;           "=&v"(p0), "=&v"(p1), "=&v"(q0), "=&v"(q1), "=&v"(u0), "=&v"(u1), "=&v"(w0), "=&v"(w1)
	v_mfma_f32_16x16x32_bf16 v[0:3], v[84:87], v[100:103], v[0:3]
	v_mfma_f32_16x16x32_bf16 v[4:7], v[84:87], v[104:107], v[4:7]
	v_mfma_f32_16x16x32_bf16 v[8:11], v[84:87], v[108:111], v[8:11]
	v_mfma_f32_16x16x32_bf16 v[12:15], v[84:87], v[112:115], v[12:15]
	v_mfma_f32_16x16x32_bf16 v[16:19], v[88:91], v[100:103], v[16:19]
	v_mfma_f32_16x16x32_bf16 v[20:23], v[88:91], v[104:107], v[20:23]
	v_mfma_f32_16x16x32_bf16 v[24:27], v[88:91], v[108:111], v[24:27]
	v_mfma_f32_16x16x32_bf16 v[28:31], v[88:91], v[112:115], v[28:31]
	v_mfma_f32_16x16x32_bf16 v[32:35], v[92:95], v[100:103], v[32:35]
	v_mfma_f32_16x16x32_bf16 v[36:39], v[92:95], v[104:107], v[36:39]
	v_mfma_f32_16x16x32_bf16 v[40:43], v[92:95], v[108:111], v[40:43]
	v_mfma_f32_16x16x32_bf16 v[44:47], v[92:95], v[112:115], v[44:47]
	v_mfma_f32_16x16x32_bf16 v[48:51], v[96:99], v[100:103], v[48:51]
	v_mfma_f32_16x16x32_bf16 v[52:55], v[96:99], v[104:107], v[52:55]
	v_mfma_f32_16x16x32_bf16 v[56:59], v[96:99], v[108:111], v[56:59]
	v_mfma_f32_16x16x32_bf16 v[60:63], v[96:99], v[112:115], v[60:63]
	s_waitcnt vmcnt(6) lgkmcnt(0)
	s_barrier
	ds_read_b128 v[84:87], v76 offset:49152
	ds_read_b128 v[88:91], v76 offset:51200
	ds_read_b128 v[92:95], v76 offset:53248
	ds_read_b128 v[96:99], v76 offset:55296
	ds_read_b128 v[100:103], v78 offset:49152
	ds_read_b128 v[104:107], v78 offset:51200
	ds_read_b128 v[108:111], v78 offset:53248
	ds_read_b128 v[112:115], v78 offset:55296
	v_mfma_f32_16x16x32_bf16 v[0:3], v[136:139], v[152:155], v[0:3]
	s_mov_b32 s24, 0x300
	s_mov_b32 s25, 0
	s_mov_b32 m0, s30
	v_lshl_add_u64 v[124:125], v[64:65], 0, s[24:25]
	global_load_lds_dwordx4 v[124:125], off
	v_mfma_f32_16x16x32_bf16 v[4:7], v[136:139], v[156:159], v[4:7]
	s_add_u32 m0, s30, 0x2000
	v_lshl_add_u64 v[126:127], v[66:67], 0, s[24:25]
	global_load_lds_dwordx4 v[126:127], off
	v_mfma_f32_16x16x32_bf16 v[8:11], v[136:139], v[160:163], v[8:11]
	s_add_u32 m0, s30, 0x4000
	v_lshl_add_u64 v[124:125], v[68:69], 0, s[24:25]
	global_load_lds_dwordx4 v[124:125], off
	v_mfma_f32_16x16x32_bf16 v[12:15], v[136:139], v[164:167], v[12:15]
	s_add_u32 m0, s30, 0x6000
	v_lshl_add_u64 v[126:127], v[70:71], 0, s[24:25]
	global_load_lds_dwordx4 v[126:127], off
	v_mfma_f32_16x16x32_bf16 v[16:19], v[140:143], v[152:155], v[16:19]
	s_add_u32 m0, s30, 0x8000
	v_lshl_add_u64 v[124:125], v[72:73], 0, s[24:25]
	global_load_lds_dwordx4 v[124:125], off
	v_mfma_f32_16x16x32_bf16 v[20:23], v[140:143], v[156:159], v[20:23]
	s_add_u32 m0, s30, 0xa000
	v_lshl_add_u64 v[126:127], v[74:75], 0, s[24:25]
	global_load_lds_dwordx4 v[126:127], off
	v_mfma_f32_16x16x32_bf16 v[24:27], v[140:143], v[160:163], v[24:27]
	v_mfma_f32_16x16x32_bf16 v[28:31], v[140:143], v[164:167], v[28:31]
	v_mfma_f32_16x16x32_bf16 v[32:35], v[144:147], v[152:155], v[32:35]
	v_mfma_f32_16x16x32_bf16 v[36:39], v[144:147], v[156:159], v[36:39]
	v_mfma_f32_16x16x32_bf16 v[40:43], v[144:147], v[160:163], v[40:43]
	v_mfma_f32_16x16x32_bf16 v[44:47], v[144:147], v[164:167], v[44:47]
	v_mfma_f32_16x16x32_bf16 v[48:51], v[148:151], v[152:155], v[48:51]
	v_mfma_f32_16x16x32_bf16 v[52:55], v[148:151], v[156:159], v[52:55]
	v_mfma_f32_16x16x32_bf16 v[56:59], v[148:151], v[160:163], v[56:59]
	v_mfma_f32_16x16x32_bf16 v[60:63], v[148:151], v[164:167], v[60:63]
	ds_read_b128 v[136:139], v77 offset:49152
	ds_read_b128 v[140:143], v77 offset:51200
	ds_read_b128 v[144:147], v77 offset:53248
	ds_read_b128 v[148:151], v77 offset:55296
	ds_read_b128 v[152:155], v79 offset:49152
	ds_read_b128 v[156:159], v79 offset:51200
	ds_read_b128 v[160:163], v79 offset:53248
	ds_read_b128 v[164:167], v79 offset:55296
	s_waitcnt lgkmcnt(8)
	v_mfma_f32_16x16x32_bf16 v[0:3], v[84:87], v[100:103], v[0:3]
	v_mfma_f32_16x16x32_bf16 v[4:7], v[84:87], v[104:107], v[4:7]
	v_mfma_f32_16x16x32_bf16 v[8:11], v[84:87], v[108:111], v[8:11]
	v_mfma_f32_16x16x32_bf16 v[12:15], v[84:87], v[112:115], v[12:15]
	v_mfma_f32_16x16x32_bf16 v[16:19], v[88:91], v[100:103], v[16:19]
	v_mfma_f32_16x16x32_bf16 v[20:23], v[88:91], v[104:107], v[20:23]
	v_mfma_f32_16x16x32_bf16 v[24:27], v[88:91], v[108:111], v[24:27]
	v_mfma_f32_16x16x32_bf16 v[28:31], v[88:91], v[112:115], v[28:31]
	v_mfma_f32_16x16x32_bf16 v[32:35], v[92:95], v[100:103], v[32:35]
	v_mfma_f32_16x16x32_bf16 v[36:39], v[92:95], v[104:107], v[36:39]
	v_mfma_f32_16x16x32_bf16 v[40:43], v[92:95], v[108:111], v[40:43]
	v_mfma_f32_16x16x32_bf16 v[44:47], v[92:95], v[112:115], v[44:47]
	v_mfma_f32_16x16x32_bf16 v[48:51], v[96:99], v[100:103], v[48:51]
	v_mfma_f32_16x16x32_bf16 v[52:55], v[96:99], v[104:107], v[52:55]
	v_mfma_f32_16x16x32_bf16 v[56:59], v[96:99], v[108:111], v[56:59]
	v_mfma_f32_16x16x32_bf16 v[60:63], v[96:99], v[112:115], v[60:63]
	s_waitcnt vmcnt(6) lgkmcnt(0)
	s_barrier
;     ...
;   for (int kt = 0; kt < nk; ++kt) {
;     if (kt + 1 < nk) asm volatile("s_waitcnt vmcnt(6)" ::: "memory");
;     else asm volatile("s_waitcnt vmcnt(0)" ::: "memory");
;     __builtin_amdgcn_s_barrier();
;     asm volatile("" ::: "memory");
;     if (kt + 2 < nk) { const int st2 = (st >= 1) ? st - 1 : 2; GEMM_ISSUE(kt + 2, st2); }
;     const char* la = lds + st * STAGE_B;
;     const char* lb = la + 32768;
;     const unsigned sa_u = (unsigned)(size_t)la + arow_u, sb_u = (unsigned)(size_t)lb + brow_u;
;     const unsigned a0 = sa_u + co0, a1 = sa_u + co1, a2 = sa_u + co2, a3 = sa_u + co3;
;     const unsigned b0 = sb_u + co0, b1 = sb_u + co1, b2 = sb_u + co2, b3 = sb_u + co3;
;     {
;       bf16x8 p0, p1, q0, q1, u0, u1, w0, w1;
;       asm volatile(
;         "ds_read_b128 %4, %12\n\tds_read_b128 %5, %12 offset:4096\n\tds_read_b128 %6, %16\n\tds_read_b128 %7, %16 offset:4096\n\t"
;         "ds_read_b128 %8, %13\n\tds_read_b128 %9, %13 offset:4096\n\tds_read_b128 %10, %17\n\tds_read_b128 %11, %17 offset:4096\n\t"
;         "s_waitcnt lgkmcnt(4)\n\t"
;         "v_mfma_f32_32x32x16_bf16 %0, %4, %6, %0\n\tv_mfma_f32_32x32x16_bf16 %1, %4, %7, %1\n\tv_mfma_f32_32x32x16_bf16 %2, %5, %6, %2\n\tv_mfma_f32_32x32x16_bf16 %3, %5, %7, %3\n\t"
;         "ds_read_b128 %4, %14\n\tds_read_b128 %5, %14 offset:4096\n\tds_read_b128 %6, %18\n\tds_read_b128 %7, %18 offset:4096\n\t"
;         "s_waitcnt lgkmcnt(4)\n\t"
;         "v_mfma_f32_32x32x16_bf16 %0, %8, %10, %0\n\tv_mfma_f32_32x32x16_bf16 %1, %8, %11, %1\n\tv_mfma_f32_32x32x16_bf16 %2, %9, %10, %2\n\tv_mfma_f32_32x32x16_bf16 %3, %9, %11, %3\n\t"
;         "ds_read_b128 %8, %15\n\tds_read_b128 %9, %15 offset:4096\n\tds_read_b128 %10, %19\n\tds_read_b128 %11, %19 offset:4096\n\t"
;         "s_waitcnt lgkmcnt(4)\n\t"
;         "v_mfma_f32_32x32x16_bf16 %0, %4, %6, %0\n\tv_mfma_f32_32x32x16_bf16 %1, %4, %7, %1\n\tv_mfma_f32_32x32x16_bf16 %2, %5, %6, %2\n\tv_mfma_f32_32x32x16_bf16 %3, %5, %7, %3\n\t"
;         "s_waitcnt lgkmcnt(0)\n\t"
;         "v_mfma_f32_32x32x16_bf16 %0, %8, %10, %0\n\tv_mfma_f32_32x32x16_bf16 %1, %8, %11, %1\n\tv_mfma_f32_32x32x16_bf16 %2, %9, %10, %2\n\tv_mfma_f32_32x32x16_bf16 %3, %9, %11, %3"
;         : "+v"(acc[0][0]), "+v"(acc[0][1]), "+v"(acc[1][0]), "+v"(acc[1][1]),
;           "=&v"(p0), "=&v"(p1), "=&v"(q0), "=&v"(q1), "=&v"(u0), "=&v"(u1), "=&v"(w0), "=&v"(w1)
	ds_read_b128 v[84:87], v80
	ds_read_b128 v[88:91], v80 offset:2048
	ds_read_b128 v[92:95], v80 offset:4096
	ds_read_b128 v[96:99], v80 offset:6144
	ds_read_b128 v[100:103], v82
	ds_read_b128 v[104:107], v82 offset:2048
	ds_read_b128 v[108:111], v82 offset:4096
	ds_read_b128 v[112:115], v82 offset:6144
	v_mfma_f32_16x16x32_bf16 v[0:3], v[136:139], v[152:155], v[0:3]
	s_mov_b32 s24, 0x380
	s_mov_b32 s25, 0
	s_add_u32 m0, s30, 0xc000
	v_lshl_add_u64 v[124:125], v[64:65], 0, s[24:25]
	global_load_lds_dwordx4 v[124:125], off
	v_mfma_f32_16x16x32_bf16 v[4:7], v[136:139], v[156:159], v[4:7]
	s_add_u32 m0, s30, 0xe000
	v_lshl_add_u64 v[126:127], v[66:67], 0, s[24:25]
	global_load_lds_dwordx4 v[126:127], off
	v_mfma_f32_16x16x32_bf16 v[8:11], v[136:139], v[160:163], v[8:11]
	s_add_u32 m0, s30, 0x10000
	v_lshl_add_u64 v[124:125], v[68:69], 0, s[24:25]
	global_load_lds_dwordx4 v[124:125], off
	v_mfma_f32_16x16x32_bf16 v[12:15], v[136:139], v[164:167], v[12:15]
	s_add_u32 m0, s30, 0x12000
	v_lshl_add_u64 v[126:127], v[70:71], 0, s[24:25]
	global_load_lds_dwordx4 v[126:127], off
	v_mfma_f32_16x16x32_bf16 v[16:19], v[140:143], v[152:155], v[16:19]
	s_add_u32 m0, s30, 0x14000
	v_lshl_add_u64 v[124:125], v[72:73], 0, s[24:25]
	global_load_lds_dwordx4 v[124:125], off
	v_mfma_f32_16x16x32_bf16 v[20:23], v[140:143], v[156:159], v[20:23]
	s_add_u32 m0, s30, 0x16000
	v_lshl_add_u64 v[126:127], v[74:75], 0, s[24:25]
	global_load_lds_dwordx4 v[126:127], off
	v_mfma_f32_16x16x32_bf16 v[24:27], v[140:143], v[160:163], v[24:27]
	v_mfma_f32_16x16x32_bf16 v[28:31], v[140:143], v[164:167], v[28:31]
	v_mfma_f32_16x16x32_bf16 v[32:35], v[144:147], v[152:155], v[32:35]
	v_mfma_f32_16x16x32_bf16 v[36:39], v[144:147], v[156:159], v[36:39]
	v_mfma_f32_16x16x32_bf16 v[40:43], v[144:147], v[160:163], v[40:43]
	v_mfma_f32_16x16x32_bf16 v[44:47], v[144:147], v[164:167], v[44:47]
	v_mfma_f32_16x16x32_bf16 v[48:51], v[148:151], v[152:155], v[48:51]
	v_mfma_f32_16x16x32_bf16 v[52:55], v[148:151], v[156:159], v[52:55]
	v_mfma_f32_16x16x32_bf16 v[56:59], v[148:151], v[160:163], v[56:59]
	v_mfma_f32_16x16x32_bf16 v[60:63], v[148:151], v[164:167], v[60:63]
	ds_read_b128 v[136:139], v81
	ds_read_b128 v[140:143], v81 offset:2048
	ds_read_b128 v[144:147], v81 offset:4096
	ds_read_b128 v[148:151], v81 offset:6144
	ds_read_b128 v[152:155], v83
	ds_read_b128 v[156:159], v83 offset:2048
	ds_read_b128 v[160:163], v83 offset:4096
	ds_read_b128 v[164:167], v83 offset:6144
	s_waitcnt lgkmcnt(8)
	v_mfma_f32_16x16x32_bf16 v[0:3], v[84:87], v[100:103], v[0:3]
	v_mfma_f32_16x16x32_bf16 v[4:7], v[84:87], v[104:107], v[4:7]
	v_mfma_f32_16x16x32_bf16 v[8:11], v[84:87], v[108:111], v[8:11]
	v_mfma_f32_16x16x32_bf16 v[12:15], v[84:87], v[112:115], v[12:15]
	v_mfma_f32_16x16x32_bf16 v[16:19], v[88:91], v[100:103], v[16:19]
	v_mfma_f32_16x16x32_bf16 v[20:23], v[88:91], v[104:107], v[20:23]
	v_mfma_f32_16x16x32_bf16 v[24:27], v[88:91], v[108:111], v[24:27]
	v_mfma_f32_16x16x32_bf16 v[28:31], v[88:91], v[112:115], v[28:31]
	v_mfma_f32_16x16x32_bf16 v[32:35], v[92:95], v[100:103], v[32:35]
	v_mfma_f32_16x16x32_bf16 v[36:39], v[92:95], v[104:107], v[36:39]
	v_mfma_f32_16x16x32_bf16 v[40:43], v[92:95], v[108:111], v[40:43]
	v_mfma_f32_16x16x32_bf16 v[44:47], v[92:95], v[112:115], v[44:47]
	v_mfma_f32_16x16x32_bf16 v[48:51], v[96:99], v[100:103], v[48:51]
	v_mfma_f32_16x16x32_bf16 v[52:55], v[96:99], v[104:107], v[52:55]
	v_mfma_f32_16x16x32_bf16 v[56:59], v[96:99], v[108:111], v[56:59]
	v_mfma_f32_16x16x32_bf16 v[60:63], v[96:99], v[112:115], v[60:63]
	s_waitcnt vmcnt(6) lgkmcnt(0)
	s_barrier
	ds_read_b128 v[84:87], v76
	ds_read_b128 v[88:91], v76 offset:2048
	ds_read_b128 v[92:95], v76 offset:4096
	ds_read_b128 v[96:99], v76 offset:6144
	ds_read_b128 v[100:103], v78
	ds_read_b128 v[104:107], v78 offset:2048
	ds_read_b128 v[108:111], v78 offset:4096
	ds_read_b128 v[112:115], v78 offset:6144
	v_mfma_f32_16x16x32_bf16 v[0:3], v[136:139], v[152:155], v[0:3]
	s_mov_b32 s24, 0x400
	s_mov_b32 s25, 0
	s_add_u32 m0, s30, 0x18000
	v_lshl_add_u64 v[124:125], v[64:65], 0, s[24:25]
	global_load_lds_dwordx4 v[124:125], off
	v_mfma_f32_16x16x32_bf16 v[4:7], v[136:139], v[156:159], v[4:7]
	s_add_u32 m0, s30, 0x1a000
	v_lshl_add_u64 v[126:127], v[66:67], 0, s[24:25]
	global_load_lds_dwordx4 v[126:127], off
	v_mfma_f32_16x16x32_bf16 v[8:11], v[136:139], v[160:163], v[8:11]
	s_add_u32 m0, s30, 0x1c000
	v_lshl_add_u64 v[124:125], v[68:69], 0, s[24:25]
	global_load_lds_dwordx4 v[124:125], off
	v_mfma_f32_16x16x32_bf16 v[12:15], v[136:139], v[164:167], v[12:15]
	s_add_u32 m0, s30, 0x1e000
	v_lshl_add_u64 v[126:127], v[70:71], 0, s[24:25]
	global_load_lds_dwordx4 v[126:127], off
	v_mfma_f32_16x16x32_bf16 v[16:19], v[140:143], v[152:155], v[16:19]
	s_add_u32 m0, s30, 0x20000
	v_lshl_add_u64 v[124:125], v[72:73], 0, s[24:25]
	global_load_lds_dwordx4 v[124:125], off
	v_mfma_f32_16x16x32_bf16 v[20:23], v[140:143], v[156:159], v[20:23]
	s_add_u32 m0, s30, 0x22000
	v_lshl_add_u64 v[126:127], v[74:75], 0, s[24:25]
	global_load_lds_dwordx4 v[126:127], off
	v_mfma_f32_16x16x32_bf16 v[24:27], v[140:143], v[160:163], v[24:27]
	v_mfma_f32_16x16x32_bf16 v[28:31], v[140:143], v[164:167], v[28:31]
	v_mfma_f32_16x16x32_bf16 v[32:35], v[144:147], v[152:155], v[32:35]
	v_mfma_f32_16x16x32_bf16 v[36:39], v[144:147], v[156:159], v[36:39]
	v_mfma_f32_16x16x32_bf16 v[40:43], v[144:147], v[160:163], v[40:43]
	v_mfma_f32_16x16x32_bf16 v[44:47], v[144:147], v[164:167], v[44:47]
	v_mfma_f32_16x16x32_bf16 v[48:51], v[148:151], v[152:155], v[48:51]
	v_mfma_f32_16x16x32_bf16 v[52:55], v[148:151], v[156:159], v[52:55]
	v_mfma_f32_16x16x32_bf16 v[56:59], v[148:151], v[160:163], v[56:59]
	v_mfma_f32_16x16x32_bf16 v[60:63], v[148:151], v[164:167], v[60:63]
	ds_read_b128 v[136:139], v77
	ds_read_b128 v[140:143], v77 offset:2048
	ds_read_b128 v[144:147], v77 offset:4096
	ds_read_b128 v[148:151], v77 offset:6144
	ds_read_b128 v[152:155], v79
	ds_read_b128 v[156:159], v79 offset:2048
	ds_read_b128 v[160:163], v79 offset:4096
	ds_read_b128 v[164:167], v79 offset:6144
	s_waitcnt lgkmcnt(8)
;     ...
;   for (int kt = 0; kt < nk; ++kt) {
;     if (kt + 1 < nk) asm volatile("s_waitcnt vmcnt(6)" ::: "memory");
;     else asm volatile("s_waitcnt vmcnt(0)" ::: "memory");
;     __builtin_amdgcn_s_barrier();
;     asm volatile("" ::: "memory");
;     if (kt + 2 < nk) { const int st2 = (st >= 1) ? st - 1 : 2; GEMM_ISSUE(kt + 2, st2); }
;     const char* la = lds + st * STAGE_B;
;     const char* lb = la + 32768;
;     const unsigned sa_u = (unsigned)(size_t)la + arow_u, sb_u = (unsigned)(size_t)lb + brow_u;
;     const unsigned a0 = sa_u + co0, a1 = sa_u + co1, a2 = sa_u + co2, a3 = sa_u + co3;
;     const unsigned b0 = sb_u + co0, b1 = sb_u + co1, b2 = sb_u + co2, b3 = sb_u + co3;
;     {
;       bf16x8 p0, p1, q0, q1, u0, u1, w0, w1;
;       asm volatile(
;         "ds_read_b128 %4, %12\n\tds_read_b128 %5, %12 offset:4096\n\tds_read_b128 %6, %16\n\tds_read_b128 %7, %16 offset:4096\n\t"
;         "ds_read_b128 %8, %13\n\tds_read_b128 %9, %13 offset:4096\n\tds_read_b128 %10, %17\n\tds_read_b128 %11, %17 offset:4096\n\t"
;         "s_waitcnt lgkmcnt(4)\n\t"
;         "v_mfma_f32_32x32x16_bf16 %0, %4, %6, %0\n\tv_mfma_f32_32x32x16_bf16 %1, %4, %7, %1\n\tv_mfma_f32_32x32x16_bf16 %2, %5, %6, %2\n\tv_mfma_f32_32x32x16_bf16 %3, %5, %7, %3\n\t"
;         "ds_read_b128 %4, %14\n\tds_read_b128 %5, %14 offset:4096\n\tds_read_b128 %6, %18\n\tds_read_b128 %7, %18 offset:4096\n\t"
;         "s_waitcnt lgkmcnt(4)\n\t"
;         "v_mfma_f32_32x32x16_bf16 %0, %8, %10, %0\n\tv_mfma_f32_32x32x16_bf16 %1, %8, %11, %1\n\tv_mfma_f32_32x32x16_bf16 %2, %9, %10, %2\n\tv_mfma_f32_32x32x16_bf16 %3, %9, %11, %3\n\t"
;         "ds_read_b128 %8, %15\n\tds_read_b128 %9, %15 offset:4096\n\tds_read_b128 %10, %19\n\tds_read_b128 %11, %19 offset:4096\n\t"
;         "s_waitcnt lgkmcnt(4)\n\t"
;         "v_mfma_f32_32x32x16_bf16 %0, %4, %6, %0\n\tv_mfma_f32_32x32x16_bf16 %1, %4, %7, %1\n\tv_mfma_f32_32x32x16_bf16 %2, %5, %6, %2\n\tv_mfma_f32_32x32x16_bf16 %3, %5, %7, %3\n\t"
;         "s_waitcnt lgkmcnt(0)\n\t"
;         "v_mfma_f32_32x32x16_bf16 %0, %8, %10, %0\n\tv_mfma_f32_32x32x16_bf16 %1, %8, %11, %1\n\tv_mfma_f32_32x32x16_bf16 %2, %9, %10, %2\n\tv_mfma_f32_32x32x16_bf16 %3, %9, %11, %3"
;         : "+v"(acc[0][0]), "+v"(acc[0][1]), "+v"(acc[1][0]), "+v"(acc[1][1]),
;           "=&v"(p0), "=&v"(p1), "=&v"(q0), "=&v"(q1), "=&v"(u0), "=&v"(u1), "=&v"(w0), "=&v"(w1)
	v_mfma_f32_16x16x32_bf16 v[0:3], v[84:87], v[100:103], v[0:3]
	v_mfma_f32_16x16x32_bf16 v[4:7], v[84:87], v[104:107], v[4:7]
	v_mfma_f32_16x16x32_bf16 v[8:11], v[84:87], v[108:111], v[8:11]
	v_mfma_f32_16x16x32_bf16 v[12:15], v[84:87], v[112:115], v[12:15]
	v_mfma_f32_16x16x32_bf16 v[16:19], v[88:91], v[100:103], v[16:19]
	v_mfma_f32_16x16x32_bf16 v[20:23], v[88:91], v[104:107], v[20:23]
	v_mfma_f32_16x16x32_bf16 v[24:27], v[88:91], v[108:111], v[24:27]
	v_mfma_f32_16x16x32_bf16 v[28:31], v[88:91], v[112:115], v[28:31]
	v_mfma_f32_16x16x32_bf16 v[32:35], v[92:95], v[100:103], v[32:35]
	v_mfma_f32_16x16x32_bf16 v[36:39], v[92:95], v[104:107], v[36:39]
	v_mfma_f32_16x16x32_bf16 v[40:43], v[92:95], v[108:111], v[40:43]
	v_mfma_f32_16x16x32_bf16 v[44:47], v[92:95], v[112:115], v[44:47]
	v_mfma_f32_16x16x32_bf16 v[48:51], v[96:99], v[100:103], v[48:51]
	v_mfma_f32_16x16x32_bf16 v[52:55], v[96:99], v[104:107], v[52:55]
	v_mfma_f32_16x16x32_bf16 v[56:59], v[96:99], v[108:111], v[56:59]
	v_mfma_f32_16x16x32_bf16 v[60:63], v[96:99], v[112:115], v[60:63]
	s_waitcnt vmcnt(6) lgkmcnt(0)
	s_barrier
	ds_read_b128 v[84:87], v76 offset:49152
	ds_read_b128 v[88:91], v76 offset:51200
	ds_read_b128 v[92:95], v76 offset:53248
	ds_read_b128 v[96:99], v76 offset:55296
	ds_read_b128 v[100:103], v78 offset:49152
	ds_read_b128 v[104:107], v78 offset:51200
	ds_read_b128 v[108:111], v78 offset:53248
	ds_read_b128 v[112:115], v78 offset:55296
	v_mfma_f32_16x16x32_bf16 v[0:3], v[136:139], v[152:155], v[0:3]
	s_mov_b32 s24, 0x480
	s_mov_b32 s25, 0
	s_mov_b32 m0, s30
	v_lshl_add_u64 v[124:125], v[64:65], 0, s[24:25]
	global_load_lds_dwordx4 v[124:125], off
	v_mfma_f32_16x16x32_bf16 v[4:7], v[136:139], v[156:159], v[4:7]
	s_add_u32 m0, s30, 0x2000
	v_lshl_add_u64 v[126:127], v[66:67], 0, s[24:25]
	global_load_lds_dwordx4 v[126:127], off
	v_mfma_f32_16x16x32_bf16 v[8:11], v[136:139], v[160:163], v[8:11]
	s_add_u32 m0, s30, 0x4000
	v_lshl_add_u64 v[124:125], v[68:69], 0, s[24:25]
	global_load_lds_dwordx4 v[124:125], off
	v_mfma_f32_16x16x32_bf16 v[12:15], v[136:139], v[164:167], v[12:15]
	s_add_u32 m0, s30, 0x6000
	v_lshl_add_u64 v[126:127], v[70:71], 0, s[24:25]
	global_load_lds_dwordx4 v[126:127], off
	v_mfma_f32_16x16x32_bf16 v[16:19], v[140:143], v[152:155], v[16:19]
	s_add_u32 m0, s30, 0x8000
	v_lshl_add_u64 v[124:125], v[72:73], 0, s[24:25]
	global_load_lds_dwordx4 v[124:125], off
	v_mfma_f32_16x16x32_bf16 v[20:23], v[140:143], v[156:159], v[20:23]
	s_add_u32 m0, s30, 0xa000
	v_lshl_add_u64 v[126:127], v[74:75], 0, s[24:25]
	global_load_lds_dwordx4 v[126:127], off
	v_mfma_f32_16x16x32_bf16 v[24:27], v[140:143], v[160:163], v[24:27]
	v_mfma_f32_16x16x32_bf16 v[28:31], v[140:143], v[164:167], v[28:31]
	v_mfma_f32_16x16x32_bf16 v[32:35], v[144:147], v[152:155], v[32:35]
	v_mfma_f32_16x16x32_bf16 v[36:39], v[144:147], v[156:159], v[36:39]
	v_mfma_f32_16x16x32_bf16 v[40:43], v[144:147], v[160:163], v[40:43]
	v_mfma_f32_16x16x32_bf16 v[44:47], v[144:147], v[164:167], v[44:47]
	v_mfma_f32_16x16x32_bf16 v[48:51], v[148:151], v[152:155], v[48:51]
	v_mfma_f32_16x16x32_bf16 v[52:55], v[148:151], v[156:159], v[52:55]
	v_mfma_f32_16x16x32_bf16 v[56:59], v[148:151], v[160:163], v[56:59]
	v_mfma_f32_16x16x32_bf16 v[60:63], v[148:151], v[164:167], v[60:63]
	ds_read_b128 v[136:139], v77 offset:49152
	ds_read_b128 v[140:143], v77 offset:51200
	ds_read_b128 v[144:147], v77 offset:53248
	ds_read_b128 v[148:151], v77 offset:55296
	ds_read_b128 v[152:155], v79 offset:49152
	ds_read_b128 v[156:159], v79 offset:51200
	ds_read_b128 v[160:163], v79 offset:53248
	ds_read_b128 v[164:167], v79 offset:55296
	s_waitcnt lgkmcnt(8)
	v_mfma_f32_16x16x32_bf16 v[0:3], v[84:87], v[100:103], v[0:3]
	v_mfma_f32_16x16x32_bf16 v[4:7], v[84:87], v[104:107], v[4:7]
	v_mfma_f32_16x16x32_bf16 v[8:11], v[84:87], v[108:111], v[8:11]
	v_mfma_f32_16x16x32_bf16 v[12:15], v[84:87], v[112:115], v[12:15]
	v_mfma_f32_16x16x32_bf16 v[16:19], v[88:91], v[100:103], v[16:19]
	v_mfma_f32_16x16x32_bf16 v[20:23], v[88:91], v[104:107], v[20:23]
	v_mfma_f32_16x16x32_bf16 v[24:27], v[88:91], v[108:111], v[24:27]
	v_mfma_f32_16x16x32_bf16 v[28:31], v[88:91], v[112:115], v[28:31]
	v_mfma_f32_16x16x32_bf16 v[32:35], v[92:95], v[100:103], v[32:35]
	v_mfma_f32_16x16x32_bf16 v[36:39], v[92:95], v[104:107], v[36:39]
	v_mfma_f32_16x16x32_bf16 v[40:43], v[92:95], v[108:111], v[40:43]
	v_mfma_f32_16x16x32_bf16 v[44:47], v[92:95], v[112:115], v[44:47]
	v_mfma_f32_16x16x32_bf16 v[48:51], v[96:99], v[100:103], v[48:51]
	v_mfma_f32_16x16x32_bf16 v[52:55], v[96:99], v[104:107], v[52:55]
	v_mfma_f32_16x16x32_bf16 v[56:59], v[96:99], v[108:111], v[56:59]
	v_mfma_f32_16x16x32_bf16 v[60:63], v[96:99], v[112:115], v[60:63]
	s_waitcnt vmcnt(6) lgkmcnt(0)
	s_barrier
;     ...
;   for (int kt = 0; kt < nk; ++kt) {
;     if (kt + 1 < nk) asm volatile("s_waitcnt vmcnt(6)" ::: "memory");
;     else asm volatile("s_waitcnt vmcnt(0)" ::: "memory");
;     __builtin_amdgcn_s_barrier();
;     asm volatile("" ::: "memory");
;     if (kt + 2 < nk) { const int st2 = (st >= 1) ? st - 1 : 2; GEMM_ISSUE(kt + 2, st2); }
;     const char* la = lds + st * STAGE_B;
;     const char* lb = la + 32768;
;     const unsigned sa_u = (unsigned)(size_t)la + arow_u, sb_u = (unsigned)(size_t)lb + brow_u;
;     const unsigned a0 = sa_u + co0, a1 = sa_u + co1, a2 = sa_u + co2, a3 = sa_u + co3;
;     const unsigned b0 = sb_u + co0, b1 = sb_u + co1, b2 = sb_u + co2, b3 = sb_u + co3;
;     {
;       bf16x8 p0, p1, q0, q1, u0, u1, w0, w1;
;       asm volatile(
;         "ds_read_b128 %4, %12\n\tds_read_b128 %5, %12 offset:4096\n\tds_read_b128 %6, %16\n\tds_read_b128 %7, %16 offset:4096\n\t"
;         "ds_read_b128 %8, %13\n\tds_read_b128 %9, %13 offset:4096\n\tds_read_b128 %10, %17\n\tds_read_b128 %11, %17 offset:4096\n\t"
;         "s_waitcnt lgkmcnt(4)\n\t"
;         "v_mfma_f32_32x32x16_bf16 %0, %4, %6, %0\n\tv_mfma_f32_32x32x16_bf16 %1, %4, %7, %1\n\tv_mfma_f32_32x32x16_bf16 %2, %5, %6, %2\n\tv_mfma_f32_32x32x16_bf16 %3, %5, %7, %3\n\t"
;         "ds_read_b128 %4, %14\n\tds_read_b128 %5, %14 offset:4096\n\tds_read_b128 %6, %18\n\tds_read_b128 %7, %18 offset:4096\n\t"
;         "s_waitcnt lgkmcnt(4)\n\t"
;         "v_mfma_f32_32x32x16_bf16 %0, %8, %10, %0\n\tv_mfma_f32_32x32x16_bf16 %1, %8, %11, %1\n\tv_mfma_f32_32x32x16_bf16 %2, %9, %10, %2\n\tv_mfma_f32_32x32x16_bf16 %3, %9, %11, %3\n\t"
;         "ds_read_b128 %8, %15\n\tds_read_b128 %9, %15 offset:4096\n\tds_read_b128 %10, %19\n\tds_read_b128 %11, %19 offset:4096\n\t"
;         "s_waitcnt lgkmcnt(4)\n\t"
;         "v_mfma_f32_32x32x16_bf16 %0, %4, %6, %0\n\tv_mfma_f32_32x32x16_bf16 %1, %4, %7, %1\n\tv_mfma_f32_32x32x16_bf16 %2, %5, %6, %2\n\tv_mfma_f32_32x32x16_bf16 %3, %5, %7, %3\n\t"
;         "s_waitcnt lgkmcnt(0)\n\t"
;         "v_mfma_f32_32x32x16_bf16 %0, %8, %10, %0\n\tv_mfma_f32_32x32x16_bf16 %1, %8, %11, %1\n\tv_mfma_f32_32x32x16_bf16 %2, %9, %10, %2\n\tv_mfma_f32_32x32x16_bf16 %3, %9, %11, %3"
;         : "+v"(acc[0][0]), "+v"(acc[0][1]), "+v"(acc[1][0]), "+v"(acc[1][1]),
;           "=&v"(p0), "=&v"(p1), "=&v"(q0), "=&v"(q1), "=&v"(u0), "=&v"(u1), "=&v"(w0), "=&v"(w1)
	ds_read_b128 v[84:87], v80
	ds_read_b128 v[88:91], v80 offset:2048
	ds_read_b128 v[92:95], v80 offset:4096
	ds_read_b128 v[96:99], v80 offset:6144
	ds_read_b128 v[100:103], v82
	ds_read_b128 v[104:107], v82 offset:2048
	ds_read_b128 v[108:111], v82 offset:4096
	ds_read_b128 v[112:115], v82 offset:6144
	v_mfma_f32_16x16x32_bf16 v[0:3], v[136:139], v[152:155], v[0:3]
	s_mov_b32 s24, 0x500
	s_mov_b32 s25, 0
	s_add_u32 m0, s30, 0xc000
	v_lshl_add_u64 v[124:125], v[64:65], 0, s[24:25]
	global_load_lds_dwordx4 v[124:125], off
	v_mfma_f32_16x16x32_bf16 v[4:7], v[136:139], v[156:159], v[4:7]
	s_add_u32 m0, s30, 0xe000
	v_lshl_add_u64 v[126:127], v[66:67], 0, s[24:25]
	global_load_lds_dwordx4 v[126:127], off
	v_mfma_f32_16x16x32_bf16 v[8:11], v[136:139], v[160:163], v[8:11]
	s_add_u32 m0, s30, 0x10000
	v_lshl_add_u64 v[124:125], v[68:69], 0, s[24:25]
	global_load_lds_dwordx4 v[124:125], off
	v_mfma_f32_16x16x32_bf16 v[12:15], v[136:139], v[164:167], v[12:15]
	s_add_u32 m0, s30, 0x12000
	v_lshl_add_u64 v[126:127], v[70:71], 0, s[24:25]
	global_load_lds_dwordx4 v[126:127], off
	v_mfma_f32_16x16x32_bf16 v[16:19], v[140:143], v[152:155], v[16:19]
	s_add_u32 m0, s30, 0x14000
	v_lshl_add_u64 v[124:125], v[72:73], 0, s[24:25]
	global_load_lds_dwordx4 v[124:125], off
	v_mfma_f32_16x16x32_bf16 v[20:23], v[140:143], v[156:159], v[20:23]
	s_add_u32 m0, s30, 0x16000
	v_lshl_add_u64 v[126:127], v[74:75], 0, s[24:25]
	global_load_lds_dwordx4 v[126:127], off
	v_mfma_f32_16x16x32_bf16 v[24:27], v[140:143], v[160:163], v[24:27]
	v_mfma_f32_16x16x32_bf16 v[28:31], v[140:143], v[164:167], v[28:31]
	v_mfma_f32_16x16x32_bf16 v[32:35], v[144:147], v[152:155], v[32:35]
	v_mfma_f32_16x16x32_bf16 v[36:39], v[144:147], v[156:159], v[36:39]
	v_mfma_f32_16x16x32_bf16 v[40:43], v[144:147], v[160:163], v[40:43]
	v_mfma_f32_16x16x32_bf16 v[44:47], v[144:147], v[164:167], v[44:47]
	v_mfma_f32_16x16x32_bf16 v[48:51], v[148:151], v[152:155], v[48:51]
	v_mfma_f32_16x16x32_bf16 v[52:55], v[148:151], v[156:159], v[52:55]
	v_mfma_f32_16x16x32_bf16 v[56:59], v[148:151], v[160:163], v[56:59]
	v_mfma_f32_16x16x32_bf16 v[60:63], v[148:151], v[164:167], v[60:63]
	ds_read_b128 v[136:139], v81
	ds_read_b128 v[140:143], v81 offset:2048
	ds_read_b128 v[144:147], v81 offset:4096
	ds_read_b128 v[148:151], v81 offset:6144
	ds_read_b128 v[152:155], v83
	ds_read_b128 v[156:159], v83 offset:2048
	ds_read_b128 v[160:163], v83 offset:4096
	ds_read_b128 v[164:167], v83 offset:6144
	s_waitcnt lgkmcnt(8)
	v_mfma_f32_16x16x32_bf16 v[0:3], v[84:87], v[100:103], v[0:3]
	v_mfma_f32_16x16x32_bf16 v[4:7], v[84:87], v[104:107], v[4:7]
	v_mfma_f32_16x16x32_bf16 v[8:11], v[84:87], v[108:111], v[8:11]
	v_mfma_f32_16x16x32_bf16 v[12:15], v[84:87], v[112:115], v[12:15]
	v_mfma_f32_16x16x32_bf16 v[16:19], v[88:91], v[100:103], v[16:19]
	v_mfma_f32_16x16x32_bf16 v[20:23], v[88:91], v[104:107], v[20:23]
	v_mfma_f32_16x16x32_bf16 v[24:27], v[88:91], v[108:111], v[24:27]
	v_mfma_f32_16x16x32_bf16 v[28:31], v[88:91], v[112:115], v[28:31]
	v_mfma_f32_16x16x32_bf16 v[32:35], v[92:95], v[100:103], v[32:35]
	v_mfma_f32_16x16x32_bf16 v[36:39], v[92:95], v[104:107], v[36:39]
	v_mfma_f32_16x16x32_bf16 v[40:43], v[92:95], v[108:111], v[40:43]
	v_mfma_f32_16x16x32_bf16 v[44:47], v[92:95], v[112:115], v[44:47]
	v_mfma_f32_16x16x32_bf16 v[48:51], v[96:99], v[100:103], v[48:51]
	v_mfma_f32_16x16x32_bf16 v[52:55], v[96:99], v[104:107], v[52:55]
	v_mfma_f32_16x16x32_bf16 v[56:59], v[96:99], v[108:111], v[56:59]
	v_mfma_f32_16x16x32_bf16 v[60:63], v[96:99], v[112:115], v[60:63]
	s_waitcnt vmcnt(6) lgkmcnt(0)
	s_barrier
	ds_read_b128 v[84:87], v76
	ds_read_b128 v[88:91], v76 offset:2048
	ds_read_b128 v[92:95], v76 offset:4096
	ds_read_b128 v[96:99], v76 offset:6144
	ds_read_b128 v[100:103], v78
	ds_read_b128 v[104:107], v78 offset:2048
	ds_read_b128 v[108:111], v78 offset:4096
	ds_read_b128 v[112:115], v78 offset:6144
	v_mfma_f32_16x16x32_bf16 v[0:3], v[136:139], v[152:155], v[0:3]
	s_mov_b32 s24, 0x580
	s_mov_b32 s25, 0
	s_add_u32 m0, s30, 0x18000
	v_lshl_add_u64 v[124:125], v[64:65], 0, s[24:25]
	global_load_lds_dwordx4 v[124:125], off
	v_mfma_f32_16x16x32_bf16 v[4:7], v[136:139], v[156:159], v[4:7]
	s_add_u32 m0, s30, 0x1a000
	v_lshl_add_u64 v[126:127], v[66:67], 0, s[24:25]
	global_load_lds_dwordx4 v[126:127], off
	v_mfma_f32_16x16x32_bf16 v[8:11], v[136:139], v[160:163], v[8:11]
	s_add_u32 m0, s30, 0x1c000
	v_lshl_add_u64 v[124:125], v[68:69], 0, s[24:25]
	global_load_lds_dwordx4 v[124:125], off
	v_mfma_f32_16x16x32_bf16 v[12:15], v[136:139], v[164:167], v[12:15]
	s_add_u32 m0, s30, 0x1e000
	v_lshl_add_u64 v[126:127], v[70:71], 0, s[24:25]
	global_load_lds_dwordx4 v[126:127], off
	v_mfma_f32_16x16x32_bf16 v[16:19], v[140:143], v[152:155], v[16:19]
	s_add_u32 m0, s30, 0x20000
	v_lshl_add_u64 v[124:125], v[72:73], 0, s[24:25]
	global_load_lds_dwordx4 v[124:125], off
	v_mfma_f32_16x16x32_bf16 v[20:23], v[140:143], v[156:159], v[20:23]
	s_add_u32 m0, s30, 0x22000
	v_lshl_add_u64 v[126:127], v[74:75], 0, s[24:25]
	global_load_lds_dwordx4 v[126:127], off
	v_mfma_f32_16x16x32_bf16 v[24:27], v[140:143], v[160:163], v[24:27]
	v_mfma_f32_16x16x32_bf16 v[28:31], v[140:143], v[164:167], v[28:31]
	v_mfma_f32_16x16x32_bf16 v[32:35], v[144:147], v[152:155], v[32:35]
	v_mfma_f32_16x16x32_bf16 v[36:39], v[144:147], v[156:159], v[36:39]
	v_mfma_f32_16x16x32_bf16 v[40:43], v[144:147], v[160:163], v[40:43]
	v_mfma_f32_16x16x32_bf16 v[44:47], v[144:147], v[164:167], v[44:47]
	v_mfma_f32_16x16x32_bf16 v[48:51], v[148:151], v[152:155], v[48:51]
	v_mfma_f32_16x16x32_bf16 v[52:55], v[148:151], v[156:159], v[52:55]
	v_mfma_f32_16x16x32_bf16 v[56:59], v[148:151], v[160:163], v[56:59]
	v_mfma_f32_16x16x32_bf16 v[60:63], v[148:151], v[164:167], v[60:63]
	ds_read_b128 v[136:139], v77
	ds_read_b128 v[140:143], v77 offset:2048
	ds_read_b128 v[144:147], v77 offset:4096
	ds_read_b128 v[148:151], v77 offset:6144
	ds_read_b128 v[152:155], v79
	ds_read_b128 v[156:159], v79 offset:2048
	ds_read_b128 v[160:163], v79 offset:4096
	ds_read_b128 v[164:167], v79 offset:6144
	s_waitcnt lgkmcnt(8)
;     ...
;   for (int kt = 0; kt < nk; ++kt) {
;     if (kt + 1 < nk) asm volatile("s_waitcnt vmcnt(6)" ::: "memory");
;     else asm volatile("s_waitcnt vmcnt(0)" ::: "memory");
;     __builtin_amdgcn_s_barrier();
;     asm volatile("" ::: "memory");
;     if (kt + 2 < nk) { const int st2 = (st >= 1) ? st - 1 : 2; GEMM_ISSUE(kt + 2, st2); }
;     const char* la = lds + st * STAGE_B;
;     const char* lb = la + 32768;
;     const unsigned sa_u = (unsigned)(size_t)la + arow_u, sb_u = (unsigned)(size_t)lb + brow_u;
;     const unsigned a0 = sa_u + co0, a1 = sa_u + co1, a2 = sa_u + co2, a3 = sa_u + co3;
;     const unsigned b0 = sb_u + co0, b1 = sb_u + co1, b2 = sb_u + co2, b3 = sb_u + co3;
;     {
;       bf16x8 p0, p1, q0, q1, u0, u1, w0, w1;
;       asm volatile(
;         "ds_read_b128 %4, %12\n\tds_read_b128 %5, %12 offset:4096\n\tds_read_b128 %6, %16\n\tds_read_b128 %7, %16 offset:4096\n\t"
;         "ds_read_b128 %8, %13\n\tds_read_b128 %9, %13 offset:4096\n\tds_read_b128 %10, %17\n\tds_read_b128 %11, %17 offset:4096\n\t"
;         "s_waitcnt lgkmcnt(4)\n\t"
;         "v_mfma_f32_32x32x16_bf16 %0, %4, %6, %0\n\tv_mfma_f32_32x32x16_bf16 %1, %4, %7, %1\n\tv_mfma_f32_32x32x16_bf16 %2, %5, %6, %2\n\tv_mfma_f32_32x32x16_bf16 %3, %5, %7, %3\n\t"
;         "ds_read_b128 %4, %14\n\tds_read_b128 %5, %14 offset:4096\n\tds_read_b128 %6, %18\n\tds_read_b128 %7, %18 offset:4096\n\t"
;         "s_waitcnt lgkmcnt(4)\n\t"
;         "v_mfma_f32_32x32x16_bf16 %0, %8, %10, %0\n\tv_mfma_f32_32x32x16_bf16 %1, %8, %11, %1\n\tv_mfma_f32_32x32x16_bf16 %2, %9, %10, %2\n\tv_mfma_f32_32x32x16_bf16 %3, %9, %11, %3\n\t"
;         "ds_read_b128 %8, %15\n\tds_read_b128 %9, %15 offset:4096\n\tds_read_b128 %10, %19\n\tds_read_b128 %11, %19 offset:4096\n\t"
;         "s_waitcnt lgkmcnt(4)\n\t"
;         "v_mfma_f32_32x32x16_bf16 %0, %4, %6, %0\n\tv_mfma_f32_32x32x16_bf16 %1, %4, %7, %1\n\tv_mfma_f32_32x32x16_bf16 %2, %5, %6, %2\n\tv_mfma_f32_32x32x16_bf16 %3, %5, %7, %3\n\t"
;         "s_waitcnt lgkmcnt(0)\n\t"
;         "v_mfma_f32_32x32x16_bf16 %0, %8, %10, %0\n\tv_mfma_f32_32x32x16_bf16 %1, %8, %11, %1\n\tv_mfma_f32_32x32x16_bf16 %2, %9, %10, %2\n\tv_mfma_f32_32x32x16_bf16 %3, %9, %11, %3"
;         : "+v"(acc[0][0]), "+v"(acc[0][1]), "+v"(acc[1][0]), "+v"(acc[1][1]),
;           "=&v"(p0), "=&v"(p1), "=&v"(q0), "=&v"(q1), "=&v"(u0), "=&v"(u1), "=&v"(w0), "=&v"(w1)
	v_mfma_f32_16x16x32_bf16 v[0:3], v[84:87], v[100:103], v[0:3]
	v_mfma_f32_16x16x32_bf16 v[4:7], v[84:87], v[104:107], v[4:7]
	v_mfma_f32_16x16x32_bf16 v[8:11], v[84:87], v[108:111], v[8:11]
	v_mfma_f32_16x16x32_bf16 v[12:15], v[84:87], v[112:115], v[12:15]
	v_mfma_f32_16x16x32_bf16 v[16:19], v[88:91], v[100:103], v[16:19]
	v_mfma_f32_16x16x32_bf16 v[20:23], v[88:91], v[104:107], v[20:23]
	v_mfma_f32_16x16x32_bf16 v[24:27], v[88:91], v[108:111], v[24:27]
	v_mfma_f32_16x16x32_bf16 v[28:31], v[88:91], v[112:115], v[28:31]
	v_mfma_f32_16x16x32_bf16 v[32:35], v[92:95], v[100:103], v[32:35]
	v_mfma_f32_16x16x32_bf16 v[36:39], v[92:95], v[104:107], v[36:39]
	v_mfma_f32_16x16x32_bf16 v[40:43], v[92:95], v[108:111], v[40:43]
	v_mfma_f32_16x16x32_bf16 v[44:47], v[92:95], v[112:115], v[44:47]
	v_mfma_f32_16x16x32_bf16 v[48:51], v[96:99], v[100:103], v[48:51]
	v_mfma_f32_16x16x32_bf16 v[52:55], v[96:99], v[104:107], v[52:55]
	v_mfma_f32_16x16x32_bf16 v[56:59], v[96:99], v[108:111], v[56:59]
	v_mfma_f32_16x16x32_bf16 v[60:63], v[96:99], v[112:115], v[60:63]
	s_waitcnt vmcnt(6) lgkmcnt(0)
	s_barrier
	ds_read_b128 v[84:87], v76 offset:49152
	ds_read_b128 v[88:91], v76 offset:51200
	ds_read_b128 v[92:95], v76 offset:53248
	ds_read_b128 v[96:99], v76 offset:55296
	ds_read_b128 v[100:103], v78 offset:49152
	ds_read_b128 v[104:107], v78 offset:51200
	ds_read_b128 v[108:111], v78 offset:53248
	ds_read_b128 v[112:115], v78 offset:55296
	v_mfma_f32_16x16x32_bf16 v[0:3], v[136:139], v[152:155], v[0:3]
	s_mov_b32 s24, 0x600
	s_mov_b32 s25, 0
	s_mov_b32 m0, s30
	v_lshl_add_u64 v[124:125], v[64:65], 0, s[24:25]
	global_load_lds_dwordx4 v[124:125], off
	v_mfma_f32_16x16x32_bf16 v[4:7], v[136:139], v[156:159], v[4:7]
	s_add_u32 m0, s30, 0x2000
	v_lshl_add_u64 v[126:127], v[66:67], 0, s[24:25]
	global_load_lds_dwordx4 v[126:127], off
	v_mfma_f32_16x16x32_bf16 v[8:11], v[136:139], v[160:163], v[8:11]
	s_add_u32 m0, s30, 0x4000
	v_lshl_add_u64 v[124:125], v[68:69], 0, s[24:25]
	global_load_lds_dwordx4 v[124:125], off
	v_mfma_f32_16x16x32_bf16 v[12:15], v[136:139], v[164:167], v[12:15]
	s_add_u32 m0, s30, 0x6000
	v_lshl_add_u64 v[126:127], v[70:71], 0, s[24:25]
	global_load_lds_dwordx4 v[126:127], off
	v_mfma_f32_16x16x32_bf16 v[16:19], v[140:143], v[152:155], v[16:19]
	s_add_u32 m0, s30, 0x8000
	v_lshl_add_u64 v[124:125], v[72:73], 0, s[24:25]
	global_load_lds_dwordx4 v[124:125], off
	v_mfma_f32_16x16x32_bf16 v[20:23], v[140:143], v[156:159], v[20:23]
	s_add_u32 m0, s30, 0xa000
	v_lshl_add_u64 v[126:127], v[74:75], 0, s[24:25]
	global_load_lds_dwordx4 v[126:127], off
	v_mfma_f32_16x16x32_bf16 v[24:27], v[140:143], v[160:163], v[24:27]
	v_mfma_f32_16x16x32_bf16 v[28:31], v[140:143], v[164:167], v[28:31]
	v_mfma_f32_16x16x32_bf16 v[32:35], v[144:147], v[152:155], v[32:35]
	v_mfma_f32_16x16x32_bf16 v[36:39], v[144:147], v[156:159], v[36:39]
	v_mfma_f32_16x16x32_bf16 v[40:43], v[144:147], v[160:163], v[40:43]
	v_mfma_f32_16x16x32_bf16 v[44:47], v[144:147], v[164:167], v[44:47]
	v_mfma_f32_16x16x32_bf16 v[48:51], v[148:151], v[152:155], v[48:51]
	v_mfma_f32_16x16x32_bf16 v[52:55], v[148:151], v[156:159], v[52:55]
	v_mfma_f32_16x16x32_bf16 v[56:59], v[148:151], v[160:163], v[56:59]
	v_mfma_f32_16x16x32_bf16 v[60:63], v[148:151], v[164:167], v[60:63]
	ds_read_b128 v[136:139], v77 offset:49152
	ds_read_b128 v[140:143], v77 offset:51200
	ds_read_b128 v[144:147], v77 offset:53248
	ds_read_b128 v[148:151], v77 offset:55296
	ds_read_b128 v[152:155], v79 offset:49152
	ds_read_b128 v[156:159], v79 offset:51200
	ds_read_b128 v[160:163], v79 offset:53248
	ds_read_b128 v[164:167], v79 offset:55296
	s_waitcnt lgkmcnt(8)
	v_mfma_f32_16x16x32_bf16 v[0:3], v[84:87], v[100:103], v[0:3]
	v_mfma_f32_16x16x32_bf16 v[4:7], v[84:87], v[104:107], v[4:7]
	v_mfma_f32_16x16x32_bf16 v[8:11], v[84:87], v[108:111], v[8:11]
	v_mfma_f32_16x16x32_bf16 v[12:15], v[84:87], v[112:115], v[12:15]
	v_mfma_f32_16x16x32_bf16 v[16:19], v[88:91], v[100:103], v[16:19]
	v_mfma_f32_16x16x32_bf16 v[20:23], v[88:91], v[104:107], v[20:23]
	v_mfma_f32_16x16x32_bf16 v[24:27], v[88:91], v[108:111], v[24:27]
	v_mfma_f32_16x16x32_bf16 v[28:31], v[88:91], v[112:115], v[28:31]
	v_mfma_f32_16x16x32_bf16 v[32:35], v[92:95], v[100:103], v[32:35]
	v_mfma_f32_16x16x32_bf16 v[36:39], v[92:95], v[104:107], v[36:39]
	v_mfma_f32_16x16x32_bf16 v[40:43], v[92:95], v[108:111], v[40:43]
	v_mfma_f32_16x16x32_bf16 v[44:47], v[92:95], v[112:115], v[44:47]
	v_mfma_f32_16x16x32_bf16 v[48:51], v[96:99], v[100:103], v[48:51]
	v_mfma_f32_16x16x32_bf16 v[52:55], v[96:99], v[104:107], v[52:55]
	v_mfma_f32_16x16x32_bf16 v[56:59], v[96:99], v[108:111], v[56:59]
	v_mfma_f32_16x16x32_bf16 v[60:63], v[96:99], v[112:115], v[60:63]
	s_waitcnt vmcnt(6) lgkmcnt(0)
	s_barrier
;     ...
;   for (int kt = 0; kt < nk; ++kt) {
;     if (kt + 1 < nk) asm volatile("s_waitcnt vmcnt(6)" ::: "memory");
;     else asm volatile("s_waitcnt vmcnt(0)" ::: "memory");
;     __builtin_amdgcn_s_barrier();
;     asm volatile("" ::: "memory");
;     if (kt + 2 < nk) { const int st2 = (st >= 1) ? st - 1 : 2; GEMM_ISSUE(kt + 2, st2); }
;     const char* la = lds + st * STAGE_B;
;     const char* lb = la + 32768;
;     const unsigned sa_u = (unsigned)(size_t)la + arow_u, sb_u = (unsigned)(size_t)lb + brow_u;
;     const unsigned a0 = sa_u + co0, a1 = sa_u + co1, a2 = sa_u + co2, a3 = sa_u + co3;
;     const unsigned b0 = sb_u + co0, b1 = sb_u + co1, b2 = sb_u + co2, b3 = sb_u + co3;
;     {
;       bf16x8 p0, p1, q0, q1, u0, u1, w0, w1;
;       asm volatile(
;         "ds_read_b128 %4, %12\n\tds_read_b128 %5, %12 offset:4096\n\tds_read_b128 %6, %16\n\tds_read_b128 %7, %16 offset:4096\n\t"
;         "ds_read_b128 %8, %13\n\tds_read_b128 %9, %13 offset:4096\n\tds_read_b128 %10, %17\n\tds_read_b128 %11, %17 offset:4096\n\t"
;         "s_waitcnt lgkmcnt(4)\n\t"
;         "v_mfma_f32_32x32x16_bf16 %0, %4, %6, %0\n\tv_mfma_f32_32x32x16_bf16 %1, %4, %7, %1\n\tv_mfma_f32_32x32x16_bf16 %2, %5, %6, %2\n\tv_mfma_f32_32x32x16_bf16 %3, %5, %7, %3\n\t"
;         "ds_read_b128 %4, %14\n\tds_read_b128 %5, %14 offset:4096\n\tds_read_b128 %6, %18\n\tds_read_b128 %7, %18 offset:4096\n\t"
;         "s_waitcnt lgkmcnt(4)\n\t"
;         "v_mfma_f32_32x32x16_bf16 %0, %8, %10, %0\n\tv_mfma_f32_32x32x16_bf16 %1, %8, %11, %1\n\tv_mfma_f32_32x32x16_bf16 %2, %9, %10, %2\n\tv_mfma_f32_32x32x16_bf16 %3, %9, %11, %3\n\t"
;         "ds_read_b128 %8, %15\n\tds_read_b128 %9, %15 offset:4096\n\tds_read_b128 %10, %19\n\tds_read_b128 %11, %19 offset:4096\n\t"
;         "s_waitcnt lgkmcnt(4)\n\t"
;         "v_mfma_f32_32x32x16_bf16 %0, %4, %6, %0\n\tv_mfma_f32_32x32x16_bf16 %1, %4, %7, %1\n\tv_mfma_f32_32x32x16_bf16 %2, %5, %6, %2\n\tv_mfma_f32_32x32x16_bf16 %3, %5, %7, %3\n\t"
;         "s_waitcnt lgkmcnt(0)\n\t"
;         "v_mfma_f32_32x32x16_bf16 %0, %8, %10, %0\n\tv_mfma_f32_32x32x16_bf16 %1, %8, %11, %1\n\tv_mfma_f32_32x32x16_bf16 %2, %9, %10, %2\n\tv_mfma_f32_32x32x16_bf16 %3, %9, %11, %3"
;         : "+v"(acc[0][0]), "+v"(acc[0][1]), "+v"(acc[1][0]), "+v"(acc[1][1]),
;           "=&v"(p0), "=&v"(p1), "=&v"(q0), "=&v"(q1), "=&v"(u0), "=&v"(u1), "=&v"(w0), "=&v"(w1)
	ds_read_b128 v[84:87], v80
	ds_read_b128 v[88:91], v80 offset:2048
	ds_read_b128 v[92:95], v80 offset:4096
	ds_read_b128 v[96:99], v80 offset:6144
	ds_read_b128 v[100:103], v82
	ds_read_b128 v[104:107], v82 offset:2048
	ds_read_b128 v[108:111], v82 offset:4096
	ds_read_b128 v[112:115], v82 offset:6144
	v_mfma_f32_16x16x32_bf16 v[0:3], v[136:139], v[152:155], v[0:3]
	s_mov_b32 s24, 0x680
	s_mov_b32 s25, 0
	s_add_u32 m0, s30, 0xc000
	v_lshl_add_u64 v[124:125], v[64:65], 0, s[24:25]
	global_load_lds_dwordx4 v[124:125], off
	v_mfma_f32_16x16x32_bf16 v[4:7], v[136:139], v[156:159], v[4:7]
	s_add_u32 m0, s30, 0xe000
	v_lshl_add_u64 v[126:127], v[66:67], 0, s[24:25]
	global_load_lds_dwordx4 v[126:127], off
	v_mfma_f32_16x16x32_bf16 v[8:11], v[136:139], v[160:163], v[8:11]
	s_add_u32 m0, s30, 0x10000
	v_lshl_add_u64 v[124:125], v[68:69], 0, s[24:25]
	global_load_lds_dwordx4 v[124:125], off
	v_mfma_f32_16x16x32_bf16 v[12:15], v[136:139], v[164:167], v[12:15]
	s_add_u32 m0, s30, 0x12000
	v_lshl_add_u64 v[126:127], v[70:71], 0, s[24:25]
	global_load_lds_dwordx4 v[126:127], off
	v_mfma_f32_16x16x32_bf16 v[16:19], v[140:143], v[152:155], v[16:19]
	s_add_u32 m0, s30, 0x14000
	v_lshl_add_u64 v[124:125], v[72:73], 0, s[24:25]
	global_load_lds_dwordx4 v[124:125], off
	v_mfma_f32_16x16x32_bf16 v[20:23], v[140:143], v[156:159], v[20:23]
	s_add_u32 m0, s30, 0x16000
	v_lshl_add_u64 v[126:127], v[74:75], 0, s[24:25]
	global_load_lds_dwordx4 v[126:127], off
	v_mfma_f32_16x16x32_bf16 v[24:27], v[140:143], v[160:163], v[24:27]
	v_mfma_f32_16x16x32_bf16 v[28:31], v[140:143], v[164:167], v[28:31]
	v_mfma_f32_16x16x32_bf16 v[32:35], v[144:147], v[152:155], v[32:35]
	v_mfma_f32_16x16x32_bf16 v[36:39], v[144:147], v[156:159], v[36:39]
	v_mfma_f32_16x16x32_bf16 v[40:43], v[144:147], v[160:163], v[40:43]
	v_mfma_f32_16x16x32_bf16 v[44:47], v[144:147], v[164:167], v[44:47]
	v_mfma_f32_16x16x32_bf16 v[48:51], v[148:151], v[152:155], v[48:51]
	v_mfma_f32_16x16x32_bf16 v[52:55], v[148:151], v[156:159], v[52:55]
	v_mfma_f32_16x16x32_bf16 v[56:59], v[148:151], v[160:163], v[56:59]
	v_mfma_f32_16x16x32_bf16 v[60:63], v[148:151], v[164:167], v[60:63]
	ds_read_b128 v[136:139], v81
	ds_read_b128 v[140:143], v81 offset:2048
	ds_read_b128 v[144:147], v81 offset:4096
	ds_read_b128 v[148:151], v81 offset:6144
	ds_read_b128 v[152:155], v83
	ds_read_b128 v[156:159], v83 offset:2048
	ds_read_b128 v[160:163], v83 offset:4096
	ds_read_b128 v[164:167], v83 offset:6144
	s_waitcnt lgkmcnt(8)
	v_mfma_f32_16x16x32_bf16 v[0:3], v[84:87], v[100:103], v[0:3]
	v_mfma_f32_16x16x32_bf16 v[4:7], v[84:87], v[104:107], v[4:7]
	v_mfma_f32_16x16x32_bf16 v[8:11], v[84:87], v[108:111], v[8:11]
	v_mfma_f32_16x16x32_bf16 v[12:15], v[84:87], v[112:115], v[12:15]
	v_mfma_f32_16x16x32_bf16 v[16:19], v[88:91], v[100:103], v[16:19]
	v_mfma_f32_16x16x32_bf16 v[20:23], v[88:91], v[104:107], v[20:23]
	v_mfma_f32_16x16x32_bf16 v[24:27], v[88:91], v[108:111], v[24:27]
	v_mfma_f32_16x16x32_bf16 v[28:31], v[88:91], v[112:115], v[28:31]
	v_mfma_f32_16x16x32_bf16 v[32:35], v[92:95], v[100:103], v[32:35]
	v_mfma_f32_16x16x32_bf16 v[36:39], v[92:95], v[104:107], v[36:39]
	v_mfma_f32_16x16x32_bf16 v[40:43], v[92:95], v[108:111], v[40:43]
	v_mfma_f32_16x16x32_bf16 v[44:47], v[92:95], v[112:115], v[44:47]
	v_mfma_f32_16x16x32_bf16 v[48:51], v[96:99], v[100:103], v[48:51]
	v_mfma_f32_16x16x32_bf16 v[52:55], v[96:99], v[104:107], v[52:55]
	v_mfma_f32_16x16x32_bf16 v[56:59], v[96:99], v[108:111], v[56:59]
	v_mfma_f32_16x16x32_bf16 v[60:63], v[96:99], v[112:115], v[60:63]
	s_waitcnt vmcnt(6) lgkmcnt(0)
	s_barrier
	ds_read_b128 v[84:87], v76
	ds_read_b128 v[88:91], v76 offset:2048
	ds_read_b128 v[92:95], v76 offset:4096
	ds_read_b128 v[96:99], v76 offset:6144
	ds_read_b128 v[100:103], v78
	ds_read_b128 v[104:107], v78 offset:2048
	ds_read_b128 v[108:111], v78 offset:4096
	ds_read_b128 v[112:115], v78 offset:6144
	v_mfma_f32_16x16x32_bf16 v[0:3], v[136:139], v[152:155], v[0:3]
	s_mov_b32 s24, 0x700
	s_mov_b32 s25, 0
	s_add_u32 m0, s30, 0x18000
	v_lshl_add_u64 v[124:125], v[64:65], 0, s[24:25]
	global_load_lds_dwordx4 v[124:125], off
	v_mfma_f32_16x16x32_bf16 v[4:7], v[136:139], v[156:159], v[4:7]
	s_add_u32 m0, s30, 0x1a000
	v_lshl_add_u64 v[126:127], v[66:67], 0, s[24:25]
	global_load_lds_dwordx4 v[126:127], off
	v_mfma_f32_16x16x32_bf16 v[8:11], v[136:139], v[160:163], v[8:11]
	s_add_u32 m0, s30, 0x1c000
	v_lshl_add_u64 v[124:125], v[68:69], 0, s[24:25]
	global_load_lds_dwordx4 v[124:125], off
	v_mfma_f32_16x16x32_bf16 v[12:15], v[136:139], v[164:167], v[12:15]
	s_add_u32 m0, s30, 0x1e000
	v_lshl_add_u64 v[126:127], v[70:71], 0, s[24:25]
	global_load_lds_dwordx4 v[126:127], off
	v_mfma_f32_16x16x32_bf16 v[16:19], v[140:143], v[152:155], v[16:19]
	s_add_u32 m0, s30, 0x20000
	v_lshl_add_u64 v[124:125], v[72:73], 0, s[24:25]
	global_load_lds_dwordx4 v[124:125], off
	v_mfma_f32_16x16x32_bf16 v[20:23], v[140:143], v[156:159], v[20:23]
	s_add_u32 m0, s30, 0x22000
	v_lshl_add_u64 v[126:127], v[74:75], 0, s[24:25]
	global_load_lds_dwordx4 v[126:127], off
	v_mfma_f32_16x16x32_bf16 v[24:27], v[140:143], v[160:163], v[24:27]
	v_mfma_f32_16x16x32_bf16 v[28:31], v[140:143], v[164:167], v[28:31]
	v_mfma_f32_16x16x32_bf16 v[32:35], v[144:147], v[152:155], v[32:35]
	v_mfma_f32_16x16x32_bf16 v[36:39], v[144:147], v[156:159], v[36:39]
	v_mfma_f32_16x16x32_bf16 v[40:43], v[144:147], v[160:163], v[40:43]
	v_mfma_f32_16x16x32_bf16 v[44:47], v[144:147], v[164:167], v[44:47]
	v_mfma_f32_16x16x32_bf16 v[48:51], v[148:151], v[152:155], v[48:51]
	v_mfma_f32_16x16x32_bf16 v[52:55], v[148:151], v[156:159], v[52:55]
	v_mfma_f32_16x16x32_bf16 v[56:59], v[148:151], v[160:163], v[56:59]
	v_mfma_f32_16x16x32_bf16 v[60:63], v[148:151], v[164:167], v[60:63]
	ds_read_b128 v[136:139], v77
	ds_read_b128 v[140:143], v77 offset:2048
	ds_read_b128 v[144:147], v77 offset:4096
	ds_read_b128 v[148:151], v77 offset:6144
	ds_read_b128 v[152:155], v79
	ds_read_b128 v[156:159], v79 offset:2048
	ds_read_b128 v[160:163], v79 offset:4096
	ds_read_b128 v[164:167], v79 offset:6144
	s_waitcnt lgkmcnt(8)
;     ...
;   for (int kt = 0; kt < nk; ++kt) {
;     if (kt + 1 < nk) asm volatile("s_waitcnt vmcnt(6)" ::: "memory");
;     else asm volatile("s_waitcnt vmcnt(0)" ::: "memory");
;     __builtin_amdgcn_s_barrier();
;     asm volatile("" ::: "memory");
;     if (kt + 2 < nk) { const int st2 = (st >= 1) ? st - 1 : 2; GEMM_ISSUE(kt + 2, st2); }
;     const char* la = lds + st * STAGE_B;
;     const char* lb = la + 32768;
;     const unsigned sa_u = (unsigned)(size_t)la + arow_u, sb_u = (unsigned)(size_t)lb + brow_u;
;     const unsigned a0 = sa_u + co0, a1 = sa_u + co1, a2 = sa_u + co2, a3 = sa_u + co3;
;     const unsigned b0 = sb_u + co0, b1 = sb_u + co1, b2 = sb_u + co2, b3 = sb_u + co3;
;     {
;       bf16x8 p0, p1, q0, q1, u0, u1, w0, w1;
;       asm volatile(
;         "ds_read_b128 %4, %12\n\tds_read_b128 %5, %12 offset:4096\n\tds_read_b128 %6, %16\n\tds_read_b128 %7, %16 offset:4096\n\t"
;         "ds_read_b128 %8, %13\n\tds_read_b128 %9, %13 offset:4096\n\tds_read_b128 %10, %17\n\tds_read_b128 %11, %17 offset:4096\n\t"
;         "s_waitcnt lgkmcnt(4)\n\t"
;         "v_mfma_f32_32x32x16_bf16 %0, %4, %6, %0\n\tv_mfma_f32_32x32x16_bf16 %1, %4, %7, %1\n\tv_mfma_f32_32x32x16_bf16 %2, %5, %6, %2\n\tv_mfma_f32_32x32x16_bf16 %3, %5, %7, %3\n\t"
;         "ds_read_b128 %4, %14\n\tds_read_b128 %5, %14 offset:4096\n\tds_read_b128 %6, %18\n\tds_read_b128 %7, %18 offset:4096\n\t"
;         "s_waitcnt lgkmcnt(4)\n\t"
;         "v_mfma_f32_32x32x16_bf16 %0, %8, %10, %0\n\tv_mfma_f32_32x32x16_bf16 %1, %8, %11, %1\n\tv_mfma_f32_32x32x16_bf16 %2, %9, %10, %2\n\tv_mfma_f32_32x32x16_bf16 %3, %9, %11, %3\n\t"
;         "ds_read_b128 %8, %15\n\tds_read_b128 %9, %15 offset:4096\n\tds_read_b128 %10, %19\n\tds_read_b128 %11, %19 offset:4096\n\t"
;         "s_waitcnt lgkmcnt(4)\n\t"
;         "v_mfma_f32_32x32x16_bf16 %0, %4, %6, %0\n\tv_mfma_f32_32x32x16_bf16 %1, %4, %7, %1\n\tv_mfma_f32_32x32x16_bf16 %2, %5, %6, %2\n\tv_mfma_f32_32x32x16_bf16 %3, %5, %7, %3\n\t"
;         "s_waitcnt lgkmcnt(0)\n\t"
;         "v_mfma_f32_32x32x16_bf16 %0, %8, %10, %0\n\tv_mfma_f32_32x32x16_bf16 %1, %8, %11, %1\n\tv_mfma_f32_32x32x16_bf16 %2, %9, %10, %2\n\tv_mfma_f32_32x32x16_bf16 %3, %9, %11, %3"
;         : "+v"(acc[0][0]), "+v"(acc[0][1]), "+v"(acc[1][0]), "+v"(acc[1][1]),
;           "=&v"(p0), "=&v"(p1), "=&v"(q0), "=&v"(q1), "=&v"(u0), "=&v"(u1), "=&v"(w0), "=&v"(w1)
	v_mfma_f32_16x16x32_bf16 v[0:3], v[84:87], v[100:103], v[0:3]
	v_mfma_f32_16x16x32_bf16 v[4:7], v[84:87], v[104:107], v[4:7]
	v_mfma_f32_16x16x32_bf16 v[8:11], v[84:87], v[108:111], v[8:11]
	v_mfma_f32_16x16x32_bf16 v[12:15], v[84:87], v[112:115], v[12:15]
	v_mfma_f32_16x16x32_bf16 v[16:19], v[88:91], v[100:103], v[16:19]
	v_mfma_f32_16x16x32_bf16 v[20:23], v[88:91], v[104:107], v[20:23]
	v_mfma_f32_16x16x32_bf16 v[24:27], v[88:91], v[108:111], v[24:27]
	v_mfma_f32_16x16x32_bf16 v[28:31], v[88:91], v[112:115], v[28:31]
	v_mfma_f32_16x16x32_bf16 v[32:35], v[92:95], v[100:103], v[32:35]
	v_mfma_f32_16x16x32_bf16 v[36:39], v[92:95], v[104:107], v[36:39]
	v_mfma_f32_16x16x32_bf16 v[40:43], v[92:95], v[108:111], v[40:43]
	v_mfma_f32_16x16x32_bf16 v[44:47], v[92:95], v[112:115], v[44:47]
	v_mfma_f32_16x16x32_bf16 v[48:51], v[96:99], v[100:103], v[48:51]
	v_mfma_f32_16x16x32_bf16 v[52:55], v[96:99], v[104:107], v[52:55]
	v_mfma_f32_16x16x32_bf16 v[56:59], v[96:99], v[108:111], v[56:59]
	v_mfma_f32_16x16x32_bf16 v[60:63], v[96:99], v[112:115], v[60:63]
	s_waitcnt vmcnt(6) lgkmcnt(0)
	s_barrier
	ds_read_b128 v[84:87], v76 offset:49152
	ds_read_b128 v[88:91], v76 offset:51200
	ds_read_b128 v[92:95], v76 offset:53248
	ds_read_b128 v[96:99], v76 offset:55296
	ds_read_b128 v[100:103], v78 offset:49152
	ds_read_b128 v[104:107], v78 offset:51200
	ds_read_b128 v[108:111], v78 offset:53248
	ds_read_b128 v[112:115], v78 offset:55296
	v_mfma_f32_16x16x32_bf16 v[0:3], v[136:139], v[152:155], v[0:3]
	s_mov_b32 s24, 0x780
	s_mov_b32 s25, 0
	s_mov_b32 m0, s30
	v_lshl_add_u64 v[124:125], v[64:65], 0, s[24:25]
	global_load_lds_dwordx4 v[124:125], off
	v_mfma_f32_16x16x32_bf16 v[4:7], v[136:139], v[156:159], v[4:7]
	s_add_u32 m0, s30, 0x2000
	v_lshl_add_u64 v[126:127], v[66:67], 0, s[24:25]
	global_load_lds_dwordx4 v[126:127], off
	v_mfma_f32_16x16x32_bf16 v[8:11], v[136:139], v[160:163], v[8:11]
	s_add_u32 m0, s30, 0x4000
	v_lshl_add_u64 v[124:125], v[68:69], 0, s[24:25]
	global_load_lds_dwordx4 v[124:125], off
	v_mfma_f32_16x16x32_bf16 v[12:15], v[136:139], v[164:167], v[12:15]
	s_add_u32 m0, s30, 0x6000
	v_lshl_add_u64 v[126:127], v[70:71], 0, s[24:25]
	global_load_lds_dwordx4 v[126:127], off
	v_mfma_f32_16x16x32_bf16 v[16:19], v[140:143], v[152:155], v[16:19]
	s_add_u32 m0, s30, 0x8000
	v_lshl_add_u64 v[124:125], v[72:73], 0, s[24:25]
	global_load_lds_dwordx4 v[124:125], off
	v_mfma_f32_16x16x32_bf16 v[20:23], v[140:143], v[156:159], v[20:23]
	s_add_u32 m0, s30, 0xa000
	v_lshl_add_u64 v[126:127], v[74:75], 0, s[24:25]
	global_load_lds_dwordx4 v[126:127], off
	v_mfma_f32_16x16x32_bf16 v[24:27], v[140:143], v[160:163], v[24:27]
	v_mfma_f32_16x16x32_bf16 v[28:31], v[140:143], v[164:167], v[28:31]
	v_mfma_f32_16x16x32_bf16 v[32:35], v[144:147], v[152:155], v[32:35]
	v_mfma_f32_16x16x32_bf16 v[36:39], v[144:147], v[156:159], v[36:39]
	v_mfma_f32_16x16x32_bf16 v[40:43], v[144:147], v[160:163], v[40:43]
	v_mfma_f32_16x16x32_bf16 v[44:47], v[144:147], v[164:167], v[44:47]
	v_mfma_f32_16x16x32_bf16 v[48:51], v[148:151], v[152:155], v[48:51]
	v_mfma_f32_16x16x32_bf16 v[52:55], v[148:151], v[156:159], v[52:55]
	v_mfma_f32_16x16x32_bf16 v[56:59], v[148:151], v[160:163], v[56:59]
	v_mfma_f32_16x16x32_bf16 v[60:63], v[148:151], v[164:167], v[60:63]
	ds_read_b128 v[136:139], v77 offset:49152
	ds_read_b128 v[140:143], v77 offset:51200
	ds_read_b128 v[144:147], v77 offset:53248
	ds_read_b128 v[148:151], v77 offset:55296
	ds_read_b128 v[152:155], v79 offset:49152
	ds_read_b128 v[156:159], v79 offset:51200
	ds_read_b128 v[160:163], v79 offset:53248
	ds_read_b128 v[164:167], v79 offset:55296
	s_waitcnt lgkmcnt(8)
	v_mfma_f32_16x16x32_bf16 v[0:3], v[84:87], v[100:103], v[0:3]
	v_mfma_f32_16x16x32_bf16 v[4:7], v[84:87], v[104:107], v[4:7]
	v_mfma_f32_16x16x32_bf16 v[8:11], v[84:87], v[108:111], v[8:11]
	v_mfma_f32_16x16x32_bf16 v[12:15], v[84:87], v[112:115], v[12:15]
	v_mfma_f32_16x16x32_bf16 v[16:19], v[88:91], v[100:103], v[16:19]
	v_mfma_f32_16x16x32_bf16 v[20:23], v[88:91], v[104:107], v[20:23]
	v_mfma_f32_16x16x32_bf16 v[24:27], v[88:91], v[108:111], v[24:27]
	v_mfma_f32_16x16x32_bf16 v[28:31], v[88:91], v[112:115], v[28:31]
	v_mfma_f32_16x16x32_bf16 v[32:35], v[92:95], v[100:103], v[32:35]
	v_mfma_f32_16x16x32_bf16 v[36:39], v[92:95], v[104:107], v[36:39]
	v_mfma_f32_16x16x32_bf16 v[40:43], v[92:95], v[108:111], v[40:43]
	v_mfma_f32_16x16x32_bf16 v[44:47], v[92:95], v[112:115], v[44:47]
	v_mfma_f32_16x16x32_bf16 v[48:51], v[96:99], v[100:103], v[48:51]
	v_mfma_f32_16x16x32_bf16 v[52:55], v[96:99], v[104:107], v[52:55]
	v_mfma_f32_16x16x32_bf16 v[56:59], v[96:99], v[108:111], v[56:59]
	v_mfma_f32_16x16x32_bf16 v[60:63], v[96:99], v[112:115], v[60:63]
	s_waitcnt vmcnt(6) lgkmcnt(0)
	s_barrier
;     ...
;   for (int kt = 0; kt < nk; ++kt) {
;     if (kt + 1 < nk) asm volatile("s_waitcnt vmcnt(6)" ::: "memory");
;     else asm volatile("s_waitcnt vmcnt(0)" ::: "memory");
;     __builtin_amdgcn_s_barrier();
;     asm volatile("" ::: "memory");
;     if (kt + 2 < nk) { const int st2 = (st >= 1) ? st - 1 : 2; GEMM_ISSUE(kt + 2, st2); }
;     const char* la = lds + st * STAGE_B;
;     const char* lb = la + 32768;
;     const unsigned sa_u = (unsigned)(size_t)la + arow_u, sb_u = (unsigned)(size_t)lb + brow_u;
;     const unsigned a0 = sa_u + co0, a1 = sa_u + co1, a2 = sa_u + co2, a3 = sa_u + co3;
;     const unsigned b0 = sb_u + co0, b1 = sb_u + co1, b2 = sb_u + co2, b3 = sb_u + co3;
;     {
;       bf16x8 p0, p1, q0, q1, u0, u1, w0, w1;
;       asm volatile(
;         "ds_read_b128 %4, %12\n\tds_read_b128 %5, %12 offset:4096\n\tds_read_b128 %6, %16\n\tds_read_b128 %7, %16 offset:4096\n\t"
;         "ds_read_b128 %8, %13\n\tds_read_b128 %9, %13 offset:4096\n\tds_read_b128 %10, %17\n\tds_read_b128 %11, %17 offset:4096\n\t"
;         "s_waitcnt lgkmcnt(4)\n\t"
;         "v_mfma_f32_32x32x16_bf16 %0, %4, %6, %0\n\tv_mfma_f32_32x32x16_bf16 %1, %4, %7, %1\n\tv_mfma_f32_32x32x16_bf16 %2, %5, %6, %2\n\tv_mfma_f32_32x32x16_bf16 %3, %5, %7, %3\n\t"
;         "ds_read_b128 %4, %14\n\tds_read_b128 %5, %14 offset:4096\n\tds_read_b128 %6, %18\n\tds_read_b128 %7, %18 offset:4096\n\t"
;         "s_waitcnt lgkmcnt(4)\n\t"
;         "v_mfma_f32_32x32x16_bf16 %0, %8, %10, %0\n\tv_mfma_f32_32x32x16_bf16 %1, %8, %11, %1\n\tv_mfma_f32_32x32x16_bf16 %2, %9, %10, %2\n\tv_mfma_f32_32x32x16_bf16 %3, %9, %11, %3\n\t"
;         "ds_read_b128 %8, %15\n\tds_read_b128 %9, %15 offset:4096\n\tds_read_b128 %10, %19\n\tds_read_b128 %11, %19 offset:4096\n\t"
;         "s_waitcnt lgkmcnt(4)\n\t"
;         "v_mfma_f32_32x32x16_bf16 %0, %4, %6, %0\n\tv_mfma_f32_32x32x16_bf16 %1, %4, %7, %1\n\tv_mfma_f32_32x32x16_bf16 %2, %5, %6, %2\n\tv_mfma_f32_32x32x16_bf16 %3, %5, %7, %3\n\t"
;         "s_waitcnt lgkmcnt(0)\n\t"
;         "v_mfma_f32_32x32x16_bf16 %0, %8, %10, %0\n\tv_mfma_f32_32x32x16_bf16 %1, %8, %11, %1\n\tv_mfma_f32_32x32x16_bf16 %2, %9, %10, %2\n\tv_mfma_f32_32x32x16_bf16 %3, %9, %11, %3"
;         : "+v"(acc[0][0]), "+v"(acc[0][1]), "+v"(acc[1][0]), "+v"(acc[1][1]),
;           "=&v"(p0), "=&v"(p1), "=&v"(q0), "=&v"(q1), "=&v"(u0), "=&v"(u1), "=&v"(w0), "=&v"(w1)
	ds_read_b128 v[84:87], v80
	ds_read_b128 v[88:91], v80 offset:2048
	ds_read_b128 v[92:95], v80 offset:4096
	ds_read_b128 v[96:99], v80 offset:6144
	ds_read_b128 v[100:103], v82
	ds_read_b128 v[104:107], v82 offset:2048
	ds_read_b128 v[108:111], v82 offset:4096
	ds_read_b128 v[112:115], v82 offset:6144
	v_mfma_f32_16x16x32_bf16 v[0:3], v[136:139], v[152:155], v[0:3]
	s_add_u32 s24, s56, 0x0
	s_addc_u32 s25, s57, 0
	s_add_u32 m0, s30, 0xc000
	v_lshl_add_u64 v[124:125], v[64:65], 0, s[24:25]
	global_load_lds_dwordx4 v[124:125], off
	v_mfma_f32_16x16x32_bf16 v[4:7], v[136:139], v[156:159], v[4:7]
	s_add_u32 m0, s30, 0xe000
	v_lshl_add_u64 v[126:127], v[66:67], 0, s[24:25]
	global_load_lds_dwordx4 v[126:127], off
	v_mfma_f32_16x16x32_bf16 v[8:11], v[136:139], v[160:163], v[8:11]
	s_add_u32 m0, s30, 0x10000
	v_lshl_add_u64 v[124:125], v[68:69], 0, s[24:25]
	global_load_lds_dwordx4 v[124:125], off
	v_mfma_f32_16x16x32_bf16 v[12:15], v[136:139], v[164:167], v[12:15]
	s_add_u32 m0, s30, 0x12000
	v_lshl_add_u64 v[126:127], v[70:71], 0, s[24:25]
	global_load_lds_dwordx4 v[126:127], off
	v_mfma_f32_16x16x32_bf16 v[16:19], v[140:143], v[152:155], v[16:19]
	s_add_u32 s24, s58, 0x0
	s_addc_u32 s25, s59, 0
	s_add_u32 m0, s30, 0x14000
	v_lshl_add_u64 v[124:125], v[72:73], 0, s[24:25]
	global_load_lds_dwordx4 v[124:125], off
	v_mfma_f32_16x16x32_bf16 v[20:23], v[140:143], v[156:159], v[20:23]
	s_add_u32 m0, s30, 0x16000
	v_lshl_add_u64 v[126:127], v[74:75], 0, s[24:25]
	global_load_lds_dwordx4 v[126:127], off
	v_mfma_f32_16x16x32_bf16 v[24:27], v[140:143], v[160:163], v[24:27]
	v_mfma_f32_16x16x32_bf16 v[28:31], v[140:143], v[164:167], v[28:31]
	v_mfma_f32_16x16x32_bf16 v[32:35], v[144:147], v[152:155], v[32:35]
	v_mfma_f32_16x16x32_bf16 v[36:39], v[144:147], v[156:159], v[36:39]
	v_mfma_f32_16x16x32_bf16 v[40:43], v[144:147], v[160:163], v[40:43]
	v_mfma_f32_16x16x32_bf16 v[44:47], v[144:147], v[164:167], v[44:47]
	v_mfma_f32_16x16x32_bf16 v[48:51], v[148:151], v[152:155], v[48:51]
	v_mfma_f32_16x16x32_bf16 v[52:55], v[148:151], v[156:159], v[52:55]
	v_mfma_f32_16x16x32_bf16 v[56:59], v[148:151], v[160:163], v[56:59]
	v_mfma_f32_16x16x32_bf16 v[60:63], v[148:151], v[164:167], v[60:63]
	ds_read_b128 v[136:139], v81
	ds_read_b128 v[140:143], v81 offset:2048
	ds_read_b128 v[144:147], v81 offset:4096
	ds_read_b128 v[148:151], v81 offset:6144
	ds_read_b128 v[152:155], v83
	ds_read_b128 v[156:159], v83 offset:2048
	ds_read_b128 v[160:163], v83 offset:4096
	ds_read_b128 v[164:167], v83 offset:6144
	s_waitcnt lgkmcnt(8)
	v_mfma_f32_16x16x32_bf16 v[0:3], v[84:87], v[100:103], v[0:3]
	v_mfma_f32_16x16x32_bf16 v[4:7], v[84:87], v[104:107], v[4:7]
	v_mfma_f32_16x16x32_bf16 v[8:11], v[84:87], v[108:111], v[8:11]
	v_mfma_f32_16x16x32_bf16 v[12:15], v[84:87], v[112:115], v[12:15]
	v_mfma_f32_16x16x32_bf16 v[16:19], v[88:91], v[100:103], v[16:19]
	v_mfma_f32_16x16x32_bf16 v[20:23], v[88:91], v[104:107], v[20:23]
	v_mfma_f32_16x16x32_bf16 v[24:27], v[88:91], v[108:111], v[24:27]
	v_mfma_f32_16x16x32_bf16 v[28:31], v[88:91], v[112:115], v[28:31]
	v_mfma_f32_16x16x32_bf16 v[32:35], v[92:95], v[100:103], v[32:35]
	v_mfma_f32_16x16x32_bf16 v[36:39], v[92:95], v[104:107], v[36:39]
	v_mfma_f32_16x16x32_bf16 v[40:43], v[92:95], v[108:111], v[40:43]
	v_mfma_f32_16x16x32_bf16 v[44:47], v[92:95], v[112:115], v[44:47]
	v_mfma_f32_16x16x32_bf16 v[48:51], v[96:99], v[100:103], v[48:51]
	v_mfma_f32_16x16x32_bf16 v[52:55], v[96:99], v[104:107], v[52:55]
	v_mfma_f32_16x16x32_bf16 v[56:59], v[96:99], v[108:111], v[56:59]
	v_mfma_f32_16x16x32_bf16 v[60:63], v[96:99], v[112:115], v[60:63]
	s_waitcnt vmcnt(6) lgkmcnt(0)
	s_barrier
	ds_read_b128 v[84:87], v76
	ds_read_b128 v[88:91], v76 offset:2048
	ds_read_b128 v[92:95], v76 offset:4096
	ds_read_b128 v[96:99], v76 offset:6144
	ds_read_b128 v[100:103], v78
	ds_read_b128 v[104:107], v78 offset:2048
	ds_read_b128 v[108:111], v78 offset:4096
	ds_read_b128 v[112:115], v78 offset:6144
	v_mfma_f32_16x16x32_bf16 v[0:3], v[136:139], v[152:155], v[0:3]
	s_add_u32 s24, s56, 0x80
	s_addc_u32 s25, s57, 0
	s_add_u32 m0, s30, 0x18000
	v_lshl_add_u64 v[124:125], v[64:65], 0, s[24:25]
	global_load_lds_dwordx4 v[124:125], off
	v_mfma_f32_16x16x32_bf16 v[4:7], v[136:139], v[156:159], v[4:7]
	s_add_u32 m0, s30, 0x1a000
	v_lshl_add_u64 v[126:127], v[66:67], 0, s[24:25]
	global_load_lds_dwordx4 v[126:127], off
	v_mfma_f32_16x16x32_bf16 v[8:11], v[136:139], v[160:163], v[8:11]
	s_add_u32 m0, s30, 0x1c000
	v_lshl_add_u64 v[124:125], v[68:69], 0, s[24:25]
	global_load_lds_dwordx4 v[124:125], off
	v_mfma_f32_16x16x32_bf16 v[12:15], v[136:139], v[164:167], v[12:15]
	s_add_u32 m0, s30, 0x1e000
	v_lshl_add_u64 v[126:127], v[70:71], 0, s[24:25]
	global_load_lds_dwordx4 v[126:127], off
	v_mfma_f32_16x16x32_bf16 v[16:19], v[140:143], v[152:155], v[16:19]
	s_add_u32 s24, s58, 0x80
	s_addc_u32 s25, s59, 0
	s_add_u32 m0, s30, 0x20000
	v_lshl_add_u64 v[124:125], v[72:73], 0, s[24:25]
	global_load_lds_dwordx4 v[124:125], off
	v_mfma_f32_16x16x32_bf16 v[20:23], v[140:143], v[156:159], v[20:23]
	s_add_u32 m0, s30, 0x22000
	v_lshl_add_u64 v[126:127], v[74:75], 0, s[24:25]
	global_load_lds_dwordx4 v[126:127], off
	v_mfma_f32_16x16x32_bf16 v[24:27], v[140:143], v[160:163], v[24:27]
	v_mfma_f32_16x16x32_bf16 v[28:31], v[140:143], v[164:167], v[28:31]
	v_mfma_f32_16x16x32_bf16 v[32:35], v[144:147], v[152:155], v[32:35]
	v_mfma_f32_16x16x32_bf16 v[36:39], v[144:147], v[156:159], v[36:39]
	v_mfma_f32_16x16x32_bf16 v[40:43], v[144:147], v[160:163], v[40:43]
	v_mfma_f32_16x16x32_bf16 v[44:47], v[144:147], v[164:167], v[44:47]
	v_mfma_f32_16x16x32_bf16 v[48:51], v[148:151], v[152:155], v[48:51]
	v_mfma_f32_16x16x32_bf16 v[52:55], v[148:151], v[156:159], v[52:55]
	v_mfma_f32_16x16x32_bf16 v[56:59], v[148:151], v[160:163], v[56:59]
	v_mfma_f32_16x16x32_bf16 v[60:63], v[148:151], v[164:167], v[60:63]
	ds_read_b128 v[136:139], v77
	ds_read_b128 v[140:143], v77 offset:2048
	ds_read_b128 v[144:147], v77 offset:4096
	ds_read_b128 v[148:151], v77 offset:6144
	ds_read_b128 v[152:155], v79
	ds_read_b128 v[156:159], v79 offset:2048
	ds_read_b128 v[160:163], v79 offset:4096
	ds_read_b128 v[164:167], v79 offset:6144
	s_waitcnt lgkmcnt(8)
;     ...
;   for (int kt = 0; kt < nk; ++kt) {
;     if (kt + 1 < nk) asm volatile("s_waitcnt vmcnt(6)" ::: "memory");
;     else asm volatile("s_waitcnt vmcnt(0)" ::: "memory");
;     __builtin_amdgcn_s_barrier();
;     asm volatile("" ::: "memory");
;     if (kt + 2 < nk) { const int st2 = (st >= 1) ? st - 1 : 2; GEMM_ISSUE(kt + 2, st2); }
;     const char* la = lds + st * STAGE_B;
;     const char* lb = la + 32768;
;     const unsigned sa_u = (unsigned)(size_t)la + arow_u, sb_u = (unsigned)(size_t)lb + brow_u;
;     const unsigned a0 = sa_u + co0, a1 = sa_u + co1, a2 = sa_u + co2, a3 = sa_u + co3;
;     const unsigned b0 = sb_u + co0, b1 = sb_u + co1, b2 = sb_u + co2, b3 = sb_u + co3;
;     {
;       bf16x8 p0, p1, q0, q1, u0, u1, w0, w1;
;       asm volatile(
;         "ds_read_b128 %4, %12\n\tds_read_b128 %5, %12 offset:4096\n\tds_read_b128 %6, %16\n\tds_read_b128 %7, %16 offset:4096\n\t"
;         "ds_read_b128 %8, %13\n\tds_read_b128 %9, %13 offset:4096\n\tds_read_b128 %10, %17\n\tds_read_b128 %11, %17 offset:4096\n\t"
;         "s_waitcnt lgkmcnt(4)\n\t"
;         "v_mfma_f32_32x32x16_bf16 %0, %4, %6, %0\n\tv_mfma_f32_32x32x16_bf16 %1, %4, %7, %1\n\tv_mfma_f32_32x32x16_bf16 %2, %5, %6, %2\n\tv_mfma_f32_32x32x16_bf16 %3, %5, %7, %3\n\t"
;         "ds_read_b128 %4, %14\n\tds_read_b128 %5, %14 offset:4096\n\tds_read_b128 %6, %18\n\tds_read_b128 %7, %18 offset:4096\n\t"
;         "s_waitcnt lgkmcnt(4)\n\t"
;         "v_mfma_f32_32x32x16_bf16 %0, %8, %10, %0\n\tv_mfma_f32_32x32x16_bf16 %1, %8, %11, %1\n\tv_mfma_f32_32x32x16_bf16 %2, %9, %10, %2\n\tv_mfma_f32_32x32x16_bf16 %3, %9, %11, %3\n\t"
;         "ds_read_b128 %8, %15\n\tds_read_b128 %9, %15 offset:4096\n\tds_read_b128 %10, %19\n\tds_read_b128 %11, %19 offset:4096\n\t"
;         "s_waitcnt lgkmcnt(4)\n\t"
;         "v_mfma_f32_32x32x16_bf16 %0, %4, %6, %0\n\tv_mfma_f32_32x32x16_bf16 %1, %4, %7, %1\n\tv_mfma_f32_32x32x16_bf16 %2, %5, %6, %2\n\tv_mfma_f32_32x32x16_bf16 %3, %5, %7, %3\n\t"
;         "s_waitcnt lgkmcnt(0)\n\t"
;         "v_mfma_f32_32x32x16_bf16 %0, %8, %10, %0\n\tv_mfma_f32_32x32x16_bf16 %1, %8, %11, %1\n\tv_mfma_f32_32x32x16_bf16 %2, %9, %10, %2\n\tv_mfma_f32_32x32x16_bf16 %3, %9, %11, %3"
;         : "+v"(acc[0][0]), "+v"(acc[0][1]), "+v"(acc[1][0]), "+v"(acc[1][1]),
;           "=&v"(p0), "=&v"(p1), "=&v"(q0), "=&v"(q1), "=&v"(u0), "=&v"(u1), "=&v"(w0), "=&v"(w1)
	v_mfma_f32_16x16x32_bf16 v[0:3], v[84:87], v[100:103], v[0:3]
	v_mfma_f32_16x16x32_bf16 v[4:7], v[84:87], v[104:107], v[4:7]
	v_mfma_f32_16x16x32_bf16 v[8:11], v[84:87], v[108:111], v[8:11]
	v_mfma_f32_16x16x32_bf16 v[12:15], v[84:87], v[112:115], v[12:15]
	v_mfma_f32_16x16x32_bf16 v[16:19], v[88:91], v[100:103], v[16:19]
	v_mfma_f32_16x16x32_bf16 v[20:23], v[88:91], v[104:107], v[20:23]
	v_mfma_f32_16x16x32_bf16 v[24:27], v[88:91], v[108:111], v[24:27]
	v_mfma_f32_16x16x32_bf16 v[28:31], v[88:91], v[112:115], v[28:31]
	v_mfma_f32_16x16x32_bf16 v[32:35], v[92:95], v[100:103], v[32:35]
	v_mfma_f32_16x16x32_bf16 v[36:39], v[92:95], v[104:107], v[36:39]
	v_mfma_f32_16x16x32_bf16 v[40:43], v[92:95], v[108:111], v[40:43]
	v_mfma_f32_16x16x32_bf16 v[44:47], v[92:95], v[112:115], v[44:47]
	v_mfma_f32_16x16x32_bf16 v[48:51], v[96:99], v[100:103], v[48:51]
	v_mfma_f32_16x16x32_bf16 v[52:55], v[96:99], v[104:107], v[52:55]
	v_mfma_f32_16x16x32_bf16 v[56:59], v[96:99], v[108:111], v[56:59]
	v_mfma_f32_16x16x32_bf16 v[60:63], v[96:99], v[112:115], v[60:63]
	s_waitcnt lgkmcnt(0)
	v_mfma_f32_16x16x32_bf16 v[0:3], v[136:139], v[152:155], v[0:3]
	v_mfma_f32_16x16x32_bf16 v[4:7], v[136:139], v[156:159], v[4:7]
	v_mfma_f32_16x16x32_bf16 v[8:11], v[136:139], v[160:163], v[8:11]
	v_mfma_f32_16x16x32_bf16 v[12:15], v[136:139], v[164:167], v[12:15]
	v_mfma_f32_16x16x32_bf16 v[16:19], v[140:143], v[152:155], v[16:19]
	v_mfma_f32_16x16x32_bf16 v[20:23], v[140:143], v[156:159], v[20:23]
	v_mfma_f32_16x16x32_bf16 v[24:27], v[140:143], v[160:163], v[24:27]
	v_mfma_f32_16x16x32_bf16 v[28:31], v[140:143], v[164:167], v[28:31]
	v_mfma_f32_16x16x32_bf16 v[32:35], v[144:147], v[152:155], v[32:35]
	v_mfma_f32_16x16x32_bf16 v[36:39], v[144:147], v[156:159], v[36:39]
	v_mfma_f32_16x16x32_bf16 v[40:43], v[144:147], v[160:163], v[40:43]
	v_mfma_f32_16x16x32_bf16 v[44:47], v[144:147], v[164:167], v[44:47]
	v_mfma_f32_16x16x32_bf16 v[48:51], v[148:151], v[152:155], v[48:51]
	v_mfma_f32_16x16x32_bf16 v[52:55], v[148:151], v[156:159], v[52:55]
	v_mfma_f32_16x16x32_bf16 v[56:59], v[148:151], v[160:163], v[56:59]
	v_mfma_f32_16x16x32_bf16 v[60:63], v[148:151], v[164:167], v[60:63]
	s_branch .Ly11_done
.Ly11_v1:
	ds_read_b128 v[84:87], v76 offset:49152
	ds_read_b128 v[88:91], v76 offset:51200
	ds_read_b128 v[92:95], v76 offset:53248
	ds_read_b128 v[96:99], v76 offset:55296
	ds_read_b128 v[100:103], v78 offset:49152
	ds_read_b128 v[104:107], v78 offset:51200
	ds_read_b128 v[108:111], v78 offset:53248
	ds_read_b128 v[112:115], v78 offset:55296
	s_mov_b32 s24, 0x100
	s_mov_b32 s25, 0
	s_mov_b32 m0, s30
	v_lshl_add_u64 v[124:125], v[64:65], 0, s[24:25]
	global_load_lds_dwordx4 v[124:125], off
	s_add_u32 m0, s30, 0x2000
	v_lshl_add_u64 v[126:127], v[66:67], 0, s[24:25]
	global_load_lds_dwordx4 v[126:127], off
	s_add_u32 m0, s30, 0x4000
	v_lshl_add_u64 v[124:125], v[68:69], 0, s[24:25]
	global_load_lds_dwordx4 v[124:125], off
	s_add_u32 m0, s30, 0x6000
	v_lshl_add_u64 v[126:127], v[70:71], 0, s[24:25]
	global_load_lds_dwordx4 v[126:127], off
	s_add_u32 m0, s30, 0x8000
	v_lshl_add_u64 v[124:125], v[72:73], 0, s[24:25]
	global_load_lds_dwordx4 v[124:125], off
	s_add_u32 m0, s30, 0xa000
	v_lshl_add_u64 v[126:127], v[74:75], 0, s[24:25]
	global_load_lds_dwordx4 v[126:127], off
	ds_read_b128 v[136:139], v77 offset:49152
	ds_read_b128 v[140:143], v77 offset:51200
	ds_read_b128 v[144:147], v77 offset:53248
	ds_read_b128 v[148:151], v77 offset:55296
	ds_read_b128 v[152:155], v79 offset:49152
	ds_read_b128 v[156:159], v79 offset:51200
	ds_read_b128 v[160:163], v79 offset:53248
	ds_read_b128 v[164:167], v79 offset:55296
	s_waitcnt lgkmcnt(8)
	v_mfma_f32_16x16x32_bf16 v[0:3], v[84:87], v[100:103], v[0:3]
	v_mfma_f32_16x16x32_bf16 v[4:7], v[84:87], v[104:107], v[4:7]
	v_mfma_f32_16x16x32_bf16 v[8:11], v[84:87], v[108:111], v[8:11]
	v_mfma_f32_16x16x32_bf16 v[12:15], v[84:87], v[112:115], v[12:15]
	v_mfma_f32_16x16x32_bf16 v[16:19], v[88:91], v[100:103], v[16:19]
	v_mfma_f32_16x16x32_bf16 v[20:23], v[88:91], v[104:107], v[20:23]
	v_mfma_f32_16x16x32_bf16 v[24:27], v[88:91], v[108:111], v[24:27]
	v_mfma_f32_16x16x32_bf16 v[28:31], v[88:91], v[112:115], v[28:31]
	v_mfma_f32_16x16x32_bf16 v[32:35], v[92:95], v[100:103], v[32:35]
	v_mfma_f32_16x16x32_bf16 v[36:39], v[92:95], v[104:107], v[36:39]
	v_mfma_f32_16x16x32_bf16 v[40:43], v[92:95], v[108:111], v[40:43]
	v_mfma_f32_16x16x32_bf16 v[44:47], v[92:95], v[112:115], v[44:47]
	v_mfma_f32_16x16x32_bf16 v[48:51], v[96:99], v[100:103], v[48:51]
	v_mfma_f32_16x16x32_bf16 v[52:55], v[96:99], v[104:107], v[52:55]
	v_mfma_f32_16x16x32_bf16 v[56:59], v[96:99], v[108:111], v[56:59]
	v_mfma_f32_16x16x32_bf16 v[60:63], v[96:99], v[112:115], v[60:63]
	s_waitcnt vmcnt(6) lgkmcnt(0)
	s_barrier
;     ...
;   for (int kt = 0; kt < nk; ++kt) {
;     if (kt + 1 < nk) asm volatile("s_waitcnt vmcnt(6)" ::: "memory");
;     else asm volatile("s_waitcnt vmcnt(0)" ::: "memory");
;     __builtin_amdgcn_s_barrier();
;     asm volatile("" ::: "memory");
;     if (kt + 2 < nk) { const int st2 = (st >= 1) ? st - 1 : 2; GEMM_ISSUE(kt + 2, st2); }
;     const char* la = lds + st * STAGE_B;
;     const char* lb = la + 32768;
;     const unsigned sa_u = (unsigned)(size_t)la + arow_u, sb_u = (unsigned)(size_t)lb + brow_u;
;     const unsigned a0 = sa_u + co0, a1 = sa_u + co1, a2 = sa_u + co2, a3 = sa_u + co3;
;     const unsigned b0 = sb_u + co0, b1 = sb_u + co1, b2 = sb_u + co2, b3 = sb_u + co3;
;     {
;       bf16x8 p0, p1, q0, q1, u0, u1, w0, w1;
;       asm volatile(
;         "ds_read_b128 %4, %12\n\tds_read_b128 %5, %12 offset:4096\n\tds_read_b128 %6, %16\n\tds_read_b128 %7, %16 offset:4096\n\t"
;         "ds_read_b128 %8, %13\n\tds_read_b128 %9, %13 offset:4096\n\tds_read_b128 %10, %17\n\tds_read_b128 %11, %17 offset:4096\n\t"
;         "s_waitcnt lgkmcnt(4)\n\t"
;         "v_mfma_f32_32x32x16_bf16 %0, %4, %6, %0\n\tv_mfma_f32_32x32x16_bf16 %1, %4, %7, %1\n\tv_mfma_f32_32x32x16_bf16 %2, %5, %6, %2\n\tv_mfma_f32_32x32x16_bf16 %3, %5, %7, %3\n\t"
;         "ds_read_b128 %4, %14\n\tds_read_b128 %5, %14 offset:4096\n\tds_read_b128 %6, %18\n\tds_read_b128 %7, %18 offset:4096\n\t"
;         "s_waitcnt lgkmcnt(4)\n\t"
;         "v_mfma_f32_32x32x16_bf16 %0, %8, %10, %0\n\tv_mfma_f32_32x32x16_bf16 %1, %8, %11, %1\n\tv_mfma_f32_32x32x16_bf16 %2, %9, %10, %2\n\tv_mfma_f32_32x32x16_bf16 %3, %9, %11, %3\n\t"
;         "ds_read_b128 %8, %15\n\tds_read_b128 %9, %15 offset:4096\n\tds_read_b128 %10, %19\n\tds_read_b128 %11, %19 offset:4096\n\t"
;         "s_waitcnt lgkmcnt(4)\n\t"
;         "v_mfma_f32_32x32x16_bf16 %0, %4, %6, %0\n\tv_mfma_f32_32x32x16_bf16 %1, %4, %7, %1\n\tv_mfma_f32_32x32x16_bf16 %2, %5, %6, %2\n\tv_mfma_f32_32x32x16_bf16 %3, %5, %7, %3\n\t"
;         "s_waitcnt lgkmcnt(0)\n\t"
;         "v_mfma_f32_32x32x16_bf16 %0, %8, %10, %0\n\tv_mfma_f32_32x32x16_bf16 %1, %8, %11, %1\n\tv_mfma_f32_32x32x16_bf16 %2, %9, %10, %2\n\tv_mfma_f32_32x32x16_bf16 %3, %9, %11, %3"
;         : "+v"(acc[0][0]), "+v"(acc[0][1]), "+v"(acc[1][0]), "+v"(acc[1][1]),
;           "=&v"(p0), "=&v"(p1), "=&v"(q0), "=&v"(q1), "=&v"(u0), "=&v"(u1), "=&v"(w0), "=&v"(w1)
	ds_read_b128 v[84:87], v80
	ds_read_b128 v[88:91], v80 offset:2048
	ds_read_b128 v[92:95], v80 offset:4096
	ds_read_b128 v[96:99], v80 offset:6144
	ds_read_b128 v[100:103], v82
	ds_read_b128 v[104:107], v82 offset:2048
	ds_read_b128 v[108:111], v82 offset:4096
	ds_read_b128 v[112:115], v82 offset:6144
	v_mfma_f32_16x16x32_bf16 v[0:3], v[136:139], v[152:155], v[0:3]
	s_mov_b32 s24, 0x180
	s_mov_b32 s25, 0
	s_add_u32 m0, s30, 0xc000
	v_lshl_add_u64 v[124:125], v[64:65], 0, s[24:25]
	global_load_lds_dwordx4 v[124:125], off
	v_mfma_f32_16x16x32_bf16 v[4:7], v[136:139], v[156:159], v[4:7]
	s_add_u32 m0, s30, 0xe000
	v_lshl_add_u64 v[126:127], v[66:67], 0, s[24:25]
	global_load_lds_dwordx4 v[126:127], off
	v_mfma_f32_16x16x32_bf16 v[8:11], v[136:139], v[160:163], v[8:11]
	s_add_u32 m0, s30, 0x10000
	v_lshl_add_u64 v[124:125], v[68:69], 0, s[24:25]
	global_load_lds_dwordx4 v[124:125], off
	v_mfma_f32_16x16x32_bf16 v[12:15], v[136:139], v[164:167], v[12:15]
	s_add_u32 m0, s30, 0x12000
	v_lshl_add_u64 v[126:127], v[70:71], 0, s[24:25]
	global_load_lds_dwordx4 v[126:127], off
	v_mfma_f32_16x16x32_bf16 v[16:19], v[140:143], v[152:155], v[16:19]
	s_add_u32 m0, s30, 0x14000
	v_lshl_add_u64 v[124:125], v[72:73], 0, s[24:25]
	global_load_lds_dwordx4 v[124:125], off
	v_mfma_f32_16x16x32_bf16 v[20:23], v[140:143], v[156:159], v[20:23]
	s_add_u32 m0, s30, 0x16000
	v_lshl_add_u64 v[126:127], v[74:75], 0, s[24:25]
	global_load_lds_dwordx4 v[126:127], off
	v_mfma_f32_16x16x32_bf16 v[24:27], v[140:143], v[160:163], v[24:27]
	v_mfma_f32_16x16x32_bf16 v[28:31], v[140:143], v[164:167], v[28:31]
	v_mfma_f32_16x16x32_bf16 v[32:35], v[144:147], v[152:155], v[32:35]
	v_mfma_f32_16x16x32_bf16 v[36:39], v[144:147], v[156:159], v[36:39]
	v_mfma_f32_16x16x32_bf16 v[40:43], v[144:147], v[160:163], v[40:43]
	v_mfma_f32_16x16x32_bf16 v[44:47], v[144:147], v[164:167], v[44:47]
	v_mfma_f32_16x16x32_bf16 v[48:51], v[148:151], v[152:155], v[48:51]
	v_mfma_f32_16x16x32_bf16 v[52:55], v[148:151], v[156:159], v[52:55]
	v_mfma_f32_16x16x32_bf16 v[56:59], v[148:151], v[160:163], v[56:59]
	v_mfma_f32_16x16x32_bf16 v[60:63], v[148:151], v[164:167], v[60:63]
	ds_read_b128 v[136:139], v81
	ds_read_b128 v[140:143], v81 offset:2048
	ds_read_b128 v[144:147], v81 offset:4096
	ds_read_b128 v[148:151], v81 offset:6144
	ds_read_b128 v[152:155], v83
	ds_read_b128 v[156:159], v83 offset:2048
	ds_read_b128 v[160:163], v83 offset:4096
	ds_read_b128 v[164:167], v83 offset:6144
	s_waitcnt lgkmcnt(8)
	v_mfma_f32_16x16x32_bf16 v[0:3], v[84:87], v[100:103], v[0:3]
	v_mfma_f32_16x16x32_bf16 v[4:7], v[84:87], v[104:107], v[4:7]
	v_mfma_f32_16x16x32_bf16 v[8:11], v[84:87], v[108:111], v[8:11]
	v_mfma_f32_16x16x32_bf16 v[12:15], v[84:87], v[112:115], v[12:15]
	v_mfma_f32_16x16x32_bf16 v[16:19], v[88:91], v[100:103], v[16:19]
	v_mfma_f32_16x16x32_bf16 v[20:23], v[88:91], v[104:107], v[20:23]
	v_mfma_f32_16x16x32_bf16 v[24:27], v[88:91], v[108:111], v[24:27]
	v_mfma_f32_16x16x32_bf16 v[28:31], v[88:91], v[112:115], v[28:31]
	v_mfma_f32_16x16x32_bf16 v[32:35], v[92:95], v[100:103], v[32:35]
	v_mfma_f32_16x16x32_bf16 v[36:39], v[92:95], v[104:107], v[36:39]
	v_mfma_f32_16x16x32_bf16 v[40:43], v[92:95], v[108:111], v[40:43]
	v_mfma_f32_16x16x32_bf16 v[44:47], v[92:95], v[112:115], v[44:47]
	v_mfma_f32_16x16x32_bf16 v[48:51], v[96:99], v[100:103], v[48:51]
	v_mfma_f32_16x16x32_bf16 v[52:55], v[96:99], v[104:107], v[52:55]
	v_mfma_f32_16x16x32_bf16 v[56:59], v[96:99], v[108:111], v[56:59]
	v_mfma_f32_16x16x32_bf16 v[60:63], v[96:99], v[112:115], v[60:63]
	s_waitcnt vmcnt(6) lgkmcnt(0)
	s_barrier
	ds_read_b128 v[84:87], v76
	ds_read_b128 v[88:91], v76 offset:2048
	ds_read_b128 v[92:95], v76 offset:4096
	ds_read_b128 v[96:99], v76 offset:6144
	ds_read_b128 v[100:103], v78
	ds_read_b128 v[104:107], v78 offset:2048
	ds_read_b128 v[108:111], v78 offset:4096
	ds_read_b128 v[112:115], v78 offset:6144
	v_mfma_f32_16x16x32_bf16 v[0:3], v[136:139], v[152:155], v[0:3]
	s_mov_b32 s24, 0x200
	s_mov_b32 s25, 0
	s_add_u32 m0, s30, 0x18000
	v_lshl_add_u64 v[124:125], v[64:65], 0, s[24:25]
	global_load_lds_dwordx4 v[124:125], off
	v_mfma_f32_16x16x32_bf16 v[4:7], v[136:139], v[156:159], v[4:7]
	s_add_u32 m0, s30, 0x1a000
	v_lshl_add_u64 v[126:127], v[66:67], 0, s[24:25]
	global_load_lds_dwordx4 v[126:127], off
	v_mfma_f32_16x16x32_bf16 v[8:11], v[136:139], v[160:163], v[8:11]
	s_add_u32 m0, s30, 0x1c000
	v_lshl_add_u64 v[124:125], v[68:69], 0, s[24:25]
	global_load_lds_dwordx4 v[124:125], off
	v_mfma_f32_16x16x32_bf16 v[12:15], v[136:139], v[164:167], v[12:15]
	s_add_u32 m0, s30, 0x1e000
	v_lshl_add_u64 v[126:127], v[70:71], 0, s[24:25]
	global_load_lds_dwordx4 v[126:127], off
	v_mfma_f32_16x16x32_bf16 v[16:19], v[140:143], v[152:155], v[16:19]
	s_add_u32 m0, s30, 0x20000
	v_lshl_add_u64 v[124:125], v[72:73], 0, s[24:25]
	global_load_lds_dwordx4 v[124:125], off
	v_mfma_f32_16x16x32_bf16 v[20:23], v[140:143], v[156:159], v[20:23]
	s_add_u32 m0, s30, 0x22000
	v_lshl_add_u64 v[126:127], v[74:75], 0, s[24:25]
	global_load_lds_dwordx4 v[126:127], off
	v_mfma_f32_16x16x32_bf16 v[24:27], v[140:143], v[160:163], v[24:27]
	v_mfma_f32_16x16x32_bf16 v[28:31], v[140:143], v[164:167], v[28:31]
	v_mfma_f32_16x16x32_bf16 v[32:35], v[144:147], v[152:155], v[32:35]
	v_mfma_f32_16x16x32_bf16 v[36:39], v[144:147], v[156:159], v[36:39]
	v_mfma_f32_16x16x32_bf16 v[40:43], v[144:147], v[160:163], v[40:43]
	v_mfma_f32_16x16x32_bf16 v[44:47], v[144:147], v[164:167], v[44:47]
	v_mfma_f32_16x16x32_bf16 v[48:51], v[148:151], v[152:155], v[48:51]
	v_mfma_f32_16x16x32_bf16 v[52:55], v[148:151], v[156:159], v[52:55]
	v_mfma_f32_16x16x32_bf16 v[56:59], v[148:151], v[160:163], v[56:59]
	v_mfma_f32_16x16x32_bf16 v[60:63], v[148:151], v[164:167], v[60:63]
	ds_read_b128 v[136:139], v77
	ds_read_b128 v[140:143], v77 offset:2048
	ds_read_b128 v[144:147], v77 offset:4096
	ds_read_b128 v[148:151], v77 offset:6144
	ds_read_b128 v[152:155], v79
	ds_read_b128 v[156:159], v79 offset:2048
	ds_read_b128 v[160:163], v79 offset:4096
	ds_read_b128 v[164:167], v79 offset:6144
	s_waitcnt lgkmcnt(8)
;     ...
;   for (int kt = 0; kt < nk; ++kt) {
;     if (kt + 1 < nk) asm volatile("s_waitcnt vmcnt(6)" ::: "memory");
;     else asm volatile("s_waitcnt vmcnt(0)" ::: "memory");
;     __builtin_amdgcn_s_barrier();
;     asm volatile("" ::: "memory");
;     if (kt + 2 < nk) { const int st2 = (st >= 1) ? st - 1 : 2; GEMM_ISSUE(kt + 2, st2); }
;     const char* la = lds + st * STAGE_B;
;     const char* lb = la + 32768;
;     const unsigned sa_u = (unsigned)(size_t)la + arow_u, sb_u = (unsigned)(size_t)lb + brow_u;
;     const unsigned a0 = sa_u + co0, a1 = sa_u + co1, a2 = sa_u + co2, a3 = sa_u + co3;
;     const unsigned b0 = sb_u + co0, b1 = sb_u + co1, b2 = sb_u + co2, b3 = sb_u + co3;
;     {
;       bf16x8 p0, p1, q0, q1, u0, u1, w0, w1;
;       asm volatile(
;         "ds_read_b128 %4, %12\n\tds_read_b128 %5, %12 offset:4096\n\tds_read_b128 %6, %16\n\tds_read_b128 %7, %16 offset:4096\n\t"
;         "ds_read_b128 %8, %13\n\tds_read_b128 %9, %13 offset:4096\n\tds_read_b128 %10, %17\n\tds_read_b128 %11, %17 offset:4096\n\t"
;         "s_waitcnt lgkmcnt(4)\n\t"
;         "v_mfma_f32_32x32x16_bf16 %0, %4, %6, %0\n\tv_mfma_f32_32x32x16_bf16 %1, %4, %7, %1\n\tv_mfma_f32_32x32x16_bf16 %2, %5, %6, %2\n\tv_mfma_f32_32x32x16_bf16 %3, %5, %7, %3\n\t"
;         "ds_read_b128 %4, %14\n\tds_read_b128 %5, %14 offset:4096\n\tds_read_b128 %6, %18\n\tds_read_b128 %7, %18 offset:4096\n\t"
;         "s_waitcnt lgkmcnt(4)\n\t"
;         "v_mfma_f32_32x32x16_bf16 %0, %8, %10, %0\n\tv_mfma_f32_32x32x16_bf16 %1, %8, %11, %1\n\tv_mfma_f32_32x32x16_bf16 %2, %9, %10, %2\n\tv_mfma_f32_32x32x16_bf16 %3, %9, %11, %3\n\t"
;         "ds_read_b128 %8, %15\n\tds_read_b128 %9, %15 offset:4096\n\tds_read_b128 %10, %19\n\tds_read_b128 %11, %19 offset:4096\n\t"
;         "s_waitcnt lgkmcnt(4)\n\t"
;         "v_mfma_f32_32x32x16_bf16 %0, %4, %6, %0\n\tv_mfma_f32_32x32x16_bf16 %1, %4, %7, %1\n\tv_mfma_f32_32x32x16_bf16 %2, %5, %6, %2\n\tv_mfma_f32_32x32x16_bf16 %3, %5, %7, %3\n\t"
;         "s_waitcnt lgkmcnt(0)\n\t"
;         "v_mfma_f32_32x32x16_bf16 %0, %8, %10, %0\n\tv_mfma_f32_32x32x16_bf16 %1, %8, %11, %1\n\tv_mfma_f32_32x32x16_bf16 %2, %9, %10, %2\n\tv_mfma_f32_32x32x16_bf16 %3, %9, %11, %3"
;         : "+v"(acc[0][0]), "+v"(acc[0][1]), "+v"(acc[1][0]), "+v"(acc[1][1]),
;           "=&v"(p0), "=&v"(p1), "=&v"(q0), "=&v"(q1), "=&v"(u0), "=&v"(u1), "=&v"(w0), "=&v"(w1)
	v_mfma_f32_16x16x32_bf16 v[0:3], v[84:87], v[100:103], v[0:3]
	v_mfma_f32_16x16x32_bf16 v[4:7], v[84:87], v[104:107], v[4:7]
	v_mfma_f32_16x16x32_bf16 v[8:11], v[84:87], v[108:111], v[8:11]
	v_mfma_f32_16x16x32_bf16 v[12:15], v[84:87], v[112:115], v[12:15]
	v_mfma_f32_16x16x32_bf16 v[16:19], v[88:91], v[100:103], v[16:19]
	v_mfma_f32_16x16x32_bf16 v[20:23], v[88:91], v[104:107], v[20:23]
	v_mfma_f32_16x16x32_bf16 v[24:27], v[88:91], v[108:111], v[24:27]
	v_mfma_f32_16x16x32_bf16 v[28:31], v[88:91], v[112:115], v[28:31]
	v_mfma_f32_16x16x32_bf16 v[32:35], v[92:95], v[100:103], v[32:35]
	v_mfma_f32_16x16x32_bf16 v[36:39], v[92:95], v[104:107], v[36:39]
	v_mfma_f32_16x16x32_bf16 v[40:43], v[92:95], v[108:111], v[40:43]
	v_mfma_f32_16x16x32_bf16 v[44:47], v[92:95], v[112:115], v[44:47]
	v_mfma_f32_16x16x32_bf16 v[48:51], v[96:99], v[100:103], v[48:51]
	v_mfma_f32_16x16x32_bf16 v[52:55], v[96:99], v[104:107], v[52:55]
	v_mfma_f32_16x16x32_bf16 v[56:59], v[96:99], v[108:111], v[56:59]
	v_mfma_f32_16x16x32_bf16 v[60:63], v[96:99], v[112:115], v[60:63]
	s_waitcnt vmcnt(6) lgkmcnt(0)
	s_barrier
	ds_read_b128 v[84:87], v76 offset:49152
	ds_read_b128 v[88:91], v76 offset:51200
	ds_read_b128 v[92:95], v76 offset:53248
	ds_read_b128 v[96:99], v76 offset:55296
	ds_read_b128 v[100:103], v78 offset:49152
	ds_read_b128 v[104:107], v78 offset:51200
	ds_read_b128 v[108:111], v78 offset:53248
	ds_read_b128 v[112:115], v78 offset:55296
	v_mfma_f32_16x16x32_bf16 v[0:3], v[136:139], v[152:155], v[0:3]
	s_mov_b32 s24, 0x280
	s_mov_b32 s25, 0
	s_mov_b32 m0, s30
	v_lshl_add_u64 v[124:125], v[64:65], 0, s[24:25]
	global_load_lds_dwordx4 v[124:125], off
	v_mfma_f32_16x16x32_bf16 v[4:7], v[136:139], v[156:159], v[4:7]
	s_add_u32 m0, s30, 0x2000
	v_lshl_add_u64 v[126:127], v[66:67], 0, s[24:25]
	global_load_lds_dwordx4 v[126:127], off
	v_mfma_f32_16x16x32_bf16 v[8:11], v[136:139], v[160:163], v[8:11]
	s_add_u32 m0, s30, 0x4000
	v_lshl_add_u64 v[124:125], v[68:69], 0, s[24:25]
	global_load_lds_dwordx4 v[124:125], off
	v_mfma_f32_16x16x32_bf16 v[12:15], v[136:139], v[164:167], v[12:15]
	s_add_u32 m0, s30, 0x6000
	v_lshl_add_u64 v[126:127], v[70:71], 0, s[24:25]
	global_load_lds_dwordx4 v[126:127], off
	v_mfma_f32_16x16x32_bf16 v[16:19], v[140:143], v[152:155], v[16:19]
	s_add_u32 m0, s30, 0x8000
	v_lshl_add_u64 v[124:125], v[72:73], 0, s[24:25]
	global_load_lds_dwordx4 v[124:125], off
	v_mfma_f32_16x16x32_bf16 v[20:23], v[140:143], v[156:159], v[20:23]
	s_add_u32 m0, s30, 0xa000
	v_lshl_add_u64 v[126:127], v[74:75], 0, s[24:25]
	global_load_lds_dwordx4 v[126:127], off
	v_mfma_f32_16x16x32_bf16 v[24:27], v[140:143], v[160:163], v[24:27]
	v_mfma_f32_16x16x32_bf16 v[28:31], v[140:143], v[164:167], v[28:31]
	v_mfma_f32_16x16x32_bf16 v[32:35], v[144:147], v[152:155], v[32:35]
	v_mfma_f32_16x16x32_bf16 v[36:39], v[144:147], v[156:159], v[36:39]
	v_mfma_f32_16x16x32_bf16 v[40:43], v[144:147], v[160:163], v[40:43]
	v_mfma_f32_16x16x32_bf16 v[44:47], v[144:147], v[164:167], v[44:47]
	v_mfma_f32_16x16x32_bf16 v[48:51], v[148:151], v[152:155], v[48:51]
	v_mfma_f32_16x16x32_bf16 v[52:55], v[148:151], v[156:159], v[52:55]
	v_mfma_f32_16x16x32_bf16 v[56:59], v[148:151], v[160:163], v[56:59]
	v_mfma_f32_16x16x32_bf16 v[60:63], v[148:151], v[164:167], v[60:63]
	ds_read_b128 v[136:139], v77 offset:49152
	ds_read_b128 v[140:143], v77 offset:51200
	ds_read_b128 v[144:147], v77 offset:53248
	ds_read_b128 v[148:151], v77 offset:55296
	ds_read_b128 v[152:155], v79 offset:49152
	ds_read_b128 v[156:159], v79 offset:51200
	ds_read_b128 v[160:163], v79 offset:53248
	ds_read_b128 v[164:167], v79 offset:55296
	s_waitcnt lgkmcnt(8)
	v_mfma_f32_16x16x32_bf16 v[0:3], v[84:87], v[100:103], v[0:3]
	v_mfma_f32_16x16x32_bf16 v[4:7], v[84:87], v[104:107], v[4:7]
	v_mfma_f32_16x16x32_bf16 v[8:11], v[84:87], v[108:111], v[8:11]
	v_mfma_f32_16x16x32_bf16 v[12:15], v[84:87], v[112:115], v[12:15]
	v_mfma_f32_16x16x32_bf16 v[16:19], v[88:91], v[100:103], v[16:19]
	v_mfma_f32_16x16x32_bf16 v[20:23], v[88:91], v[104:107], v[20:23]
	v_mfma_f32_16x16x32_bf16 v[24:27], v[88:91], v[108:111], v[24:27]
	v_mfma_f32_16x16x32_bf16 v[28:31], v[88:91], v[112:115], v[28:31]
	v_mfma_f32_16x16x32_bf16 v[32:35], v[92:95], v[100:103], v[32:35]
	v_mfma_f32_16x16x32_bf16 v[36:39], v[92:95], v[104:107], v[36:39]
	v_mfma_f32_16x16x32_bf16 v[40:43], v[92:95], v[108:111], v[40:43]
	v_mfma_f32_16x16x32_bf16 v[44:47], v[92:95], v[112:115], v[44:47]
	v_mfma_f32_16x16x32_bf16 v[48:51], v[96:99], v[100:103], v[48:51]
	v_mfma_f32_16x16x32_bf16 v[52:55], v[96:99], v[104:107], v[52:55]
	v_mfma_f32_16x16x32_bf16 v[56:59], v[96:99], v[108:111], v[56:59]
	v_mfma_f32_16x16x32_bf16 v[60:63], v[96:99], v[112:115], v[60:63]
	s_waitcnt vmcnt(6) lgkmcnt(0)
	s_barrier
;     ...
;   for (int kt = 0; kt < nk; ++kt) {
;     if (kt + 1 < nk) asm volatile("s_waitcnt vmcnt(6)" ::: "memory");
;     else asm volatile("s_waitcnt vmcnt(0)" ::: "memory");
;     __builtin_amdgcn_s_barrier();
;     asm volatile("" ::: "memory");
;     if (kt + 2 < nk) { const int st2 = (st >= 1) ? st - 1 : 2; GEMM_ISSUE(kt + 2, st2); }
;     const char* la = lds + st * STAGE_B;
;     const char* lb = la + 32768;
;     const unsigned sa_u = (unsigned)(size_t)la + arow_u, sb_u = (unsigned)(size_t)lb + brow_u;
;     const unsigned a0 = sa_u + co0, a1 = sa_u + co1, a2 = sa_u + co2, a3 = sa_u + co3;
;     const unsigned b0 = sb_u + co0, b1 = sb_u + co1, b2 = sb_u + co2, b3 = sb_u + co3;
;     {
;       bf16x8 p0, p1, q0, q1, u0, u1, w0, w1;
;       asm volatile(
;         "ds_read_b128 %4, %12\n\tds_read_b128 %5, %12 offset:4096\n\tds_read_b128 %6, %16\n\tds_read_b128 %7, %16 offset:4096\n\t"
;         "ds_read_b128 %8, %13\n\tds_read_b128 %9, %13 offset:4096\n\tds_read_b128 %10, %17\n\tds_read_b128 %11, %17 offset:4096\n\t"
;         "s_waitcnt lgkmcnt(4)\n\t"
;         "v_mfma_f32_32x32x16_bf16 %0, %4, %6, %0\n\tv_mfma_f32_32x32x16_bf16 %1, %4, %7, %1\n\tv_mfma_f32_32x32x16_bf16 %2, %5, %6, %2\n\tv_mfma_f32_32x32x16_bf16 %3, %5, %7, %3\n\t"
;         "ds_read_b128 %4, %14\n\tds_read_b128 %5, %14 offset:4096\n\tds_read_b128 %6, %18\n\tds_read_b128 %7, %18 offset:4096\n\t"
;         "s_waitcnt lgkmcnt(4)\n\t"
;         "v_mfma_f32_32x32x16_bf16 %0, %8, %10, %0\n\tv_mfma_f32_32x32x16_bf16 %1, %8, %11, %1\n\tv_mfma_f32_32x32x16_bf16 %2, %9, %10, %2\n\tv_mfma_f32_32x32x16_bf16 %3, %9, %11, %3\n\t"
;         "ds_read_b128 %8, %15\n\tds_read_b128 %9, %15 offset:4096\n\tds_read_b128 %10, %19\n\tds_read_b128 %11, %19 offset:4096\n\t"
;         "s_waitcnt lgkmcnt(4)\n\t"
;         "v_mfma_f32_32x32x16_bf16 %0, %4, %6, %0\n\tv_mfma_f32_32x32x16_bf16 %1, %4, %7, %1\n\tv_mfma_f32_32x32x16_bf16 %2, %5, %6, %2\n\tv_mfma_f32_32x32x16_bf16 %3, %5, %7, %3\n\t"
;         "s_waitcnt lgkmcnt(0)\n\t"
;         "v_mfma_f32_32x32x16_bf16 %0, %8, %10, %0\n\tv_mfma_f32_32x32x16_bf16 %1, %8, %11, %1\n\tv_mfma_f32_32x32x16_bf16 %2, %9, %10, %2\n\tv_mfma_f32_32x32x16_bf16 %3, %9, %11, %3"
;         : "+v"(acc[0][0]), "+v"(acc[0][1]), "+v"(acc[1][0]), "+v"(acc[1][1]),
;           "=&v"(p0), "=&v"(p1), "=&v"(q0), "=&v"(q1), "=&v"(u0), "=&v"(u1), "=&v"(w0), "=&v"(w1)
	ds_read_b128 v[84:87], v80
	ds_read_b128 v[88:91], v80 offset:2048
	ds_read_b128 v[92:95], v80 offset:4096
	ds_read_b128 v[96:99], v80 offset:6144
	ds_read_b128 v[100:103], v82
	ds_read_b128 v[104:107], v82 offset:2048
	ds_read_b128 v[108:111], v82 offset:4096
	ds_read_b128 v[112:115], v82 offset:6144
	v_mfma_f32_16x16x32_bf16 v[0:3], v[136:139], v[152:155], v[0:3]
	s_mov_b32 s24, 0x300
	s_mov_b32 s25, 0
	s_add_u32 m0, s30, 0xc000
	v_lshl_add_u64 v[124:125], v[64:65], 0, s[24:25]
	global_load_lds_dwordx4 v[124:125], off
	v_mfma_f32_16x16x32_bf16 v[4:7], v[136:139], v[156:159], v[4:7]
	s_add_u32 m0, s30, 0xe000
	v_lshl_add_u64 v[126:127], v[66:67], 0, s[24:25]
	global_load_lds_dwordx4 v[126:127], off
	v_mfma_f32_16x16x32_bf16 v[8:11], v[136:139], v[160:163], v[8:11]
	s_add_u32 m0, s30, 0x10000
	v_lshl_add_u64 v[124:125], v[68:69], 0, s[24:25]
	global_load_lds_dwordx4 v[124:125], off
	v_mfma_f32_16x16x32_bf16 v[12:15], v[136:139], v[164:167], v[12:15]
	s_add_u32 m0, s30, 0x12000
	v_lshl_add_u64 v[126:127], v[70:71], 0, s[24:25]
	global_load_lds_dwordx4 v[126:127], off
	v_mfma_f32_16x16x32_bf16 v[16:19], v[140:143], v[152:155], v[16:19]
	s_add_u32 m0, s30, 0x14000
	v_lshl_add_u64 v[124:125], v[72:73], 0, s[24:25]
	global_load_lds_dwordx4 v[124:125], off
	v_mfma_f32_16x16x32_bf16 v[20:23], v[140:143], v[156:159], v[20:23]
	s_add_u32 m0, s30, 0x16000
	v_lshl_add_u64 v[126:127], v[74:75], 0, s[24:25]
	global_load_lds_dwordx4 v[126:127], off
	v_mfma_f32_16x16x32_bf16 v[24:27], v[140:143], v[160:163], v[24:27]
	v_mfma_f32_16x16x32_bf16 v[28:31], v[140:143], v[164:167], v[28:31]
	v_mfma_f32_16x16x32_bf16 v[32:35], v[144:147], v[152:155], v[32:35]
	v_mfma_f32_16x16x32_bf16 v[36:39], v[144:147], v[156:159], v[36:39]
	v_mfma_f32_16x16x32_bf16 v[40:43], v[144:147], v[160:163], v[40:43]
	v_mfma_f32_16x16x32_bf16 v[44:47], v[144:147], v[164:167], v[44:47]
	v_mfma_f32_16x16x32_bf16 v[48:51], v[148:151], v[152:155], v[48:51]
	v_mfma_f32_16x16x32_bf16 v[52:55], v[148:151], v[156:159], v[52:55]
	v_mfma_f32_16x16x32_bf16 v[56:59], v[148:151], v[160:163], v[56:59]
	v_mfma_f32_16x16x32_bf16 v[60:63], v[148:151], v[164:167], v[60:63]
	ds_read_b128 v[136:139], v81
	ds_read_b128 v[140:143], v81 offset:2048
	ds_read_b128 v[144:147], v81 offset:4096
	ds_read_b128 v[148:151], v81 offset:6144
	ds_read_b128 v[152:155], v83
	ds_read_b128 v[156:159], v83 offset:2048
	ds_read_b128 v[160:163], v83 offset:4096
	ds_read_b128 v[164:167], v83 offset:6144
	s_waitcnt lgkmcnt(8)
	v_mfma_f32_16x16x32_bf16 v[0:3], v[84:87], v[100:103], v[0:3]
	v_mfma_f32_16x16x32_bf16 v[4:7], v[84:87], v[104:107], v[4:7]
	v_mfma_f32_16x16x32_bf16 v[8:11], v[84:87], v[108:111], v[8:11]
	v_mfma_f32_16x16x32_bf16 v[12:15], v[84:87], v[112:115], v[12:15]
	v_mfma_f32_16x16x32_bf16 v[16:19], v[88:91], v[100:103], v[16:19]
	v_mfma_f32_16x16x32_bf16 v[20:23], v[88:91], v[104:107], v[20:23]
	v_mfma_f32_16x16x32_bf16 v[24:27], v[88:91], v[108:111], v[24:27]
	v_mfma_f32_16x16x32_bf16 v[28:31], v[88:91], v[112:115], v[28:31]
	v_mfma_f32_16x16x32_bf16 v[32:35], v[92:95], v[100:103], v[32:35]
	v_mfma_f32_16x16x32_bf16 v[36:39], v[92:95], v[104:107], v[36:39]
	v_mfma_f32_16x16x32_bf16 v[40:43], v[92:95], v[108:111], v[40:43]
	v_mfma_f32_16x16x32_bf16 v[44:47], v[92:95], v[112:115], v[44:47]
	v_mfma_f32_16x16x32_bf16 v[48:51], v[96:99], v[100:103], v[48:51]
	v_mfma_f32_16x16x32_bf16 v[52:55], v[96:99], v[104:107], v[52:55]
	v_mfma_f32_16x16x32_bf16 v[56:59], v[96:99], v[108:111], v[56:59]
	v_mfma_f32_16x16x32_bf16 v[60:63], v[96:99], v[112:115], v[60:63]
	s_waitcnt vmcnt(6) lgkmcnt(0)
	s_barrier
	ds_read_b128 v[84:87], v76
	ds_read_b128 v[88:91], v76 offset:2048
	ds_read_b128 v[92:95], v76 offset:4096
	ds_read_b128 v[96:99], v76 offset:6144
	ds_read_b128 v[100:103], v78
	ds_read_b128 v[104:107], v78 offset:2048
	ds_read_b128 v[108:111], v78 offset:4096
	ds_read_b128 v[112:115], v78 offset:6144
	v_mfma_f32_16x16x32_bf16 v[0:3], v[136:139], v[152:155], v[0:3]
	s_mov_b32 s24, 0x380
	s_mov_b32 s25, 0
	s_add_u32 m0, s30, 0x18000
	v_lshl_add_u64 v[124:125], v[64:65], 0, s[24:25]
	global_load_lds_dwordx4 v[124:125], off
	v_mfma_f32_16x16x32_bf16 v[4:7], v[136:139], v[156:159], v[4:7]
	s_add_u32 m0, s30, 0x1a000
	v_lshl_add_u64 v[126:127], v[66:67], 0, s[24:25]
	global_load_lds_dwordx4 v[126:127], off
	v_mfma_f32_16x16x32_bf16 v[8:11], v[136:139], v[160:163], v[8:11]
	s_add_u32 m0, s30, 0x1c000
	v_lshl_add_u64 v[124:125], v[68:69], 0, s[24:25]
	global_load_lds_dwordx4 v[124:125], off
	v_mfma_f32_16x16x32_bf16 v[12:15], v[136:139], v[164:167], v[12:15]
	s_add_u32 m0, s30, 0x1e000
	v_lshl_add_u64 v[126:127], v[70:71], 0, s[24:25]
	global_load_lds_dwordx4 v[126:127], off
	v_mfma_f32_16x16x32_bf16 v[16:19], v[140:143], v[152:155], v[16:19]
	s_add_u32 m0, s30, 0x20000
	v_lshl_add_u64 v[124:125], v[72:73], 0, s[24:25]
	global_load_lds_dwordx4 v[124:125], off
	v_mfma_f32_16x16x32_bf16 v[20:23], v[140:143], v[156:159], v[20:23]
	s_add_u32 m0, s30, 0x22000
	v_lshl_add_u64 v[126:127], v[74:75], 0, s[24:25]
	global_load_lds_dwordx4 v[126:127], off
	v_mfma_f32_16x16x32_bf16 v[24:27], v[140:143], v[160:163], v[24:27]
	v_mfma_f32_16x16x32_bf16 v[28:31], v[140:143], v[164:167], v[28:31]
	v_mfma_f32_16x16x32_bf16 v[32:35], v[144:147], v[152:155], v[32:35]
	v_mfma_f32_16x16x32_bf16 v[36:39], v[144:147], v[156:159], v[36:39]
	v_mfma_f32_16x16x32_bf16 v[40:43], v[144:147], v[160:163], v[40:43]
	v_mfma_f32_16x16x32_bf16 v[44:47], v[144:147], v[164:167], v[44:47]
	v_mfma_f32_16x16x32_bf16 v[48:51], v[148:151], v[152:155], v[48:51]
	v_mfma_f32_16x16x32_bf16 v[52:55], v[148:151], v[156:159], v[52:55]
	v_mfma_f32_16x16x32_bf16 v[56:59], v[148:151], v[160:163], v[56:59]
	v_mfma_f32_16x16x32_bf16 v[60:63], v[148:151], v[164:167], v[60:63]
	ds_read_b128 v[136:139], v77
	ds_read_b128 v[140:143], v77 offset:2048
	ds_read_b128 v[144:147], v77 offset:4096
	ds_read_b128 v[148:151], v77 offset:6144
	ds_read_b128 v[152:155], v79
	ds_read_b128 v[156:159], v79 offset:2048
	ds_read_b128 v[160:163], v79 offset:4096
	ds_read_b128 v[164:167], v79 offset:6144
	s_waitcnt lgkmcnt(8)
;     ...
;   for (int kt = 0; kt < nk; ++kt) {
;     if (kt + 1 < nk) asm volatile("s_waitcnt vmcnt(6)" ::: "memory");
;     else asm volatile("s_waitcnt vmcnt(0)" ::: "memory");
;     __builtin_amdgcn_s_barrier();
;     asm volatile("" ::: "memory");
;     if (kt + 2 < nk) { const int st2 = (st >= 1) ? st - 1 : 2; GEMM_ISSUE(kt + 2, st2); }
;     const char* la = lds + st * STAGE_B;
;     const char* lb = la + 32768;
;     const unsigned sa_u = (unsigned)(size_t)la + arow_u, sb_u = (unsigned)(size_t)lb + brow_u;
;     const unsigned a0 = sa_u + co0, a1 = sa_u + co1, a2 = sa_u + co2, a3 = sa_u + co3;
;     const unsigned b0 = sb_u + co0, b1 = sb_u + co1, b2 = sb_u + co2, b3 = sb_u + co3;
;     {
;       bf16x8 p0, p1, q0, q1, u0, u1, w0, w1;
;       asm volatile(
;         "ds_read_b128 %4, %12\n\tds_read_b128 %5, %12 offset:4096\n\tds_read_b128 %6, %16\n\tds_read_b128 %7, %16 offset:4096\n\t"
;         "ds_read_b128 %8, %13\n\tds_read_b128 %9, %13 offset:4096\n\tds_read_b128 %10, %17\n\tds_read_b128 %11, %17 offset:4096\n\t"
;         "s_waitcnt lgkmcnt(4)\n\t"
;         "v_mfma_f32_32x32x16_bf16 %0, %4, %6, %0\n\tv_mfma_f32_32x32x16_bf16 %1, %4, %7, %1\n\tv_mfma_f32_32x32x16_bf16 %2, %5, %6, %2\n\tv_mfma_f32_32x32x16_bf16 %3, %5, %7, %3\n\t"
;         "ds_read_b128 %4, %14\n\tds_read_b128 %5, %14 offset:4096\n\tds_read_b128 %6, %18\n\tds_read_b128 %7, %18 offset:4096\n\t"
;         "s_waitcnt lgkmcnt(4)\n\t"
;         "v_mfma_f32_32x32x16_bf16 %0, %8, %10, %0\n\tv_mfma_f32_32x32x16_bf16 %1, %8, %11, %1\n\tv_mfma_f32_32x32x16_bf16 %2, %9, %10, %2\n\tv_mfma_f32_32x32x16_bf16 %3, %9, %11, %3\n\t"
;         "ds_read_b128 %8, %15\n\tds_read_b128 %9, %15 offset:4096\n\tds_read_b128 %10, %19\n\tds_read_b128 %11, %19 offset:4096\n\t"
;         "s_waitcnt lgkmcnt(4)\n\t"
;         "v_mfma_f32_32x32x16_bf16 %0, %4, %6, %0\n\tv_mfma_f32_32x32x16_bf16 %1, %4, %7, %1\n\tv_mfma_f32_32x32x16_bf16 %2, %5, %6, %2\n\tv_mfma_f32_32x32x16_bf16 %3, %5, %7, %3\n\t"
;         "s_waitcnt lgkmcnt(0)\n\t"
;         "v_mfma_f32_32x32x16_bf16 %0, %8, %10, %0\n\tv_mfma_f32_32x32x16_bf16 %1, %8, %11, %1\n\tv_mfma_f32_32x32x16_bf16 %2, %9, %10, %2\n\tv_mfma_f32_32x32x16_bf16 %3, %9, %11, %3"
;         : "+v"(acc[0][0]), "+v"(acc[0][1]), "+v"(acc[1][0]), "+v"(acc[1][1]),
;           "=&v"(p0), "=&v"(p1), "=&v"(q0), "=&v"(q1), "=&v"(u0), "=&v"(u1), "=&v"(w0), "=&v"(w1)
	v_mfma_f32_16x16x32_bf16 v[0:3], v[84:87], v[100:103], v[0:3]
	v_mfma_f32_16x16x32_bf16 v[4:7], v[84:87], v[104:107], v[4:7]
	v_mfma_f32_16x16x32_bf16 v[8:11], v[84:87], v[108:111], v[8:11]
	v_mfma_f32_16x16x32_bf16 v[12:15], v[84:87], v[112:115], v[12:15]
	v_mfma_f32_16x16x32_bf16 v[16:19], v[88:91], v[100:103], v[16:19]
	v_mfma_f32_16x16x32_bf16 v[20:23], v[88:91], v[104:107], v[20:23]
	v_mfma_f32_16x16x32_bf16 v[24:27], v[88:91], v[108:111], v[24:27]
	v_mfma_f32_16x16x32_bf16 v[28:31], v[88:91], v[112:115], v[28:31]
	v_mfma_f32_16x16x32_bf16 v[32:35], v[92:95], v[100:103], v[32:35]
	v_mfma_f32_16x16x32_bf16 v[36:39], v[92:95], v[104:107], v[36:39]
	v_mfma_f32_16x16x32_bf16 v[40:43], v[92:95], v[108:111], v[40:43]
	v_mfma_f32_16x16x32_bf16 v[44:47], v[92:95], v[112:115], v[44:47]
	v_mfma_f32_16x16x32_bf16 v[48:51], v[96:99], v[100:103], v[48:51]
	v_mfma_f32_16x16x32_bf16 v[52:55], v[96:99], v[104:107], v[52:55]
	v_mfma_f32_16x16x32_bf16 v[56:59], v[96:99], v[108:111], v[56:59]
	v_mfma_f32_16x16x32_bf16 v[60:63], v[96:99], v[112:115], v[60:63]
	s_waitcnt vmcnt(6) lgkmcnt(0)
	s_barrier
	ds_read_b128 v[84:87], v76 offset:49152
	ds_read_b128 v[88:91], v76 offset:51200
	ds_read_b128 v[92:95], v76 offset:53248
	ds_read_b128 v[96:99], v76 offset:55296
	ds_read_b128 v[100:103], v78 offset:49152
	ds_read_b128 v[104:107], v78 offset:51200
	ds_read_b128 v[108:111], v78 offset:53248
	ds_read_b128 v[112:115], v78 offset:55296
	v_mfma_f32_16x16x32_bf16 v[0:3], v[136:139], v[152:155], v[0:3]
	s_mov_b32 s24, 0x400
	s_mov_b32 s25, 0
	s_mov_b32 m0, s30
	v_lshl_add_u64 v[124:125], v[64:65], 0, s[24:25]
	global_load_lds_dwordx4 v[124:125], off
	v_mfma_f32_16x16x32_bf16 v[4:7], v[136:139], v[156:159], v[4:7]
	s_add_u32 m0, s30, 0x2000
	v_lshl_add_u64 v[126:127], v[66:67], 0, s[24:25]
	global_load_lds_dwordx4 v[126:127], off
	v_mfma_f32_16x16x32_bf16 v[8:11], v[136:139], v[160:163], v[8:11]
	s_add_u32 m0, s30, 0x4000
	v_lshl_add_u64 v[124:125], v[68:69], 0, s[24:25]
	global_load_lds_dwordx4 v[124:125], off
	v_mfma_f32_16x16x32_bf16 v[12:15], v[136:139], v[164:167], v[12:15]
	s_add_u32 m0, s30, 0x6000
	v_lshl_add_u64 v[126:127], v[70:71], 0, s[24:25]
	global_load_lds_dwordx4 v[126:127], off
	v_mfma_f32_16x16x32_bf16 v[16:19], v[140:143], v[152:155], v[16:19]
	s_add_u32 m0, s30, 0x8000
	v_lshl_add_u64 v[124:125], v[72:73], 0, s[24:25]
	global_load_lds_dwordx4 v[124:125], off
	v_mfma_f32_16x16x32_bf16 v[20:23], v[140:143], v[156:159], v[20:23]
	s_add_u32 m0, s30, 0xa000
	v_lshl_add_u64 v[126:127], v[74:75], 0, s[24:25]
	global_load_lds_dwordx4 v[126:127], off
	v_mfma_f32_16x16x32_bf16 v[24:27], v[140:143], v[160:163], v[24:27]
	v_mfma_f32_16x16x32_bf16 v[28:31], v[140:143], v[164:167], v[28:31]
	v_mfma_f32_16x16x32_bf16 v[32:35], v[144:147], v[152:155], v[32:35]
	v_mfma_f32_16x16x32_bf16 v[36:39], v[144:147], v[156:159], v[36:39]
	v_mfma_f32_16x16x32_bf16 v[40:43], v[144:147], v[160:163], v[40:43]
	v_mfma_f32_16x16x32_bf16 v[44:47], v[144:147], v[164:167], v[44:47]
	v_mfma_f32_16x16x32_bf16 v[48:51], v[148:151], v[152:155], v[48:51]
	v_mfma_f32_16x16x32_bf16 v[52:55], v[148:151], v[156:159], v[52:55]
	v_mfma_f32_16x16x32_bf16 v[56:59], v[148:151], v[160:163], v[56:59]
	v_mfma_f32_16x16x32_bf16 v[60:63], v[148:151], v[164:167], v[60:63]
	ds_read_b128 v[136:139], v77 offset:49152
	ds_read_b128 v[140:143], v77 offset:51200
	ds_read_b128 v[144:147], v77 offset:53248
	ds_read_b128 v[148:151], v77 offset:55296
	ds_read_b128 v[152:155], v79 offset:49152
	ds_read_b128 v[156:159], v79 offset:51200
	ds_read_b128 v[160:163], v79 offset:53248
	ds_read_b128 v[164:167], v79 offset:55296
	s_waitcnt lgkmcnt(8)
	v_mfma_f32_16x16x32_bf16 v[0:3], v[84:87], v[100:103], v[0:3]
	v_mfma_f32_16x16x32_bf16 v[4:7], v[84:87], v[104:107], v[4:7]
	v_mfma_f32_16x16x32_bf16 v[8:11], v[84:87], v[108:111], v[8:11]
	v_mfma_f32_16x16x32_bf16 v[12:15], v[84:87], v[112:115], v[12:15]
	v_mfma_f32_16x16x32_bf16 v[16:19], v[88:91], v[100:103], v[16:19]
	v_mfma_f32_16x16x32_bf16 v[20:23], v[88:91], v[104:107], v[20:23]
	v_mfma_f32_16x16x32_bf16 v[24:27], v[88:91], v[108:111], v[24:27]
	v_mfma_f32_16x16x32_bf16 v[28:31], v[88:91], v[112:115], v[28:31]
	v_mfma_f32_16x16x32_bf16 v[32:35], v[92:95], v[100:103], v[32:35]
	v_mfma_f32_16x16x32_bf16 v[36:39], v[92:95], v[104:107], v[36:39]
	v_mfma_f32_16x16x32_bf16 v[40:43], v[92:95], v[108:111], v[40:43]
	v_mfma_f32_16x16x32_bf16 v[44:47], v[92:95], v[112:115], v[44:47]
	v_mfma_f32_16x16x32_bf16 v[48:51], v[96:99], v[100:103], v[48:51]
	v_mfma_f32_16x16x32_bf16 v[52:55], v[96:99], v[104:107], v[52:55]
	v_mfma_f32_16x16x32_bf16 v[56:59], v[96:99], v[108:111], v[56:59]
	v_mfma_f32_16x16x32_bf16 v[60:63], v[96:99], v[112:115], v[60:63]
	s_waitcnt vmcnt(6) lgkmcnt(0)
	s_barrier
;     ...
;   if (PART != 2) {
;     GEMM_ISSUE(0, 0);
;     if (nk > 1) GEMM_ISSUE(1, 1);
;   }
;   if (PART == 1) return;
;   int st = 0;
;   for (int kt = 0; kt < nk; ++kt) {
;     if (kt + 1 < nk) asm volatile("s_waitcnt vmcnt(6)" ::: "memory");
;     else asm volatile("s_waitcnt vmcnt(0)" ::: "memory");
;     __builtin_amdgcn_s_barrier();
;     asm volatile("" ::: "memory");
;     if (kt + 2 < nk) { const int st2 = (st >= 1) ? st - 1 : 2; GEMM_ISSUE(kt + 2, st2); }
;     const char* la = lds + st * STAGE_B;
;     const char* lb = la + 32768;
;     const unsigned sa_u = (unsigned)(size_t)la + arow_u, sb_u = (unsigned)(size_t)lb + brow_u;
;     const unsigned a0 = sa_u + co0, a1 = sa_u + co1, a2 = sa_u + co2, a3 = sa_u + co3;
;     const unsigned b0 = sb_u + co0, b1 = sb_u + co1, b2 = sb_u + co2, b3 = sb_u + co3;
;     {
;       bf16x8 p0, p1, q0, q1, u0, u1, w0, w1;
;       asm volatile(
;         "ds_read_b128 %4, %12\n\tds_read_b128 %5, %12 offset:4096\n\tds_read_b128 %6, %16\n\tds_read_b128 %7, %16 offset:4096\n\t"
;         "ds_read_b128 %8, %13\n\tds_read_b128 %9, %13 offset:4096\n\tds_read_b128 %10, %17\n\tds_read_b128 %11, %17 offset:4096\n\t"
;         "s_waitcnt lgkmcnt(4)\n\t"
;         "v_mfma_f32_32x32x16_bf16 %0, %4, %6, %0\n\tv_mfma_f32_32x32x16_bf16 %1, %4, %7, %1\n\tv_mfma_f32_32x32x16_bf16 %2, %5, %6, %2\n\tv_mfma_f32_32x32x16_bf16 %3, %5, %7, %3\n\t"
;         "ds_read_b128 %4, %14\n\tds_read_b128 %5, %14 offset:4096\n\tds_read_b128 %6, %18\n\tds_read_b128 %7, %18 offset:4096\n\t"
;         "s_waitcnt lgkmcnt(4)\n\t"
;         "v_mfma_f32_32x32x16_bf16 %0, %8, %10, %0\n\tv_mfma_f32_32x32x16_bf16 %1, %8, %11, %1\n\tv_mfma_f32_32x32x16_bf16 %2, %9, %10, %2\n\tv_mfma_f32_32x32x16_bf16 %3, %9, %11, %3\n\t"
;         "ds_read_b128 %8, %15\n\tds_read_b128 %9, %15 offset:4096\n\tds_read_b128 %10, %19\n\tds_read_b128 %11, %19 offset:4096\n\t"
;         "s_waitcnt lgkmcnt(4)\n\t"
;         "v_mfma_f32_32x32x16_bf16 %0, %4, %6, %0\n\tv_mfma_f32_32x32x16_bf16 %1, %4, %7, %1\n\tv_mfma_f32_32x32x16_bf16 %2, %5, %6, %2\n\tv_mfma_f32_32x32x16_bf16 %3, %5, %7, %3\n\t"
;         "s_waitcnt lgkmcnt(0)\n\t"
;         "v_mfma_f32_32x32x16_bf16 %0, %8, %10, %0\n\tv_mfma_f32_32x32x16_bf16 %1, %8, %11, %1\n\tv_mfma_f32_32x32x16_bf16 %2, %9, %10, %2\n\tv_mfma_f32_32x32x16_bf16 %3, %9, %11, %3"
	ds_read_b128 v[84:87], v80
	ds_read_b128 v[88:91], v80 offset:2048
	ds_read_b128 v[92:95], v80 offset:4096
	ds_read_b128 v[96:99], v80 offset:6144
	ds_read_b128 v[100:103], v82
	ds_read_b128 v[104:107], v82 offset:2048
	ds_read_b128 v[108:111], v82 offset:4096
	ds_read_b128 v[112:115], v82 offset:6144
	v_mfma_f32_16x16x32_bf16 v[0:3], v[136:139], v[152:155], v[0:3]
	s_mov_b32 s24, 0x480
	s_mov_b32 s25, 0
	s_add_u32 m0, s30, 0xc000
	v_lshl_add_u64 v[124:125], v[64:65], 0, s[24:25]
	global_load_lds_dwordx4 v[124:125], off
	v_mfma_f32_16x16x32_bf16 v[4:7], v[136:139], v[156:159], v[4:7]
	s_add_u32 m0, s30, 0xe000
	v_lshl_add_u64 v[126:127], v[66:67], 0, s[24:25]
	global_load_lds_dwordx4 v[126:127], off
	v_mfma_f32_16x16x32_bf16 v[8:11], v[136:139], v[160:163], v[8:11]
	s_add_u32 m0, s30, 0x10000
	v_lshl_add_u64 v[124:125], v[68:69], 0, s[24:25]
	global_load_lds_dwordx4 v[124:125], off
	v_mfma_f32_16x16x32_bf16 v[12:15], v[136:139], v[164:167], v[12:15]
	s_add_u32 m0, s30, 0x12000
	v_lshl_add_u64 v[126:127], v[70:71], 0, s[24:25]
	global_load_lds_dwordx4 v[126:127], off
	v_mfma_f32_16x16x32_bf16 v[16:19], v[140:143], v[152:155], v[16:19]
	s_add_u32 m0, s30, 0x14000
	v_lshl_add_u64 v[124:125], v[72:73], 0, s[24:25]
	global_load_lds_dwordx4 v[124:125], off
	v_mfma_f32_16x16x32_bf16 v[20:23], v[140:143], v[156:159], v[20:23]
	s_add_u32 m0, s30, 0x16000
	v_lshl_add_u64 v[126:127], v[74:75], 0, s[24:25]
	global_load_lds_dwordx4 v[126:127], off
	v_mfma_f32_16x16x32_bf16 v[24:27], v[140:143], v[160:163], v[24:27]
	v_mfma_f32_16x16x32_bf16 v[28:31], v[140:143], v[164:167], v[28:31]
	v_mfma_f32_16x16x32_bf16 v[32:35], v[144:147], v[152:155], v[32:35]
	v_mfma_f32_16x16x32_bf16 v[36:39], v[144:147], v[156:159], v[36:39]
	v_mfma_f32_16x16x32_bf16 v[40:43], v[144:147], v[160:163], v[40:43]
	v_mfma_f32_16x16x32_bf16 v[44:47], v[144:147], v[164:167], v[44:47]
	v_mfma_f32_16x16x32_bf16 v[48:51], v[148:151], v[152:155], v[48:51]
	v_mfma_f32_16x16x32_bf16 v[52:55], v[148:151], v[156:159], v[52:55]
	v_mfma_f32_16x16x32_bf16 v[56:59], v[148:151], v[160:163], v[56:59]
	v_mfma_f32_16x16x32_bf16 v[60:63], v[148:151], v[164:167], v[60:63]
	ds_read_b128 v[136:139], v81
	ds_read_b128 v[140:143], v81 offset:2048
	ds_read_b128 v[144:147], v81 offset:4096
	ds_read_b128 v[148:151], v81 offset:6144
	ds_read_b128 v[152:155], v83
	ds_read_b128 v[156:159], v83 offset:2048
	ds_read_b128 v[160:163], v83 offset:4096
	ds_read_b128 v[164:167], v83 offset:6144
	s_waitcnt lgkmcnt(8)
	v_mfma_f32_16x16x32_bf16 v[0:3], v[84:87], v[100:103], v[0:3]
	v_mfma_f32_16x16x32_bf16 v[4:7], v[84:87], v[104:107], v[4:7]
	v_mfma_f32_16x16x32_bf16 v[8:11], v[84:87], v[108:111], v[8:11]
	v_mfma_f32_16x16x32_bf16 v[12:15], v[84:87], v[112:115], v[12:15]
	v_mfma_f32_16x16x32_bf16 v[16:19], v[88:91], v[100:103], v[16:19]
	v_mfma_f32_16x16x32_bf16 v[20:23], v[88:91], v[104:107], v[20:23]
	v_mfma_f32_16x16x32_bf16 v[24:27], v[88:91], v[108:111], v[24:27]
	v_mfma_f32_16x16x32_bf16 v[28:31], v[88:91], v[112:115], v[28:31]
	v_mfma_f32_16x16x32_bf16 v[32:35], v[92:95], v[100:103], v[32:35]
	v_mfma_f32_16x16x32_bf16 v[36:39], v[92:95], v[104:107], v[36:39]
	v_mfma_f32_16x16x32_bf16 v[40:43], v[92:95], v[108:111], v[40:43]
	v_mfma_f32_16x16x32_bf16 v[44:47], v[92:95], v[112:115], v[44:47]
	v_mfma_f32_16x16x32_bf16 v[48:51], v[96:99], v[100:103], v[48:51]
	v_mfma_f32_16x16x32_bf16 v[52:55], v[96:99], v[104:107], v[52:55]
	v_mfma_f32_16x16x32_bf16 v[56:59], v[96:99], v[108:111], v[56:59]
	v_mfma_f32_16x16x32_bf16 v[60:63], v[96:99], v[112:115], v[60:63]
	s_waitcnt vmcnt(6) lgkmcnt(0)
	s_barrier
	ds_read_b128 v[84:87], v76
	ds_read_b128 v[88:91], v76 offset:2048
	ds_read_b128 v[92:95], v76 offset:4096
	ds_read_b128 v[96:99], v76 offset:6144
	ds_read_b128 v[100:103], v78
	ds_read_b128 v[104:107], v78 offset:2048
	ds_read_b128 v[108:111], v78 offset:4096
	ds_read_b128 v[112:115], v78 offset:6144
	v_mfma_f32_16x16x32_bf16 v[0:3], v[136:139], v[152:155], v[0:3]
	s_mov_b32 s24, 0x500
	s_mov_b32 s25, 0
	s_add_u32 m0, s30, 0x18000
	v_lshl_add_u64 v[124:125], v[64:65], 0, s[24:25]
	global_load_lds_dwordx4 v[124:125], off
	v_mfma_f32_16x16x32_bf16 v[4:7], v[136:139], v[156:159], v[4:7]
	s_add_u32 m0, s30, 0x1a000
	v_lshl_add_u64 v[126:127], v[66:67], 0, s[24:25]
	global_load_lds_dwordx4 v[126:127], off
	v_mfma_f32_16x16x32_bf16 v[8:11], v[136:139], v[160:163], v[8:11]
	s_add_u32 m0, s30, 0x1c000
	v_lshl_add_u64 v[124:125], v[68:69], 0, s[24:25]
	global_load_lds_dwordx4 v[124:125], off
	v_mfma_f32_16x16x32_bf16 v[12:15], v[136:139], v[164:167], v[12:15]
	s_add_u32 m0, s30, 0x1e000
	v_lshl_add_u64 v[126:127], v[70:71], 0, s[24:25]
	global_load_lds_dwordx4 v[126:127], off
	v_mfma_f32_16x16x32_bf16 v[16:19], v[140:143], v[152:155], v[16:19]
	s_add_u32 m0, s30, 0x20000
	v_lshl_add_u64 v[124:125], v[72:73], 0, s[24:25]
	global_load_lds_dwordx4 v[124:125], off
	v_mfma_f32_16x16x32_bf16 v[20:23], v[140:143], v[156:159], v[20:23]
	s_add_u32 m0, s30, 0x22000
	v_lshl_add_u64 v[126:127], v[74:75], 0, s[24:25]
	global_load_lds_dwordx4 v[126:127], off
	v_mfma_f32_16x16x32_bf16 v[24:27], v[140:143], v[160:163], v[24:27]
	v_mfma_f32_16x16x32_bf16 v[28:31], v[140:143], v[164:167], v[28:31]
	v_mfma_f32_16x16x32_bf16 v[32:35], v[144:147], v[152:155], v[32:35]
	v_mfma_f32_16x16x32_bf16 v[36:39], v[144:147], v[156:159], v[36:39]
	v_mfma_f32_16x16x32_bf16 v[40:43], v[144:147], v[160:163], v[40:43]
	v_mfma_f32_16x16x32_bf16 v[44:47], v[144:147], v[164:167], v[44:47]
	v_mfma_f32_16x16x32_bf16 v[48:51], v[148:151], v[152:155], v[48:51]
	v_mfma_f32_16x16x32_bf16 v[52:55], v[148:151], v[156:159], v[52:55]
	v_mfma_f32_16x16x32_bf16 v[56:59], v[148:151], v[160:163], v[56:59]
	v_mfma_f32_16x16x32_bf16 v[60:63], v[148:151], v[164:167], v[60:63]
	ds_read_b128 v[136:139], v77
	ds_read_b128 v[140:143], v77 offset:2048
	ds_read_b128 v[144:147], v77 offset:4096
	ds_read_b128 v[148:151], v77 offset:6144
	ds_read_b128 v[152:155], v79
	ds_read_b128 v[156:159], v79 offset:2048
	ds_read_b128 v[160:163], v79 offset:4096
	ds_read_b128 v[164:167], v79 offset:6144
	s_waitcnt lgkmcnt(8)
;     ...
;   if (PART != 2) {
;     GEMM_ISSUE(0, 0);
;     if (nk > 1) GEMM_ISSUE(1, 1);
;   }
;   if (PART == 1) return;
;   int st = 0;
;   for (int kt = 0; kt < nk; ++kt) {
;     if (kt + 1 < nk) asm volatile("s_waitcnt vmcnt(6)" ::: "memory");
;     else asm volatile("s_waitcnt vmcnt(0)" ::: "memory");
;     __builtin_amdgcn_s_barrier();
;     asm volatile("" ::: "memory");
;     if (kt + 2 < nk) { const int st2 = (st >= 1) ? st - 1 : 2; GEMM_ISSUE(kt + 2, st2); }
;     const char* la = lds + st * STAGE_B;
;     const char* lb = la + 32768;
;     const unsigned sa_u = (unsigned)(size_t)la + arow_u, sb_u = (unsigned)(size_t)lb + brow_u;
;     const unsigned a0 = sa_u + co0, a1 = sa_u + co1, a2 = sa_u + co2, a3 = sa_u + co3;
;     const unsigned b0 = sb_u + co0, b1 = sb_u + co1, b2 = sb_u + co2, b3 = sb_u + co3;
;     {
;       bf16x8 p0, p1, q0, q1, u0, u1, w0, w1;
;       asm volatile(
;         "ds_read_b128 %4, %12\n\tds_read_b128 %5, %12 offset:4096\n\tds_read_b128 %6, %16\n\tds_read_b128 %7, %16 offset:4096\n\t"
;         "ds_read_b128 %8, %13\n\tds_read_b128 %9, %13 offset:4096\n\tds_read_b128 %10, %17\n\tds_read_b128 %11, %17 offset:4096\n\t"
;         "s_waitcnt lgkmcnt(4)\n\t"
;         "v_mfma_f32_32x32x16_bf16 %0, %4, %6, %0\n\tv_mfma_f32_32x32x16_bf16 %1, %4, %7, %1\n\tv_mfma_f32_32x32x16_bf16 %2, %5, %6, %2\n\tv_mfma_f32_32x32x16_bf16 %3, %5, %7, %3\n\t"
;         "ds_read_b128 %4, %14\n\tds_read_b128 %5, %14 offset:4096\n\tds_read_b128 %6, %18\n\tds_read_b128 %7, %18 offset:4096\n\t"
;         "s_waitcnt lgkmcnt(4)\n\t"
;         "v_mfma_f32_32x32x16_bf16 %0, %8, %10, %0\n\tv_mfma_f32_32x32x16_bf16 %1, %8, %11, %1\n\tv_mfma_f32_32x32x16_bf16 %2, %9, %10, %2\n\tv_mfma_f32_32x32x16_bf16 %3, %9, %11, %3\n\t"
;         "ds_read_b128 %8, %15\n\tds_read_b128 %9, %15 offset:4096\n\tds_read_b128 %10, %19\n\tds_read_b128 %11, %19 offset:4096\n\t"
;         "s_waitcnt lgkmcnt(4)\n\t"
;         "v_mfma_f32_32x32x16_bf16 %0, %4, %6, %0\n\tv_mfma_f32_32x32x16_bf16 %1, %4, %7, %1\n\tv_mfma_f32_32x32x16_bf16 %2, %5, %6, %2\n\tv_mfma_f32_32x32x16_bf16 %3, %5, %7, %3\n\t"
;         "s_waitcnt lgkmcnt(0)\n\t"
;         "v_mfma_f32_32x32x16_bf16 %0, %8, %10, %0\n\tv_mfma_f32_32x32x16_bf16 %1, %8, %11, %1\n\tv_mfma_f32_32x32x16_bf16 %2, %9, %10, %2\n\tv_mfma_f32_32x32x16_bf16 %3, %9, %11, %3"
	v_mfma_f32_16x16x32_bf16 v[0:3], v[84:87], v[100:103], v[0:3]
	v_mfma_f32_16x16x32_bf16 v[4:7], v[84:87], v[104:107], v[4:7]
	v_mfma_f32_16x16x32_bf16 v[8:11], v[84:87], v[108:111], v[8:11]
	v_mfma_f32_16x16x32_bf16 v[12:15], v[84:87], v[112:115], v[12:15]
	v_mfma_f32_16x16x32_bf16 v[16:19], v[88:91], v[100:103], v[16:19]
	v_mfma_f32_16x16x32_bf16 v[20:23], v[88:91], v[104:107], v[20:23]
	v_mfma_f32_16x16x32_bf16 v[24:27], v[88:91], v[108:111], v[24:27]
	v_mfma_f32_16x16x32_bf16 v[28:31], v[88:91], v[112:115], v[28:31]
	v_mfma_f32_16x16x32_bf16 v[32:35], v[92:95], v[100:103], v[32:35]
	v_mfma_f32_16x16x32_bf16 v[36:39], v[92:95], v[104:107], v[36:39]
	v_mfma_f32_16x16x32_bf16 v[40:43], v[92:95], v[108:111], v[40:43]
	v_mfma_f32_16x16x32_bf16 v[44:47], v[92:95], v[112:115], v[44:47]
	v_mfma_f32_16x16x32_bf16 v[48:51], v[96:99], v[100:103], v[48:51]
	v_mfma_f32_16x16x32_bf16 v[52:55], v[96:99], v[104:107], v[52:55]
	v_mfma_f32_16x16x32_bf16 v[56:59], v[96:99], v[108:111], v[56:59]
	v_mfma_f32_16x16x32_bf16 v[60:63], v[96:99], v[112:115], v[60:63]
	s_waitcnt vmcnt(6) lgkmcnt(0)
	s_barrier
	ds_read_b128 v[84:87], v76 offset:49152
	ds_read_b128 v[88:91], v76 offset:51200
	ds_read_b128 v[92:95], v76 offset:53248
	ds_read_b128 v[96:99], v76 offset:55296
	ds_read_b128 v[100:103], v78 offset:49152
	ds_read_b128 v[104:107], v78 offset:51200
	ds_read_b128 v[108:111], v78 offset:53248
	ds_read_b128 v[112:115], v78 offset:55296
	v_mfma_f32_16x16x32_bf16 v[0:3], v[136:139], v[152:155], v[0:3]
	s_mov_b32 s24, 0x580
	s_mov_b32 s25, 0
	s_mov_b32 m0, s30
	v_lshl_add_u64 v[124:125], v[64:65], 0, s[24:25]
	global_load_lds_dwordx4 v[124:125], off
	v_mfma_f32_16x16x32_bf16 v[4:7], v[136:139], v[156:159], v[4:7]
	s_add_u32 m0, s30, 0x2000
	v_lshl_add_u64 v[126:127], v[66:67], 0, s[24:25]
	global_load_lds_dwordx4 v[126:127], off
	v_mfma_f32_16x16x32_bf16 v[8:11], v[136:139], v[160:163], v[8:11]
	s_add_u32 m0, s30, 0x4000
	v_lshl_add_u64 v[124:125], v[68:69], 0, s[24:25]
	global_load_lds_dwordx4 v[124:125], off
	v_mfma_f32_16x16x32_bf16 v[12:15], v[136:139], v[164:167], v[12:15]
	s_add_u32 m0, s30, 0x6000
	v_lshl_add_u64 v[126:127], v[70:71], 0, s[24:25]
	global_load_lds_dwordx4 v[126:127], off
	v_mfma_f32_16x16x32_bf16 v[16:19], v[140:143], v[152:155], v[16:19]
	s_add_u32 m0, s30, 0x8000
	v_lshl_add_u64 v[124:125], v[72:73], 0, s[24:25]
	global_load_lds_dwordx4 v[124:125], off
	v_mfma_f32_16x16x32_bf16 v[20:23], v[140:143], v[156:159], v[20:23]
	s_add_u32 m0, s30, 0xa000
	v_lshl_add_u64 v[126:127], v[74:75], 0, s[24:25]
	global_load_lds_dwordx4 v[126:127], off
	v_mfma_f32_16x16x32_bf16 v[24:27], v[140:143], v[160:163], v[24:27]
	v_mfma_f32_16x16x32_bf16 v[28:31], v[140:143], v[164:167], v[28:31]
	v_mfma_f32_16x16x32_bf16 v[32:35], v[144:147], v[152:155], v[32:35]
	v_mfma_f32_16x16x32_bf16 v[36:39], v[144:147], v[156:159], v[36:39]
	v_mfma_f32_16x16x32_bf16 v[40:43], v[144:147], v[160:163], v[40:43]
	v_mfma_f32_16x16x32_bf16 v[44:47], v[144:147], v[164:167], v[44:47]
	v_mfma_f32_16x16x32_bf16 v[48:51], v[148:151], v[152:155], v[48:51]
	v_mfma_f32_16x16x32_bf16 v[52:55], v[148:151], v[156:159], v[52:55]
	v_mfma_f32_16x16x32_bf16 v[56:59], v[148:151], v[160:163], v[56:59]
	v_mfma_f32_16x16x32_bf16 v[60:63], v[148:151], v[164:167], v[60:63]
	ds_read_b128 v[136:139], v77 offset:49152
	ds_read_b128 v[140:143], v77 offset:51200
	ds_read_b128 v[144:147], v77 offset:53248
	ds_read_b128 v[148:151], v77 offset:55296
	ds_read_b128 v[152:155], v79 offset:49152
	ds_read_b128 v[156:159], v79 offset:51200
	ds_read_b128 v[160:163], v79 offset:53248
	ds_read_b128 v[164:167], v79 offset:55296
	s_waitcnt lgkmcnt(8)
	v_mfma_f32_16x16x32_bf16 v[0:3], v[84:87], v[100:103], v[0:3]
	v_mfma_f32_16x16x32_bf16 v[4:7], v[84:87], v[104:107], v[4:7]
	v_mfma_f32_16x16x32_bf16 v[8:11], v[84:87], v[108:111], v[8:11]
	v_mfma_f32_16x16x32_bf16 v[12:15], v[84:87], v[112:115], v[12:15]
	v_mfma_f32_16x16x32_bf16 v[16:19], v[88:91], v[100:103], v[16:19]
	v_mfma_f32_16x16x32_bf16 v[20:23], v[88:91], v[104:107], v[20:23]
	v_mfma_f32_16x16x32_bf16 v[24:27], v[88:91], v[108:111], v[24:27]
	v_mfma_f32_16x16x32_bf16 v[28:31], v[88:91], v[112:115], v[28:31]
	v_mfma_f32_16x16x32_bf16 v[32:35], v[92:95], v[100:103], v[32:35]
	v_mfma_f32_16x16x32_bf16 v[36:39], v[92:95], v[104:107], v[36:39]
	v_mfma_f32_16x16x32_bf16 v[40:43], v[92:95], v[108:111], v[40:43]
	v_mfma_f32_16x16x32_bf16 v[44:47], v[92:95], v[112:115], v[44:47]
	v_mfma_f32_16x16x32_bf16 v[48:51], v[96:99], v[100:103], v[48:51]
	v_mfma_f32_16x16x32_bf16 v[52:55], v[96:99], v[104:107], v[52:55]
	v_mfma_f32_16x16x32_bf16 v[56:59], v[96:99], v[108:111], v[56:59]
	v_mfma_f32_16x16x32_bf16 v[60:63], v[96:99], v[112:115], v[60:63]
	s_waitcnt vmcnt(6) lgkmcnt(0)
	s_barrier
;     ...
;   if (PART != 2) {
;     GEMM_ISSUE(0, 0);
;     if (nk > 1) GEMM_ISSUE(1, 1);
;   }
;   if (PART == 1) return;
;   int st = 0;
;   for (int kt = 0; kt < nk; ++kt) {
;     if (kt + 1 < nk) asm volatile("s_waitcnt vmcnt(6)" ::: "memory");
;     else asm volatile("s_waitcnt vmcnt(0)" ::: "memory");
;     __builtin_amdgcn_s_barrier();
;     asm volatile("" ::: "memory");
;     if (kt + 2 < nk) { const int st2 = (st >= 1) ? st - 1 : 2; GEMM_ISSUE(kt + 2, st2); }
;     const char* la = lds + st * STAGE_B;
;     const char* lb = la + 32768;
;     const unsigned sa_u = (unsigned)(size_t)la + arow_u, sb_u = (unsigned)(size_t)lb + brow_u;
;     const unsigned a0 = sa_u + co0, a1 = sa_u + co1, a2 = sa_u + co2, a3 = sa_u + co3;
;     const unsigned b0 = sb_u + co0, b1 = sb_u + co1, b2 = sb_u + co2, b3 = sb_u + co3;
;     {
;       bf16x8 p0, p1, q0, q1, u0, u1, w0, w1;
;       asm volatile(
;         "ds_read_b128 %4, %12\n\tds_read_b128 %5, %12 offset:4096\n\tds_read_b128 %6, %16\n\tds_read_b128 %7, %16 offset:4096\n\t"
;         "ds_read_b128 %8, %13\n\tds_read_b128 %9, %13 offset:4096\n\tds_read_b128 %10, %17\n\tds_read_b128 %11, %17 offset:4096\n\t"
;         "s_waitcnt lgkmcnt(4)\n\t"
;         "v_mfma_f32_32x32x16_bf16 %0, %4, %6, %0\n\tv_mfma_f32_32x32x16_bf16 %1, %4, %7, %1\n\tv_mfma_f32_32x32x16_bf16 %2, %5, %6, %2\n\tv_mfma_f32_32x32x16_bf16 %3, %5, %7, %3\n\t"
;         "ds_read_b128 %4, %14\n\tds_read_b128 %5, %14 offset:4096\n\tds_read_b128 %6, %18\n\tds_read_b128 %7, %18 offset:4096\n\t"
;         "s_waitcnt lgkmcnt(4)\n\t"
;         "v_mfma_f32_32x32x16_bf16 %0, %8, %10, %0\n\tv_mfma_f32_32x32x16_bf16 %1, %8, %11, %1\n\tv_mfma_f32_32x32x16_bf16 %2, %9, %10, %2\n\tv_mfma_f32_32x32x16_bf16 %3, %9, %11, %3\n\t"
;         "ds_read_b128 %8, %15\n\tds_read_b128 %9, %15 offset:4096\n\tds_read_b128 %10, %19\n\tds_read_b128 %11, %19 offset:4096\n\t"
;         "s_waitcnt lgkmcnt(4)\n\t"
;         "v_mfma_f32_32x32x16_bf16 %0, %4, %6, %0\n\tv_mfma_f32_32x32x16_bf16 %1, %4, %7, %1\n\tv_mfma_f32_32x32x16_bf16 %2, %5, %6, %2\n\tv_mfma_f32_32x32x16_bf16 %3, %5, %7, %3\n\t"
;         "s_waitcnt lgkmcnt(0)\n\t"
;         "v_mfma_f32_32x32x16_bf16 %0, %8, %10, %0\n\tv_mfma_f32_32x32x16_bf16 %1, %8, %11, %1\n\tv_mfma_f32_32x32x16_bf16 %2, %9, %10, %2\n\tv_mfma_f32_32x32x16_bf16 %3, %9, %11, %3"
	ds_read_b128 v[84:87], v80
	ds_read_b128 v[88:91], v80 offset:2048
	ds_read_b128 v[92:95], v80 offset:4096
	ds_read_b128 v[96:99], v80 offset:6144
	ds_read_b128 v[100:103], v82
	ds_read_b128 v[104:107], v82 offset:2048
	ds_read_b128 v[108:111], v82 offset:4096
	ds_read_b128 v[112:115], v82 offset:6144
	v_mfma_f32_16x16x32_bf16 v[0:3], v[136:139], v[152:155], v[0:3]
	s_mov_b32 s24, 0x600
	s_mov_b32 s25, 0
	s_add_u32 m0, s30, 0xc000
	v_lshl_add_u64 v[124:125], v[64:65], 0, s[24:25]
	global_load_lds_dwordx4 v[124:125], off
	v_mfma_f32_16x16x32_bf16 v[4:7], v[136:139], v[156:159], v[4:7]
	s_add_u32 m0, s30, 0xe000
	v_lshl_add_u64 v[126:127], v[66:67], 0, s[24:25]
	global_load_lds_dwordx4 v[126:127], off
	v_mfma_f32_16x16x32_bf16 v[8:11], v[136:139], v[160:163], v[8:11]
	s_add_u32 m0, s30, 0x10000
	v_lshl_add_u64 v[124:125], v[68:69], 0, s[24:25]
	global_load_lds_dwordx4 v[124:125], off
	v_mfma_f32_16x16x32_bf16 v[12:15], v[136:139], v[164:167], v[12:15]
	s_add_u32 m0, s30, 0x12000
	v_lshl_add_u64 v[126:127], v[70:71], 0, s[24:25]
	global_load_lds_dwordx4 v[126:127], off
	v_mfma_f32_16x16x32_bf16 v[16:19], v[140:143], v[152:155], v[16:19]
	s_add_u32 m0, s30, 0x14000
	v_lshl_add_u64 v[124:125], v[72:73], 0, s[24:25]
	global_load_lds_dwordx4 v[124:125], off
	v_mfma_f32_16x16x32_bf16 v[20:23], v[140:143], v[156:159], v[20:23]
	s_add_u32 m0, s30, 0x16000
	v_lshl_add_u64 v[126:127], v[74:75], 0, s[24:25]
	global_load_lds_dwordx4 v[126:127], off
	v_mfma_f32_16x16x32_bf16 v[24:27], v[140:143], v[160:163], v[24:27]
	v_mfma_f32_16x16x32_bf16 v[28:31], v[140:143], v[164:167], v[28:31]
	v_mfma_f32_16x16x32_bf16 v[32:35], v[144:147], v[152:155], v[32:35]
	v_mfma_f32_16x16x32_bf16 v[36:39], v[144:147], v[156:159], v[36:39]
	v_mfma_f32_16x16x32_bf16 v[40:43], v[144:147], v[160:163], v[40:43]
	v_mfma_f32_16x16x32_bf16 v[44:47], v[144:147], v[164:167], v[44:47]
	v_mfma_f32_16x16x32_bf16 v[48:51], v[148:151], v[152:155], v[48:51]
	v_mfma_f32_16x16x32_bf16 v[52:55], v[148:151], v[156:159], v[52:55]
	v_mfma_f32_16x16x32_bf16 v[56:59], v[148:151], v[160:163], v[56:59]
	v_mfma_f32_16x16x32_bf16 v[60:63], v[148:151], v[164:167], v[60:63]
	ds_read_b128 v[136:139], v81
	ds_read_b128 v[140:143], v81 offset:2048
	ds_read_b128 v[144:147], v81 offset:4096
	ds_read_b128 v[148:151], v81 offset:6144
	ds_read_b128 v[152:155], v83
	ds_read_b128 v[156:159], v83 offset:2048
	ds_read_b128 v[160:163], v83 offset:4096
	ds_read_b128 v[164:167], v83 offset:6144
	s_waitcnt lgkmcnt(8)
	v_mfma_f32_16x16x32_bf16 v[0:3], v[84:87], v[100:103], v[0:3]
	v_mfma_f32_16x16x32_bf16 v[4:7], v[84:87], v[104:107], v[4:7]
	v_mfma_f32_16x16x32_bf16 v[8:11], v[84:87], v[108:111], v[8:11]
	v_mfma_f32_16x16x32_bf16 v[12:15], v[84:87], v[112:115], v[12:15]
	v_mfma_f32_16x16x32_bf16 v[16:19], v[88:91], v[100:103], v[16:19]
	v_mfma_f32_16x16x32_bf16 v[20:23], v[88:91], v[104:107], v[20:23]
	v_mfma_f32_16x16x32_bf16 v[24:27], v[88:91], v[108:111], v[24:27]
	v_mfma_f32_16x16x32_bf16 v[28:31], v[88:91], v[112:115], v[28:31]
	v_mfma_f32_16x16x32_bf16 v[32:35], v[92:95], v[100:103], v[32:35]
	v_mfma_f32_16x16x32_bf16 v[36:39], v[92:95], v[104:107], v[36:39]
	v_mfma_f32_16x16x32_bf16 v[40:43], v[92:95], v[108:111], v[40:43]
	v_mfma_f32_16x16x32_bf16 v[44:47], v[92:95], v[112:115], v[44:47]
	v_mfma_f32_16x16x32_bf16 v[48:51], v[96:99], v[100:103], v[48:51]
	v_mfma_f32_16x16x32_bf16 v[52:55], v[96:99], v[104:107], v[52:55]
	v_mfma_f32_16x16x32_bf16 v[56:59], v[96:99], v[108:111], v[56:59]
	v_mfma_f32_16x16x32_bf16 v[60:63], v[96:99], v[112:115], v[60:63]
	s_waitcnt vmcnt(6) lgkmcnt(0)
	s_barrier
	ds_read_b128 v[84:87], v76
	ds_read_b128 v[88:91], v76 offset:2048
	ds_read_b128 v[92:95], v76 offset:4096
	ds_read_b128 v[96:99], v76 offset:6144
	ds_read_b128 v[100:103], v78
	ds_read_b128 v[104:107], v78 offset:2048
	ds_read_b128 v[108:111], v78 offset:4096
	ds_read_b128 v[112:115], v78 offset:6144
	v_mfma_f32_16x16x32_bf16 v[0:3], v[136:139], v[152:155], v[0:3]
	s_mov_b32 s24, 0x680
	s_mov_b32 s25, 0
	s_add_u32 m0, s30, 0x18000
	v_lshl_add_u64 v[124:125], v[64:65], 0, s[24:25]
	global_load_lds_dwordx4 v[124:125], off
	v_mfma_f32_16x16x32_bf16 v[4:7], v[136:139], v[156:159], v[4:7]
	s_add_u32 m0, s30, 0x1a000
	v_lshl_add_u64 v[126:127], v[66:67], 0, s[24:25]
	global_load_lds_dwordx4 v[126:127], off
	v_mfma_f32_16x16x32_bf16 v[8:11], v[136:139], v[160:163], v[8:11]
	s_add_u32 m0, s30, 0x1c000
	v_lshl_add_u64 v[124:125], v[68:69], 0, s[24:25]
	global_load_lds_dwordx4 v[124:125], off
	v_mfma_f32_16x16x32_bf16 v[12:15], v[136:139], v[164:167], v[12:15]
	s_add_u32 m0, s30, 0x1e000
	v_lshl_add_u64 v[126:127], v[70:71], 0, s[24:25]
	global_load_lds_dwordx4 v[126:127], off
	v_mfma_f32_16x16x32_bf16 v[16:19], v[140:143], v[152:155], v[16:19]
	s_add_u32 m0, s30, 0x20000
	v_lshl_add_u64 v[124:125], v[72:73], 0, s[24:25]
	global_load_lds_dwordx4 v[124:125], off
	v_mfma_f32_16x16x32_bf16 v[20:23], v[140:143], v[156:159], v[20:23]
	s_add_u32 m0, s30, 0x22000
	v_lshl_add_u64 v[126:127], v[74:75], 0, s[24:25]
	global_load_lds_dwordx4 v[126:127], off
	v_mfma_f32_16x16x32_bf16 v[24:27], v[140:143], v[160:163], v[24:27]
	v_mfma_f32_16x16x32_bf16 v[28:31], v[140:143], v[164:167], v[28:31]
	v_mfma_f32_16x16x32_bf16 v[32:35], v[144:147], v[152:155], v[32:35]
	v_mfma_f32_16x16x32_bf16 v[36:39], v[144:147], v[156:159], v[36:39]
	v_mfma_f32_16x16x32_bf16 v[40:43], v[144:147], v[160:163], v[40:43]
	v_mfma_f32_16x16x32_bf16 v[44:47], v[144:147], v[164:167], v[44:47]
	v_mfma_f32_16x16x32_bf16 v[48:51], v[148:151], v[152:155], v[48:51]
	v_mfma_f32_16x16x32_bf16 v[52:55], v[148:151], v[156:159], v[52:55]
	v_mfma_f32_16x16x32_bf16 v[56:59], v[148:151], v[160:163], v[56:59]
	v_mfma_f32_16x16x32_bf16 v[60:63], v[148:151], v[164:167], v[60:63]
	ds_read_b128 v[136:139], v77
	ds_read_b128 v[140:143], v77 offset:2048
	ds_read_b128 v[144:147], v77 offset:4096
	ds_read_b128 v[148:151], v77 offset:6144
	ds_read_b128 v[152:155], v79
	ds_read_b128 v[156:159], v79 offset:2048
	ds_read_b128 v[160:163], v79 offset:4096
	ds_read_b128 v[164:167], v79 offset:6144
	s_waitcnt lgkmcnt(8)
;     ...
;   if (PART != 2) {
;     GEMM_ISSUE(0, 0);
;     if (nk > 1) GEMM_ISSUE(1, 1);
;   }
;   if (PART == 1) return;
;   int st = 0;
;   for (int kt = 0; kt < nk; ++kt) {
;     if (kt + 1 < nk) asm volatile("s_waitcnt vmcnt(6)" ::: "memory");
;     else asm volatile("s_waitcnt vmcnt(0)" ::: "memory");
;     __builtin_amdgcn_s_barrier();
;     asm volatile("" ::: "memory");
;     if (kt + 2 < nk) { const int st2 = (st >= 1) ? st - 1 : 2; GEMM_ISSUE(kt + 2, st2); }
;     const char* la = lds + st * STAGE_B;
;     const char* lb = la + 32768;
;     const unsigned sa_u = (unsigned)(size_t)la + arow_u, sb_u = (unsigned)(size_t)lb + brow_u;
;     const unsigned a0 = sa_u + co0, a1 = sa_u + co1, a2 = sa_u + co2, a3 = sa_u + co3;
;     const unsigned b0 = sb_u + co0, b1 = sb_u + co1, b2 = sb_u + co2, b3 = sb_u + co3;
;     {
;       bf16x8 p0, p1, q0, q1, u0, u1, w0, w1;
;       asm volatile(
;         "ds_read_b128 %4, %12\n\tds_read_b128 %5, %12 offset:4096\n\tds_read_b128 %6, %16\n\tds_read_b128 %7, %16 offset:4096\n\t"
;         "ds_read_b128 %8, %13\n\tds_read_b128 %9, %13 offset:4096\n\tds_read_b128 %10, %17\n\tds_read_b128 %11, %17 offset:4096\n\t"
;         "s_waitcnt lgkmcnt(4)\n\t"
;         "v_mfma_f32_32x32x16_bf16 %0, %4, %6, %0\n\tv_mfma_f32_32x32x16_bf16 %1, %4, %7, %1\n\tv_mfma_f32_32x32x16_bf16 %2, %5, %6, %2\n\tv_mfma_f32_32x32x16_bf16 %3, %5, %7, %3\n\t"
;         "ds_read_b128 %4, %14\n\tds_read_b128 %5, %14 offset:4096\n\tds_read_b128 %6, %18\n\tds_read_b128 %7, %18 offset:4096\n\t"
;         "s_waitcnt lgkmcnt(4)\n\t"
;         "v_mfma_f32_32x32x16_bf16 %0, %8, %10, %0\n\tv_mfma_f32_32x32x16_bf16 %1, %8, %11, %1\n\tv_mfma_f32_32x32x16_bf16 %2, %9, %10, %2\n\tv_mfma_f32_32x32x16_bf16 %3, %9, %11, %3\n\t"
;         "ds_read_b128 %8, %15\n\tds_read_b128 %9, %15 offset:4096\n\tds_read_b128 %10, %19\n\tds_read_b128 %11, %19 offset:4096\n\t"
;         "s_waitcnt lgkmcnt(4)\n\t"
;         "v_mfma_f32_32x32x16_bf16 %0, %4, %6, %0\n\tv_mfma_f32_32x32x16_bf16 %1, %4, %7, %1\n\tv_mfma_f32_32x32x16_bf16 %2, %5, %6, %2\n\tv_mfma_f32_32x32x16_bf16 %3, %5, %7, %3\n\t"
;         "s_waitcnt lgkmcnt(0)\n\t"
;         "v_mfma_f32_32x32x16_bf16 %0, %8, %10, %0\n\tv_mfma_f32_32x32x16_bf16 %1, %8, %11, %1\n\tv_mfma_f32_32x32x16_bf16 %2, %9, %10, %2\n\tv_mfma_f32_32x32x16_bf16 %3, %9, %11, %3"
	v_mfma_f32_16x16x32_bf16 v[0:3], v[84:87], v[100:103], v[0:3]
	v_mfma_f32_16x16x32_bf16 v[4:7], v[84:87], v[104:107], v[4:7]
	v_mfma_f32_16x16x32_bf16 v[8:11], v[84:87], v[108:111], v[8:11]
	v_mfma_f32_16x16x32_bf16 v[12:15], v[84:87], v[112:115], v[12:15]
	v_mfma_f32_16x16x32_bf16 v[16:19], v[88:91], v[100:103], v[16:19]
	v_mfma_f32_16x16x32_bf16 v[20:23], v[88:91], v[104:107], v[20:23]
	v_mfma_f32_16x16x32_bf16 v[24:27], v[88:91], v[108:111], v[24:27]
	v_mfma_f32_16x16x32_bf16 v[28:31], v[88:91], v[112:115], v[28:31]
	v_mfma_f32_16x16x32_bf16 v[32:35], v[92:95], v[100:103], v[32:35]
	v_mfma_f32_16x16x32_bf16 v[36:39], v[92:95], v[104:107], v[36:39]
	v_mfma_f32_16x16x32_bf16 v[40:43], v[92:95], v[108:111], v[40:43]
	v_mfma_f32_16x16x32_bf16 v[44:47], v[92:95], v[112:115], v[44:47]
	v_mfma_f32_16x16x32_bf16 v[48:51], v[96:99], v[100:103], v[48:51]
	v_mfma_f32_16x16x32_bf16 v[52:55], v[96:99], v[104:107], v[52:55]
	v_mfma_f32_16x16x32_bf16 v[56:59], v[96:99], v[108:111], v[56:59]
	v_mfma_f32_16x16x32_bf16 v[60:63], v[96:99], v[112:115], v[60:63]
	s_waitcnt vmcnt(6) lgkmcnt(0)
	s_barrier
	ds_read_b128 v[84:87], v76 offset:49152
	ds_read_b128 v[88:91], v76 offset:51200
	ds_read_b128 v[92:95], v76 offset:53248
	ds_read_b128 v[96:99], v76 offset:55296
	ds_read_b128 v[100:103], v78 offset:49152
	ds_read_b128 v[104:107], v78 offset:51200
	ds_read_b128 v[108:111], v78 offset:53248
	ds_read_b128 v[112:115], v78 offset:55296
	v_mfma_f32_16x16x32_bf16 v[0:3], v[136:139], v[152:155], v[0:3]
	s_mov_b32 s24, 0x700
	s_mov_b32 s25, 0
	s_mov_b32 m0, s30
	v_lshl_add_u64 v[124:125], v[64:65], 0, s[24:25]
	global_load_lds_dwordx4 v[124:125], off
	v_mfma_f32_16x16x32_bf16 v[4:7], v[136:139], v[156:159], v[4:7]
	s_add_u32 m0, s30, 0x2000
	v_lshl_add_u64 v[126:127], v[66:67], 0, s[24:25]
	global_load_lds_dwordx4 v[126:127], off
	v_mfma_f32_16x16x32_bf16 v[8:11], v[136:139], v[160:163], v[8:11]
	s_add_u32 m0, s30, 0x4000
	v_lshl_add_u64 v[124:125], v[68:69], 0, s[24:25]
	global_load_lds_dwordx4 v[124:125], off
	v_mfma_f32_16x16x32_bf16 v[12:15], v[136:139], v[164:167], v[12:15]
	s_add_u32 m0, s30, 0x6000
	v_lshl_add_u64 v[126:127], v[70:71], 0, s[24:25]
	global_load_lds_dwordx4 v[126:127], off
	v_mfma_f32_16x16x32_bf16 v[16:19], v[140:143], v[152:155], v[16:19]
	s_add_u32 m0, s30, 0x8000
	v_lshl_add_u64 v[124:125], v[72:73], 0, s[24:25]
	global_load_lds_dwordx4 v[124:125], off
	v_mfma_f32_16x16x32_bf16 v[20:23], v[140:143], v[156:159], v[20:23]
	s_add_u32 m0, s30, 0xa000
	v_lshl_add_u64 v[126:127], v[74:75], 0, s[24:25]
	global_load_lds_dwordx4 v[126:127], off
	v_mfma_f32_16x16x32_bf16 v[24:27], v[140:143], v[160:163], v[24:27]
	v_mfma_f32_16x16x32_bf16 v[28:31], v[140:143], v[164:167], v[28:31]
	v_mfma_f32_16x16x32_bf16 v[32:35], v[144:147], v[152:155], v[32:35]
	v_mfma_f32_16x16x32_bf16 v[36:39], v[144:147], v[156:159], v[36:39]
	v_mfma_f32_16x16x32_bf16 v[40:43], v[144:147], v[160:163], v[40:43]
	v_mfma_f32_16x16x32_bf16 v[44:47], v[144:147], v[164:167], v[44:47]
	v_mfma_f32_16x16x32_bf16 v[48:51], v[148:151], v[152:155], v[48:51]
	v_mfma_f32_16x16x32_bf16 v[52:55], v[148:151], v[156:159], v[52:55]
	v_mfma_f32_16x16x32_bf16 v[56:59], v[148:151], v[160:163], v[56:59]
	v_mfma_f32_16x16x32_bf16 v[60:63], v[148:151], v[164:167], v[60:63]
	ds_read_b128 v[136:139], v77 offset:49152
	ds_read_b128 v[140:143], v77 offset:51200
	ds_read_b128 v[144:147], v77 offset:53248
	ds_read_b128 v[148:151], v77 offset:55296
	ds_read_b128 v[152:155], v79 offset:49152
	ds_read_b128 v[156:159], v79 offset:51200
	ds_read_b128 v[160:163], v79 offset:53248
	ds_read_b128 v[164:167], v79 offset:55296
	s_waitcnt lgkmcnt(8)
	v_mfma_f32_16x16x32_bf16 v[0:3], v[84:87], v[100:103], v[0:3]
	v_mfma_f32_16x16x32_bf16 v[4:7], v[84:87], v[104:107], v[4:7]
	v_mfma_f32_16x16x32_bf16 v[8:11], v[84:87], v[108:111], v[8:11]
	v_mfma_f32_16x16x32_bf16 v[12:15], v[84:87], v[112:115], v[12:15]
	v_mfma_f32_16x16x32_bf16 v[16:19], v[88:91], v[100:103], v[16:19]
	v_mfma_f32_16x16x32_bf16 v[20:23], v[88:91], v[104:107], v[20:23]
	v_mfma_f32_16x16x32_bf16 v[24:27], v[88:91], v[108:111], v[24:27]
	v_mfma_f32_16x16x32_bf16 v[28:31], v[88:91], v[112:115], v[28:31]
	v_mfma_f32_16x16x32_bf16 v[32:35], v[92:95], v[100:103], v[32:35]
	v_mfma_f32_16x16x32_bf16 v[36:39], v[92:95], v[104:107], v[36:39]
	v_mfma_f32_16x16x32_bf16 v[40:43], v[92:95], v[108:111], v[40:43]
	v_mfma_f32_16x16x32_bf16 v[44:47], v[92:95], v[112:115], v[44:47]
	v_mfma_f32_16x16x32_bf16 v[48:51], v[96:99], v[100:103], v[48:51]
	v_mfma_f32_16x16x32_bf16 v[52:55], v[96:99], v[104:107], v[52:55]
	v_mfma_f32_16x16x32_bf16 v[56:59], v[96:99], v[108:111], v[56:59]
	v_mfma_f32_16x16x32_bf16 v[60:63], v[96:99], v[112:115], v[60:63]
	s_waitcnt vmcnt(6) lgkmcnt(0)
	s_barrier
;     ...
;   if (PART != 2) {
;     GEMM_ISSUE(0, 0);
;     if (nk > 1) GEMM_ISSUE(1, 1);
;   }
;   if (PART == 1) return;
;   int st = 0;
;   for (int kt = 0; kt < nk; ++kt) {
;     if (kt + 1 < nk) asm volatile("s_waitcnt vmcnt(6)" ::: "memory");
;     else asm volatile("s_waitcnt vmcnt(0)" ::: "memory");
;     __builtin_amdgcn_s_barrier();
;     asm volatile("" ::: "memory");
;     if (kt + 2 < nk) { const int st2 = (st >= 1) ? st - 1 : 2; GEMM_ISSUE(kt + 2, st2); }
;     const char* la = lds + st * STAGE_B;
;     const char* lb = la + 32768;
;     const unsigned sa_u = (unsigned)(size_t)la + arow_u, sb_u = (unsigned)(size_t)lb + brow_u;
;     const unsigned a0 = sa_u + co0, a1 = sa_u + co1, a2 = sa_u + co2, a3 = sa_u + co3;
;     const unsigned b0 = sb_u + co0, b1 = sb_u + co1, b2 = sb_u + co2, b3 = sb_u + co3;
;     {
;       bf16x8 p0, p1, q0, q1, u0, u1, w0, w1;
;       asm volatile(
;         "ds_read_b128 %4, %12\n\tds_read_b128 %5, %12 offset:4096\n\tds_read_b128 %6, %16\n\tds_read_b128 %7, %16 offset:4096\n\t"
;         "ds_read_b128 %8, %13\n\tds_read_b128 %9, %13 offset:4096\n\tds_read_b128 %10, %17\n\tds_read_b128 %11, %17 offset:4096\n\t"
;         "s_waitcnt lgkmcnt(4)\n\t"
;         "v_mfma_f32_32x32x16_bf16 %0, %4, %6, %0\n\tv_mfma_f32_32x32x16_bf16 %1, %4, %7, %1\n\tv_mfma_f32_32x32x16_bf16 %2, %5, %6, %2\n\tv_mfma_f32_32x32x16_bf16 %3, %5, %7, %3\n\t"
;         "ds_read_b128 %4, %14\n\tds_read_b128 %5, %14 offset:4096\n\tds_read_b128 %6, %18\n\tds_read_b128 %7, %18 offset:4096\n\t"
;         "s_waitcnt lgkmcnt(4)\n\t"
;         "v_mfma_f32_32x32x16_bf16 %0, %8, %10, %0\n\tv_mfma_f32_32x32x16_bf16 %1, %8, %11, %1\n\tv_mfma_f32_32x32x16_bf16 %2, %9, %10, %2\n\tv_mfma_f32_32x32x16_bf16 %3, %9, %11, %3\n\t"
;         "ds_read_b128 %8, %15\n\tds_read_b128 %9, %15 offset:4096\n\tds_read_b128 %10, %19\n\tds_read_b128 %11, %19 offset:4096\n\t"
;         "s_waitcnt lgkmcnt(4)\n\t"
;         "v_mfma_f32_32x32x16_bf16 %0, %4, %6, %0\n\tv_mfma_f32_32x32x16_bf16 %1, %4, %7, %1\n\tv_mfma_f32_32x32x16_bf16 %2, %5, %6, %2\n\tv_mfma_f32_32x32x16_bf16 %3, %5, %7, %3\n\t"
;         "s_waitcnt lgkmcnt(0)\n\t"
;         "v_mfma_f32_32x32x16_bf16 %0, %8, %10, %0\n\tv_mfma_f32_32x32x16_bf16 %1, %8, %11, %1\n\tv_mfma_f32_32x32x16_bf16 %2, %9, %10, %2\n\tv_mfma_f32_32x32x16_bf16 %3, %9, %11, %3"
	ds_read_b128 v[84:87], v80
	ds_read_b128 v[88:91], v80 offset:2048
	ds_read_b128 v[92:95], v80 offset:4096
	ds_read_b128 v[96:99], v80 offset:6144
	ds_read_b128 v[100:103], v82
	ds_read_b128 v[104:107], v82 offset:2048
	ds_read_b128 v[108:111], v82 offset:4096
	ds_read_b128 v[112:115], v82 offset:6144
	v_mfma_f32_16x16x32_bf16 v[0:3], v[136:139], v[152:155], v[0:3]
	s_mov_b32 s24, 0x780
	s_mov_b32 s25, 0
	s_add_u32 m0, s30, 0xc000
	v_lshl_add_u64 v[124:125], v[64:65], 0, s[24:25]
	global_load_lds_dwordx4 v[124:125], off
	v_mfma_f32_16x16x32_bf16 v[4:7], v[136:139], v[156:159], v[4:7]
	s_add_u32 m0, s30, 0xe000
	v_lshl_add_u64 v[126:127], v[66:67], 0, s[24:25]
	global_load_lds_dwordx4 v[126:127], off
	v_mfma_f32_16x16x32_bf16 v[8:11], v[136:139], v[160:163], v[8:11]
	s_add_u32 m0, s30, 0x10000
	v_lshl_add_u64 v[124:125], v[68:69], 0, s[24:25]
	global_load_lds_dwordx4 v[124:125], off
	v_mfma_f32_16x16x32_bf16 v[12:15], v[136:139], v[164:167], v[12:15]
	s_add_u32 m0, s30, 0x12000
	v_lshl_add_u64 v[126:127], v[70:71], 0, s[24:25]
	global_load_lds_dwordx4 v[126:127], off
	v_mfma_f32_16x16x32_bf16 v[16:19], v[140:143], v[152:155], v[16:19]
	s_add_u32 m0, s30, 0x14000
	v_lshl_add_u64 v[124:125], v[72:73], 0, s[24:25]
	global_load_lds_dwordx4 v[124:125], off
	v_mfma_f32_16x16x32_bf16 v[20:23], v[140:143], v[156:159], v[20:23]
	s_add_u32 m0, s30, 0x16000
	v_lshl_add_u64 v[126:127], v[74:75], 0, s[24:25]
	global_load_lds_dwordx4 v[126:127], off
	v_mfma_f32_16x16x32_bf16 v[24:27], v[140:143], v[160:163], v[24:27]
	v_mfma_f32_16x16x32_bf16 v[28:31], v[140:143], v[164:167], v[28:31]
	v_mfma_f32_16x16x32_bf16 v[32:35], v[144:147], v[152:155], v[32:35]
	v_mfma_f32_16x16x32_bf16 v[36:39], v[144:147], v[156:159], v[36:39]
	v_mfma_f32_16x16x32_bf16 v[40:43], v[144:147], v[160:163], v[40:43]
	v_mfma_f32_16x16x32_bf16 v[44:47], v[144:147], v[164:167], v[44:47]
	v_mfma_f32_16x16x32_bf16 v[48:51], v[148:151], v[152:155], v[48:51]
	v_mfma_f32_16x16x32_bf16 v[52:55], v[148:151], v[156:159], v[52:55]
	v_mfma_f32_16x16x32_bf16 v[56:59], v[148:151], v[160:163], v[56:59]
	v_mfma_f32_16x16x32_bf16 v[60:63], v[148:151], v[164:167], v[60:63]
	ds_read_b128 v[136:139], v81
	ds_read_b128 v[140:143], v81 offset:2048
	ds_read_b128 v[144:147], v81 offset:4096
	ds_read_b128 v[148:151], v81 offset:6144
	ds_read_b128 v[152:155], v83
	ds_read_b128 v[156:159], v83 offset:2048
	ds_read_b128 v[160:163], v83 offset:4096
	ds_read_b128 v[164:167], v83 offset:6144
	s_waitcnt lgkmcnt(8)
	v_mfma_f32_16x16x32_bf16 v[0:3], v[84:87], v[100:103], v[0:3]
	v_mfma_f32_16x16x32_bf16 v[4:7], v[84:87], v[104:107], v[4:7]
	v_mfma_f32_16x16x32_bf16 v[8:11], v[84:87], v[108:111], v[8:11]
	v_mfma_f32_16x16x32_bf16 v[12:15], v[84:87], v[112:115], v[12:15]
	v_mfma_f32_16x16x32_bf16 v[16:19], v[88:91], v[100:103], v[16:19]
	v_mfma_f32_16x16x32_bf16 v[20:23], v[88:91], v[104:107], v[20:23]
	v_mfma_f32_16x16x32_bf16 v[24:27], v[88:91], v[108:111], v[24:27]
	v_mfma_f32_16x16x32_bf16 v[28:31], v[88:91], v[112:115], v[28:31]
	v_mfma_f32_16x16x32_bf16 v[32:35], v[92:95], v[100:103], v[32:35]
	v_mfma_f32_16x16x32_bf16 v[36:39], v[92:95], v[104:107], v[36:39]
	v_mfma_f32_16x16x32_bf16 v[40:43], v[92:95], v[108:111], v[40:43]
	v_mfma_f32_16x16x32_bf16 v[44:47], v[92:95], v[112:115], v[44:47]
	v_mfma_f32_16x16x32_bf16 v[48:51], v[96:99], v[100:103], v[48:51]
	v_mfma_f32_16x16x32_bf16 v[52:55], v[96:99], v[104:107], v[52:55]
	v_mfma_f32_16x16x32_bf16 v[56:59], v[96:99], v[108:111], v[56:59]
	v_mfma_f32_16x16x32_bf16 v[60:63], v[96:99], v[112:115], v[60:63]
	s_waitcnt vmcnt(6) lgkmcnt(0)
	s_barrier
	ds_read_b128 v[84:87], v76
	ds_read_b128 v[88:91], v76 offset:2048
	ds_read_b128 v[92:95], v76 offset:4096
	ds_read_b128 v[96:99], v76 offset:6144
	ds_read_b128 v[100:103], v78
	ds_read_b128 v[104:107], v78 offset:2048
	ds_read_b128 v[108:111], v78 offset:4096
	ds_read_b128 v[112:115], v78 offset:6144
	v_mfma_f32_16x16x32_bf16 v[0:3], v[136:139], v[152:155], v[0:3]
	s_add_u32 s24, s56, 0x0
	s_addc_u32 s25, s57, 0
	s_add_u32 m0, s30, 0x18000
	v_lshl_add_u64 v[124:125], v[64:65], 0, s[24:25]
	global_load_lds_dwordx4 v[124:125], off
	v_mfma_f32_16x16x32_bf16 v[4:7], v[136:139], v[156:159], v[4:7]
	s_add_u32 m0, s30, 0x1a000
	v_lshl_add_u64 v[126:127], v[66:67], 0, s[24:25]
	global_load_lds_dwordx4 v[126:127], off
	v_mfma_f32_16x16x32_bf16 v[8:11], v[136:139], v[160:163], v[8:11]
	s_add_u32 m0, s30, 0x1c000
	v_lshl_add_u64 v[124:125], v[68:69], 0, s[24:25]
	global_load_lds_dwordx4 v[124:125], off
	v_mfma_f32_16x16x32_bf16 v[12:15], v[136:139], v[164:167], v[12:15]
	s_add_u32 m0, s30, 0x1e000
	v_lshl_add_u64 v[126:127], v[70:71], 0, s[24:25]
	global_load_lds_dwordx4 v[126:127], off
	v_mfma_f32_16x16x32_bf16 v[16:19], v[140:143], v[152:155], v[16:19]
	s_add_u32 s24, s58, 0x0
	s_addc_u32 s25, s59, 0
	s_add_u32 m0, s30, 0x20000
	v_lshl_add_u64 v[124:125], v[72:73], 0, s[24:25]
	global_load_lds_dwordx4 v[124:125], off
	v_mfma_f32_16x16x32_bf16 v[20:23], v[140:143], v[156:159], v[20:23]
	s_add_u32 m0, s30, 0x22000
	v_lshl_add_u64 v[126:127], v[74:75], 0, s[24:25]
	global_load_lds_dwordx4 v[126:127], off
	v_mfma_f32_16x16x32_bf16 v[24:27], v[140:143], v[160:163], v[24:27]
	v_mfma_f32_16x16x32_bf16 v[28:31], v[140:143], v[164:167], v[28:31]
	v_mfma_f32_16x16x32_bf16 v[32:35], v[144:147], v[152:155], v[32:35]
	v_mfma_f32_16x16x32_bf16 v[36:39], v[144:147], v[156:159], v[36:39]
	v_mfma_f32_16x16x32_bf16 v[40:43], v[144:147], v[160:163], v[40:43]
	v_mfma_f32_16x16x32_bf16 v[44:47], v[144:147], v[164:167], v[44:47]
	v_mfma_f32_16x16x32_bf16 v[48:51], v[148:151], v[152:155], v[48:51]
	v_mfma_f32_16x16x32_bf16 v[52:55], v[148:151], v[156:159], v[52:55]
	v_mfma_f32_16x16x32_bf16 v[56:59], v[148:151], v[160:163], v[56:59]
	v_mfma_f32_16x16x32_bf16 v[60:63], v[148:151], v[164:167], v[60:63]
	ds_read_b128 v[136:139], v77
	ds_read_b128 v[140:143], v77 offset:2048
	ds_read_b128 v[144:147], v77 offset:4096
	ds_read_b128 v[148:151], v77 offset:6144
	ds_read_b128 v[152:155], v79
	ds_read_b128 v[156:159], v79 offset:2048
	ds_read_b128 v[160:163], v79 offset:4096
	ds_read_b128 v[164:167], v79 offset:6144
	s_waitcnt lgkmcnt(8)
;     ...
;   if (PART != 2) {
;     GEMM_ISSUE(0, 0);
;     if (nk > 1) GEMM_ISSUE(1, 1);
;   }
;   if (PART == 1) return;
;   int st = 0;
;   for (int kt = 0; kt < nk; ++kt) {
;     if (kt + 1 < nk) asm volatile("s_waitcnt vmcnt(6)" ::: "memory");
;     else asm volatile("s_waitcnt vmcnt(0)" ::: "memory");
;     __builtin_amdgcn_s_barrier();
;     asm volatile("" ::: "memory");
;     if (kt + 2 < nk) { const int st2 = (st >= 1) ? st - 1 : 2; GEMM_ISSUE(kt + 2, st2); }
;     const char* la = lds + st * STAGE_B;
;     const char* lb = la + 32768;
;     const unsigned sa_u = (unsigned)(size_t)la + arow_u, sb_u = (unsigned)(size_t)lb + brow_u;
;     const unsigned a0 = sa_u + co0, a1 = sa_u + co1, a2 = sa_u + co2, a3 = sa_u + co3;
;     const unsigned b0 = sb_u + co0, b1 = sb_u + co1, b2 = sb_u + co2, b3 = sb_u + co3;
;     {
;       bf16x8 p0, p1, q0, q1, u0, u1, w0, w1;
;       asm volatile(
;         "ds_read_b128 %4, %12\n\tds_read_b128 %5, %12 offset:4096\n\tds_read_b128 %6, %16\n\tds_read_b128 %7, %16 offset:4096\n\t"
;         "ds_read_b128 %8, %13\n\tds_read_b128 %9, %13 offset:4096\n\tds_read_b128 %10, %17\n\tds_read_b128 %11, %17 offset:4096\n\t"
;         "s_waitcnt lgkmcnt(4)\n\t"
;         "v_mfma_f32_32x32x16_bf16 %0, %4, %6, %0\n\tv_mfma_f32_32x32x16_bf16 %1, %4, %7, %1\n\tv_mfma_f32_32x32x16_bf16 %2, %5, %6, %2\n\tv_mfma_f32_32x32x16_bf16 %3, %5, %7, %3\n\t"
;         "ds_read_b128 %4, %14\n\tds_read_b128 %5, %14 offset:4096\n\tds_read_b128 %6, %18\n\tds_read_b128 %7, %18 offset:4096\n\t"
;         "s_waitcnt lgkmcnt(4)\n\t"
;         "v_mfma_f32_32x32x16_bf16 %0, %8, %10, %0\n\tv_mfma_f32_32x32x16_bf16 %1, %8, %11, %1\n\tv_mfma_f32_32x32x16_bf16 %2, %9, %10, %2\n\tv_mfma_f32_32x32x16_bf16 %3, %9, %11, %3\n\t"
;         "ds_read_b128 %8, %15\n\tds_read_b128 %9, %15 offset:4096\n\tds_read_b128 %10, %19\n\tds_read_b128 %11, %19 offset:4096\n\t"
;         "s_waitcnt lgkmcnt(4)\n\t"
;         "v_mfma_f32_32x32x16_bf16 %0, %4, %6, %0\n\tv_mfma_f32_32x32x16_bf16 %1, %4, %7, %1\n\tv_mfma_f32_32x32x16_bf16 %2, %5, %6, %2\n\tv_mfma_f32_32x32x16_bf16 %3, %5, %7, %3\n\t"
;         "s_waitcnt lgkmcnt(0)\n\t"
;         "v_mfma_f32_32x32x16_bf16 %0, %8, %10, %0\n\tv_mfma_f32_32x32x16_bf16 %1, %8, %11, %1\n\tv_mfma_f32_32x32x16_bf16 %2, %9, %10, %2\n\tv_mfma_f32_32x32x16_bf16 %3, %9, %11, %3"
	v_mfma_f32_16x16x32_bf16 v[0:3], v[84:87], v[100:103], v[0:3]
	v_mfma_f32_16x16x32_bf16 v[4:7], v[84:87], v[104:107], v[4:7]
	v_mfma_f32_16x16x32_bf16 v[8:11], v[84:87], v[108:111], v[8:11]
	v_mfma_f32_16x16x32_bf16 v[12:15], v[84:87], v[112:115], v[12:15]
	v_mfma_f32_16x16x32_bf16 v[16:19], v[88:91], v[100:103], v[16:19]
	v_mfma_f32_16x16x32_bf16 v[20:23], v[88:91], v[104:107], v[20:23]
	v_mfma_f32_16x16x32_bf16 v[24:27], v[88:91], v[108:111], v[24:27]
	v_mfma_f32_16x16x32_bf16 v[28:31], v[88:91], v[112:115], v[28:31]
	v_mfma_f32_16x16x32_bf16 v[32:35], v[92:95], v[100:103], v[32:35]
	v_mfma_f32_16x16x32_bf16 v[36:39], v[92:95], v[104:107], v[36:39]
	v_mfma_f32_16x16x32_bf16 v[40:43], v[92:95], v[108:111], v[40:43]
	v_mfma_f32_16x16x32_bf16 v[44:47], v[92:95], v[112:115], v[44:47]
	v_mfma_f32_16x16x32_bf16 v[48:51], v[96:99], v[100:103], v[48:51]
	v_mfma_f32_16x16x32_bf16 v[52:55], v[96:99], v[104:107], v[52:55]
	v_mfma_f32_16x16x32_bf16 v[56:59], v[96:99], v[108:111], v[56:59]
	v_mfma_f32_16x16x32_bf16 v[60:63], v[96:99], v[112:115], v[60:63]
	s_waitcnt vmcnt(6) lgkmcnt(0)
	s_barrier
	ds_read_b128 v[84:87], v76 offset:49152
	ds_read_b128 v[88:91], v76 offset:51200
	ds_read_b128 v[92:95], v76 offset:53248
	ds_read_b128 v[96:99], v76 offset:55296
	ds_read_b128 v[100:103], v78 offset:49152
	ds_read_b128 v[104:107], v78 offset:51200
	ds_read_b128 v[108:111], v78 offset:53248
	ds_read_b128 v[112:115], v78 offset:55296
	v_mfma_f32_16x16x32_bf16 v[0:3], v[136:139], v[152:155], v[0:3]
	s_add_u32 s24, s56, 0x80
	s_addc_u32 s25, s57, 0
	s_mov_b32 m0, s30
	v_lshl_add_u64 v[124:125], v[64:65], 0, s[24:25]
	global_load_lds_dwordx4 v[124:125], off
	v_mfma_f32_16x16x32_bf16 v[4:7], v[136:139], v[156:159], v[4:7]
	s_add_u32 m0, s30, 0x2000
	v_lshl_add_u64 v[126:127], v[66:67], 0, s[24:25]
	global_load_lds_dwordx4 v[126:127], off
	v_mfma_f32_16x16x32_bf16 v[8:11], v[136:139], v[160:163], v[8:11]
	s_add_u32 m0, s30, 0x4000
	v_lshl_add_u64 v[124:125], v[68:69], 0, s[24:25]
	global_load_lds_dwordx4 v[124:125], off
	v_mfma_f32_16x16x32_bf16 v[12:15], v[136:139], v[164:167], v[12:15]
	s_add_u32 m0, s30, 0x6000
	v_lshl_add_u64 v[126:127], v[70:71], 0, s[24:25]
	global_load_lds_dwordx4 v[126:127], off
	v_mfma_f32_16x16x32_bf16 v[16:19], v[140:143], v[152:155], v[16:19]
	s_add_u32 s24, s58, 0x80
	s_addc_u32 s25, s59, 0
	s_add_u32 m0, s30, 0x8000
	v_lshl_add_u64 v[124:125], v[72:73], 0, s[24:25]
	global_load_lds_dwordx4 v[124:125], off
	v_mfma_f32_16x16x32_bf16 v[20:23], v[140:143], v[156:159], v[20:23]
	s_add_u32 m0, s30, 0xa000
	v_lshl_add_u64 v[126:127], v[74:75], 0, s[24:25]
	global_load_lds_dwordx4 v[126:127], off
	v_mfma_f32_16x16x32_bf16 v[24:27], v[140:143], v[160:163], v[24:27]
	v_mfma_f32_16x16x32_bf16 v[28:31], v[140:143], v[164:167], v[28:31]
	v_mfma_f32_16x16x32_bf16 v[32:35], v[144:147], v[152:155], v[32:35]
	v_mfma_f32_16x16x32_bf16 v[36:39], v[144:147], v[156:159], v[36:39]
	v_mfma_f32_16x16x32_bf16 v[40:43], v[144:147], v[160:163], v[40:43]
	v_mfma_f32_16x16x32_bf16 v[44:47], v[144:147], v[164:167], v[44:47]
	v_mfma_f32_16x16x32_bf16 v[48:51], v[148:151], v[152:155], v[48:51]
	v_mfma_f32_16x16x32_bf16 v[52:55], v[148:151], v[156:159], v[52:55]
	v_mfma_f32_16x16x32_bf16 v[56:59], v[148:151], v[160:163], v[56:59]
	v_mfma_f32_16x16x32_bf16 v[60:63], v[148:151], v[164:167], v[60:63]
	ds_read_b128 v[136:139], v77 offset:49152
	ds_read_b128 v[140:143], v77 offset:51200
	ds_read_b128 v[144:147], v77 offset:53248
	ds_read_b128 v[148:151], v77 offset:55296
	ds_read_b128 v[152:155], v79 offset:49152
	ds_read_b128 v[156:159], v79 offset:51200
	ds_read_b128 v[160:163], v79 offset:53248
	ds_read_b128 v[164:167], v79 offset:55296
	s_waitcnt lgkmcnt(8)
	v_mfma_f32_16x16x32_bf16 v[0:3], v[84:87], v[100:103], v[0:3]
	v_mfma_f32_16x16x32_bf16 v[4:7], v[84:87], v[104:107], v[4:7]
	v_mfma_f32_16x16x32_bf16 v[8:11], v[84:87], v[108:111], v[8:11]
	v_mfma_f32_16x16x32_bf16 v[12:15], v[84:87], v[112:115], v[12:15]
	v_mfma_f32_16x16x32_bf16 v[16:19], v[88:91], v[100:103], v[16:19]
	v_mfma_f32_16x16x32_bf16 v[20:23], v[88:91], v[104:107], v[20:23]
	v_mfma_f32_16x16x32_bf16 v[24:27], v[88:91], v[108:111], v[24:27]
	v_mfma_f32_16x16x32_bf16 v[28:31], v[88:91], v[112:115], v[28:31]
	v_mfma_f32_16x16x32_bf16 v[32:35], v[92:95], v[100:103], v[32:35]
	v_mfma_f32_16x16x32_bf16 v[36:39], v[92:95], v[104:107], v[36:39]
	v_mfma_f32_16x16x32_bf16 v[40:43], v[92:95], v[108:111], v[40:43]
	v_mfma_f32_16x16x32_bf16 v[44:47], v[92:95], v[112:115], v[44:47]
	v_mfma_f32_16x16x32_bf16 v[48:51], v[96:99], v[100:103], v[48:51]
	v_mfma_f32_16x16x32_bf16 v[52:55], v[96:99], v[104:107], v[52:55]
	v_mfma_f32_16x16x32_bf16 v[56:59], v[96:99], v[108:111], v[56:59]
	v_mfma_f32_16x16x32_bf16 v[60:63], v[96:99], v[112:115], v[60:63]
	s_waitcnt lgkmcnt(0)
	v_mfma_f32_16x16x32_bf16 v[0:3], v[136:139], v[152:155], v[0:3]
	v_mfma_f32_16x16x32_bf16 v[4:7], v[136:139], v[156:159], v[4:7]
	v_mfma_f32_16x16x32_bf16 v[8:11], v[136:139], v[160:163], v[8:11]
	v_mfma_f32_16x16x32_bf16 v[12:15], v[136:139], v[164:167], v[12:15]
	v_mfma_f32_16x16x32_bf16 v[16:19], v[140:143], v[152:155], v[16:19]
	v_mfma_f32_16x16x32_bf16 v[20:23], v[140:143], v[156:159], v[20:23]
	v_mfma_f32_16x16x32_bf16 v[24:27], v[140:143], v[160:163], v[24:27]
	v_mfma_f32_16x16x32_bf16 v[28:31], v[140:143], v[164:167], v[28:31]
	v_mfma_f32_16x16x32_bf16 v[32:35], v[144:147], v[152:155], v[32:35]
	v_mfma_f32_16x16x32_bf16 v[36:39], v[144:147], v[156:159], v[36:39]
	v_mfma_f32_16x16x32_bf16 v[40:43], v[144:147], v[160:163], v[40:43]
	v_mfma_f32_16x16x32_bf16 v[44:47], v[144:147], v[164:167], v[44:47]
	v_mfma_f32_16x16x32_bf16 v[48:51], v[148:151], v[152:155], v[48:51]
	v_mfma_f32_16x16x32_bf16 v[52:55], v[148:151], v[156:159], v[52:55]
	v_mfma_f32_16x16x32_bf16 v[56:59], v[148:151], v[160:163], v[56:59]
	v_mfma_f32_16x16x32_bf16 v[60:63], v[148:151], v[164:167], v[60:63]
	s_branch .Ly11_done
;     ...
;   if (PART != 2) {
;     GEMM_ISSUE(0, 0);
;     if (nk > 1) GEMM_ISSUE(1, 1);
;   }
;   if (PART == 1) return;
;   int st = 0;
;   for (int kt = 0; kt < nk; ++kt) {
;     if (kt + 1 < nk) asm volatile("s_waitcnt vmcnt(6)" ::: "memory");
;     else asm volatile("s_waitcnt vmcnt(0)" ::: "memory");
;     __builtin_amdgcn_s_barrier();
;     asm volatile("" ::: "memory");
;     if (kt + 2 < nk) { const int st2 = (st >= 1) ? st - 1 : 2; GEMM_ISSUE(kt + 2, st2); }
;     const char* la = lds + st * STAGE_B;
;     const char* lb = la + 32768;
;     const unsigned sa_u = (unsigned)(size_t)la + arow_u, sb_u = (unsigned)(size_t)lb + brow_u;
;     const unsigned a0 = sa_u + co0, a1 = sa_u + co1, a2 = sa_u + co2, a3 = sa_u + co3;
;     const unsigned b0 = sb_u + co0, b1 = sb_u + co1, b2 = sb_u + co2, b3 = sb_u + co3;
;     {
;       bf16x8 p0, p1, q0, q1, u0, u1, w0, w1;
;       asm volatile(
;         "ds_read_b128 %4, %12\n\tds_read_b128 %5, %12 offset:4096\n\tds_read_b128 %6, %16\n\tds_read_b128 %7, %16 offset:4096\n\t"
;         "ds_read_b128 %8, %13\n\tds_read_b128 %9, %13 offset:4096\n\tds_read_b128 %10, %17\n\tds_read_b128 %11, %17 offset:4096\n\t"
;         "s_waitcnt lgkmcnt(4)\n\t"
;         "v_mfma_f32_32x32x16_bf16 %0, %4, %6, %0\n\tv_mfma_f32_32x32x16_bf16 %1, %4, %7, %1\n\tv_mfma_f32_32x32x16_bf16 %2, %5, %6, %2\n\tv_mfma_f32_32x32x16_bf16 %3, %5, %7, %3\n\t"
;         "ds_read_b128 %4, %14\n\tds_read_b128 %5, %14 offset:4096\n\tds_read_b128 %6, %18\n\tds_read_b128 %7, %18 offset:4096\n\t"
;         "s_waitcnt lgkmcnt(4)\n\t"
;         "v_mfma_f32_32x32x16_bf16 %0, %8, %10, %0\n\tv_mfma_f32_32x32x16_bf16 %1, %8, %11, %1\n\tv_mfma_f32_32x32x16_bf16 %2, %9, %10, %2\n\tv_mfma_f32_32x32x16_bf16 %3, %9, %11, %3\n\t"
;         "ds_read_b128 %8, %15\n\tds_read_b128 %9, %15 offset:4096\n\tds_read_b128 %10, %19\n\tds_read_b128 %11, %19 offset:4096\n\t"
;         "s_waitcnt lgkmcnt(4)\n\t"
;         "v_mfma_f32_32x32x16_bf16 %0, %4, %6, %0\n\tv_mfma_f32_32x32x16_bf16 %1, %4, %7, %1\n\tv_mfma_f32_32x32x16_bf16 %2, %5, %6, %2\n\tv_mfma_f32_32x32x16_bf16 %3, %5, %7, %3\n\t"
;         "s_waitcnt lgkmcnt(0)\n\t"
;         "v_mfma_f32_32x32x16_bf16 %0, %8, %10, %0\n\tv_mfma_f32_32x32x16_bf16 %1, %8, %11, %1\n\tv_mfma_f32_32x32x16_bf16 %2, %9, %10, %2\n\tv_mfma_f32_32x32x16_bf16 %3, %9, %11, %3"
.Ly11_v2:
	ds_read_b128 v[84:87], v80
	ds_read_b128 v[88:91], v80 offset:2048
	ds_read_b128 v[92:95], v80 offset:4096
	ds_read_b128 v[96:99], v80 offset:6144
	ds_read_b128 v[100:103], v82
	ds_read_b128 v[104:107], v82 offset:2048
	ds_read_b128 v[108:111], v82 offset:4096
	ds_read_b128 v[112:115], v82 offset:6144
	s_mov_b32 s24, 0x100
	s_mov_b32 s25, 0
	s_add_u32 m0, s30, 0xc000
	v_lshl_add_u64 v[124:125], v[64:65], 0, s[24:25]
	global_load_lds_dwordx4 v[124:125], off
	s_add_u32 m0, s30, 0xe000
	v_lshl_add_u64 v[126:127], v[66:67], 0, s[24:25]
	global_load_lds_dwordx4 v[126:127], off
	s_add_u32 m0, s30, 0x10000
	v_lshl_add_u64 v[124:125], v[68:69], 0, s[24:25]
	global_load_lds_dwordx4 v[124:125], off
	s_add_u32 m0, s30, 0x12000
	v_lshl_add_u64 v[126:127], v[70:71], 0, s[24:25]
	global_load_lds_dwordx4 v[126:127], off
	s_add_u32 m0, s30, 0x14000
	v_lshl_add_u64 v[124:125], v[72:73], 0, s[24:25]
	global_load_lds_dwordx4 v[124:125], off
	s_add_u32 m0, s30, 0x16000
	v_lshl_add_u64 v[126:127], v[74:75], 0, s[24:25]
	global_load_lds_dwordx4 v[126:127], off
	ds_read_b128 v[136:139], v81
	ds_read_b128 v[140:143], v81 offset:2048
	ds_read_b128 v[144:147], v81 offset:4096
	ds_read_b128 v[148:151], v81 offset:6144
	ds_read_b128 v[152:155], v83
	ds_read_b128 v[156:159], v83 offset:2048
	ds_read_b128 v[160:163], v83 offset:4096
	ds_read_b128 v[164:167], v83 offset:6144
	s_waitcnt lgkmcnt(8)
	v_mfma_f32_16x16x32_bf16 v[0:3], v[84:87], v[100:103], v[0:3]
	v_mfma_f32_16x16x32_bf16 v[4:7], v[84:87], v[104:107], v[4:7]
	v_mfma_f32_16x16x32_bf16 v[8:11], v[84:87], v[108:111], v[8:11]
	v_mfma_f32_16x16x32_bf16 v[12:15], v[84:87], v[112:115], v[12:15]
	v_mfma_f32_16x16x32_bf16 v[16:19], v[88:91], v[100:103], v[16:19]
	v_mfma_f32_16x16x32_bf16 v[20:23], v[88:91], v[104:107], v[20:23]
	v_mfma_f32_16x16x32_bf16 v[24:27], v[88:91], v[108:111], v[24:27]
	v_mfma_f32_16x16x32_bf16 v[28:31], v[88:91], v[112:115], v[28:31]
	v_mfma_f32_16x16x32_bf16 v[32:35], v[92:95], v[100:103], v[32:35]
	v_mfma_f32_16x16x32_bf16 v[36:39], v[92:95], v[104:107], v[36:39]
	v_mfma_f32_16x16x32_bf16 v[40:43], v[92:95], v[108:111], v[40:43]
	v_mfma_f32_16x16x32_bf16 v[44:47], v[92:95], v[112:115], v[44:47]
	v_mfma_f32_16x16x32_bf16 v[48:51], v[96:99], v[100:103], v[48:51]
	v_mfma_f32_16x16x32_bf16 v[52:55], v[96:99], v[104:107], v[52:55]
	v_mfma_f32_16x16x32_bf16 v[56:59], v[96:99], v[108:111], v[56:59]
	v_mfma_f32_16x16x32_bf16 v[60:63], v[96:99], v[112:115], v[60:63]
	s_waitcnt vmcnt(6) lgkmcnt(0)
	s_barrier
	ds_read_b128 v[84:87], v76
	ds_read_b128 v[88:91], v76 offset:2048
	ds_read_b128 v[92:95], v76 offset:4096
	ds_read_b128 v[96:99], v76 offset:6144
	ds_read_b128 v[100:103], v78
	ds_read_b128 v[104:107], v78 offset:2048
	ds_read_b128 v[108:111], v78 offset:4096
	ds_read_b128 v[112:115], v78 offset:6144
	v_mfma_f32_16x16x32_bf16 v[0:3], v[136:139], v[152:155], v[0:3]
	s_mov_b32 s24, 0x180
	s_mov_b32 s25, 0
	s_add_u32 m0, s30, 0x18000
	v_lshl_add_u64 v[124:125], v[64:65], 0, s[24:25]
	global_load_lds_dwordx4 v[124:125], off
	v_mfma_f32_16x16x32_bf16 v[4:7], v[136:139], v[156:159], v[4:7]
	s_add_u32 m0, s30, 0x1a000
	v_lshl_add_u64 v[126:127], v[66:67], 0, s[24:25]
	global_load_lds_dwordx4 v[126:127], off
	v_mfma_f32_16x16x32_bf16 v[8:11], v[136:139], v[160:163], v[8:11]
	s_add_u32 m0, s30, 0x1c000
	v_lshl_add_u64 v[124:125], v[68:69], 0, s[24:25]
	global_load_lds_dwordx4 v[124:125], off
	v_mfma_f32_16x16x32_bf16 v[12:15], v[136:139], v[164:167], v[12:15]
	s_add_u32 m0, s30, 0x1e000
	v_lshl_add_u64 v[126:127], v[70:71], 0, s[24:25]
	global_load_lds_dwordx4 v[126:127], off
	v_mfma_f32_16x16x32_bf16 v[16:19], v[140:143], v[152:155], v[16:19]
	s_add_u32 m0, s30, 0x20000
	v_lshl_add_u64 v[124:125], v[72:73], 0, s[24:25]
	global_load_lds_dwordx4 v[124:125], off
	v_mfma_f32_16x16x32_bf16 v[20:23], v[140:143], v[156:159], v[20:23]
	s_add_u32 m0, s30, 0x22000
	v_lshl_add_u64 v[126:127], v[74:75], 0, s[24:25]
	global_load_lds_dwordx4 v[126:127], off
	v_mfma_f32_16x16x32_bf16 v[24:27], v[140:143], v[160:163], v[24:27]
	v_mfma_f32_16x16x32_bf16 v[28:31], v[140:143], v[164:167], v[28:31]
	v_mfma_f32_16x16x32_bf16 v[32:35], v[144:147], v[152:155], v[32:35]
	v_mfma_f32_16x16x32_bf16 v[36:39], v[144:147], v[156:159], v[36:39]
	v_mfma_f32_16x16x32_bf16 v[40:43], v[144:147], v[160:163], v[40:43]
	v_mfma_f32_16x16x32_bf16 v[44:47], v[144:147], v[164:167], v[44:47]
	v_mfma_f32_16x16x32_bf16 v[48:51], v[148:151], v[152:155], v[48:51]
	v_mfma_f32_16x16x32_bf16 v[52:55], v[148:151], v[156:159], v[52:55]
	v_mfma_f32_16x16x32_bf16 v[56:59], v[148:151], v[160:163], v[56:59]
	v_mfma_f32_16x16x32_bf16 v[60:63], v[148:151], v[164:167], v[60:63]
	ds_read_b128 v[136:139], v77
	ds_read_b128 v[140:143], v77 offset:2048
	ds_read_b128 v[144:147], v77 offset:4096
	ds_read_b128 v[148:151], v77 offset:6144
	ds_read_b128 v[152:155], v79
	ds_read_b128 v[156:159], v79 offset:2048
	ds_read_b128 v[160:163], v79 offset:4096
	ds_read_b128 v[164:167], v79 offset:6144
	s_waitcnt lgkmcnt(8)
	v_mfma_f32_16x16x32_bf16 v[0:3], v[84:87], v[100:103], v[0:3]
	v_mfma_f32_16x16x32_bf16 v[4:7], v[84:87], v[104:107], v[4:7]
	v_mfma_f32_16x16x32_bf16 v[8:11], v[84:87], v[108:111], v[8:11]
	v_mfma_f32_16x16x32_bf16 v[12:15], v[84:87], v[112:115], v[12:15]
	v_mfma_f32_16x16x32_bf16 v[16:19], v[88:91], v[100:103], v[16:19]
	v_mfma_f32_16x16x32_bf16 v[20:23], v[88:91], v[104:107], v[20:23]
	v_mfma_f32_16x16x32_bf16 v[24:27], v[88:91], v[108:111], v[24:27]
	v_mfma_f32_16x16x32_bf16 v[28:31], v[88:91], v[112:115], v[28:31]
	v_mfma_f32_16x16x32_bf16 v[32:35], v[92:95], v[100:103], v[32:35]
	v_mfma_f32_16x16x32_bf16 v[36:39], v[92:95], v[104:107], v[36:39]
	v_mfma_f32_16x16x32_bf16 v[40:43], v[92:95], v[108:111], v[40:43]
	v_mfma_f32_16x16x32_bf16 v[44:47], v[92:95], v[112:115], v[44:47]
	v_mfma_f32_16x16x32_bf16 v[48:51], v[96:99], v[100:103], v[48:51]
	v_mfma_f32_16x16x32_bf16 v[52:55], v[96:99], v[104:107], v[52:55]
	v_mfma_f32_16x16x32_bf16 v[56:59], v[96:99], v[108:111], v[56:59]
	v_mfma_f32_16x16x32_bf16 v[60:63], v[96:99], v[112:115], v[60:63]
	s_waitcnt vmcnt(6) lgkmcnt(0)
	s_barrier
;     ...
;   if (PART != 2) {
;     GEMM_ISSUE(0, 0);
;     if (nk > 1) GEMM_ISSUE(1, 1);
;   }
;   if (PART == 1) return;
;   int st = 0;
;   for (int kt = 0; kt < nk; ++kt) {
;     if (kt + 1 < nk) asm volatile("s_waitcnt vmcnt(6)" ::: "memory");
;     else asm volatile("s_waitcnt vmcnt(0)" ::: "memory");
;     __builtin_amdgcn_s_barrier();
;     asm volatile("" ::: "memory");
;     if (kt + 2 < nk) { const int st2 = (st >= 1) ? st - 1 : 2; GEMM_ISSUE(kt + 2, st2); }
;     const char* la = lds + st * STAGE_B;
;     const char* lb = la + 32768;
;     const unsigned sa_u = (unsigned)(size_t)la + arow_u, sb_u = (unsigned)(size_t)lb + brow_u;
;     const unsigned a0 = sa_u + co0, a1 = sa_u + co1, a2 = sa_u + co2, a3 = sa_u + co3;
;     const unsigned b0 = sb_u + co0, b1 = sb_u + co1, b2 = sb_u + co2, b3 = sb_u + co3;
;     {
;       bf16x8 p0, p1, q0, q1, u0, u1, w0, w1;
;       asm volatile(
;         "ds_read_b128 %4, %12\n\tds_read_b128 %5, %12 offset:4096\n\tds_read_b128 %6, %16\n\tds_read_b128 %7, %16 offset:4096\n\t"
;         "ds_read_b128 %8, %13\n\tds_read_b128 %9, %13 offset:4096\n\tds_read_b128 %10, %17\n\tds_read_b128 %11, %17 offset:4096\n\t"
;         "s_waitcnt lgkmcnt(4)\n\t"
;         "v_mfma_f32_32x32x16_bf16 %0, %4, %6, %0\n\tv_mfma_f32_32x32x16_bf16 %1, %4, %7, %1\n\tv_mfma_f32_32x32x16_bf16 %2, %5, %6, %2\n\tv_mfma_f32_32x32x16_bf16 %3, %5, %7, %3\n\t"
;         "ds_read_b128 %4, %14\n\tds_read_b128 %5, %14 offset:4096\n\tds_read_b128 %6, %18\n\tds_read_b128 %7, %18 offset:4096\n\t"
;         "s_waitcnt lgkmcnt(4)\n\t"
;         "v_mfma_f32_32x32x16_bf16 %0, %8, %10, %0\n\tv_mfma_f32_32x32x16_bf16 %1, %8, %11, %1\n\tv_mfma_f32_32x32x16_bf16 %2, %9, %10, %2\n\tv_mfma_f32_32x32x16_bf16 %3, %9, %11, %3\n\t"
;         "ds_read_b128 %8, %15\n\tds_read_b128 %9, %15 offset:4096\n\tds_read_b128 %10, %19\n\tds_read_b128 %11, %19 offset:4096\n\t"
;         "s_waitcnt lgkmcnt(4)\n\t"
;         "v_mfma_f32_32x32x16_bf16 %0, %4, %6, %0\n\tv_mfma_f32_32x32x16_bf16 %1, %4, %7, %1\n\tv_mfma_f32_32x32x16_bf16 %2, %5, %6, %2\n\tv_mfma_f32_32x32x16_bf16 %3, %5, %7, %3\n\t"
;         "s_waitcnt lgkmcnt(0)\n\t"
;         "v_mfma_f32_32x32x16_bf16 %0, %8, %10, %0\n\tv_mfma_f32_32x32x16_bf16 %1, %8, %11, %1\n\tv_mfma_f32_32x32x16_bf16 %2, %9, %10, %2\n\tv_mfma_f32_32x32x16_bf16 %3, %9, %11, %3"
	ds_read_b128 v[84:87], v76 offset:49152
	ds_read_b128 v[88:91], v76 offset:51200
	ds_read_b128 v[92:95], v76 offset:53248
	ds_read_b128 v[96:99], v76 offset:55296
	ds_read_b128 v[100:103], v78 offset:49152
	ds_read_b128 v[104:107], v78 offset:51200
	ds_read_b128 v[108:111], v78 offset:53248
	ds_read_b128 v[112:115], v78 offset:55296
	v_mfma_f32_16x16x32_bf16 v[0:3], v[136:139], v[152:155], v[0:3]
	s_mov_b32 s24, 0x200
	s_mov_b32 s25, 0
	s_mov_b32 m0, s30
	v_lshl_add_u64 v[124:125], v[64:65], 0, s[24:25]
	global_load_lds_dwordx4 v[124:125], off
	v_mfma_f32_16x16x32_bf16 v[4:7], v[136:139], v[156:159], v[4:7]
	s_add_u32 m0, s30, 0x2000
	v_lshl_add_u64 v[126:127], v[66:67], 0, s[24:25]
	global_load_lds_dwordx4 v[126:127], off
	v_mfma_f32_16x16x32_bf16 v[8:11], v[136:139], v[160:163], v[8:11]
	s_add_u32 m0, s30, 0x4000
	v_lshl_add_u64 v[124:125], v[68:69], 0, s[24:25]
	global_load_lds_dwordx4 v[124:125], off
	v_mfma_f32_16x16x32_bf16 v[12:15], v[136:139], v[164:167], v[12:15]
	s_add_u32 m0, s30, 0x6000
	v_lshl_add_u64 v[126:127], v[70:71], 0, s[24:25]
	global_load_lds_dwordx4 v[126:127], off
	v_mfma_f32_16x16x32_bf16 v[16:19], v[140:143], v[152:155], v[16:19]
	s_add_u32 m0, s30, 0x8000
	v_lshl_add_u64 v[124:125], v[72:73], 0, s[24:25]
	global_load_lds_dwordx4 v[124:125], off
	v_mfma_f32_16x16x32_bf16 v[20:23], v[140:143], v[156:159], v[20:23]
	s_add_u32 m0, s30, 0xa000
	v_lshl_add_u64 v[126:127], v[74:75], 0, s[24:25]
	global_load_lds_dwordx4 v[126:127], off
	v_mfma_f32_16x16x32_bf16 v[24:27], v[140:143], v[160:163], v[24:27]
	v_mfma_f32_16x16x32_bf16 v[28:31], v[140:143], v[164:167], v[28:31]
	v_mfma_f32_16x16x32_bf16 v[32:35], v[144:147], v[152:155], v[32:35]
	v_mfma_f32_16x16x32_bf16 v[36:39], v[144:147], v[156:159], v[36:39]
	v_mfma_f32_16x16x32_bf16 v[40:43], v[144:147], v[160:163], v[40:43]
	v_mfma_f32_16x16x32_bf16 v[44:47], v[144:147], v[164:167], v[44:47]
	v_mfma_f32_16x16x32_bf16 v[48:51], v[148:151], v[152:155], v[48:51]
	v_mfma_f32_16x16x32_bf16 v[52:55], v[148:151], v[156:159], v[52:55]
	v_mfma_f32_16x16x32_bf16 v[56:59], v[148:151], v[160:163], v[56:59]
	v_mfma_f32_16x16x32_bf16 v[60:63], v[148:151], v[164:167], v[60:63]
	ds_read_b128 v[136:139], v77 offset:49152
	ds_read_b128 v[140:143], v77 offset:51200
	ds_read_b128 v[144:147], v77 offset:53248
	ds_read_b128 v[148:151], v77 offset:55296
	ds_read_b128 v[152:155], v79 offset:49152
	ds_read_b128 v[156:159], v79 offset:51200
	ds_read_b128 v[160:163], v79 offset:53248
	ds_read_b128 v[164:167], v79 offset:55296
	s_waitcnt lgkmcnt(8)
	v_mfma_f32_16x16x32_bf16 v[0:3], v[84:87], v[100:103], v[0:3]
	v_mfma_f32_16x16x32_bf16 v[4:7], v[84:87], v[104:107], v[4:7]
	v_mfma_f32_16x16x32_bf16 v[8:11], v[84:87], v[108:111], v[8:11]
	v_mfma_f32_16x16x32_bf16 v[12:15], v[84:87], v[112:115], v[12:15]
	v_mfma_f32_16x16x32_bf16 v[16:19], v[88:91], v[100:103], v[16:19]
	v_mfma_f32_16x16x32_bf16 v[20:23], v[88:91], v[104:107], v[20:23]
	v_mfma_f32_16x16x32_bf16 v[24:27], v[88:91], v[108:111], v[24:27]
	v_mfma_f32_16x16x32_bf16 v[28:31], v[88:91], v[112:115], v[28:31]
	v_mfma_f32_16x16x32_bf16 v[32:35], v[92:95], v[100:103], v[32:35]
	v_mfma_f32_16x16x32_bf16 v[36:39], v[92:95], v[104:107], v[36:39]
	v_mfma_f32_16x16x32_bf16 v[40:43], v[92:95], v[108:111], v[40:43]
	v_mfma_f32_16x16x32_bf16 v[44:47], v[92:95], v[112:115], v[44:47]
	v_mfma_f32_16x16x32_bf16 v[48:51], v[96:99], v[100:103], v[48:51]
	v_mfma_f32_16x16x32_bf16 v[52:55], v[96:99], v[104:107], v[52:55]
	v_mfma_f32_16x16x32_bf16 v[56:59], v[96:99], v[108:111], v[56:59]
	v_mfma_f32_16x16x32_bf16 v[60:63], v[96:99], v[112:115], v[60:63]
	s_waitcnt vmcnt(6) lgkmcnt(0)
	s_barrier
	ds_read_b128 v[84:87], v80
	ds_read_b128 v[88:91], v80 offset:2048
	ds_read_b128 v[92:95], v80 offset:4096
	ds_read_b128 v[96:99], v80 offset:6144
	ds_read_b128 v[100:103], v82
	ds_read_b128 v[104:107], v82 offset:2048
	ds_read_b128 v[108:111], v82 offset:4096
	ds_read_b128 v[112:115], v82 offset:6144
	v_mfma_f32_16x16x32_bf16 v[0:3], v[136:139], v[152:155], v[0:3]
	s_mov_b32 s24, 0x280
	s_mov_b32 s25, 0
	s_add_u32 m0, s30, 0xc000
	v_lshl_add_u64 v[124:125], v[64:65], 0, s[24:25]
	global_load_lds_dwordx4 v[124:125], off
	v_mfma_f32_16x16x32_bf16 v[4:7], v[136:139], v[156:159], v[4:7]
	s_add_u32 m0, s30, 0xe000
	v_lshl_add_u64 v[126:127], v[66:67], 0, s[24:25]
	global_load_lds_dwordx4 v[126:127], off
	v_mfma_f32_16x16x32_bf16 v[8:11], v[136:139], v[160:163], v[8:11]
	s_add_u32 m0, s30, 0x10000
	v_lshl_add_u64 v[124:125], v[68:69], 0, s[24:25]
	global_load_lds_dwordx4 v[124:125], off
	v_mfma_f32_16x16x32_bf16 v[12:15], v[136:139], v[164:167], v[12:15]
	s_add_u32 m0, s30, 0x12000
	v_lshl_add_u64 v[126:127], v[70:71], 0, s[24:25]
	global_load_lds_dwordx4 v[126:127], off
	v_mfma_f32_16x16x32_bf16 v[16:19], v[140:143], v[152:155], v[16:19]
	s_add_u32 m0, s30, 0x14000
	v_lshl_add_u64 v[124:125], v[72:73], 0, s[24:25]
	global_load_lds_dwordx4 v[124:125], off
	v_mfma_f32_16x16x32_bf16 v[20:23], v[140:143], v[156:159], v[20:23]
	s_add_u32 m0, s30, 0x16000
	v_lshl_add_u64 v[126:127], v[74:75], 0, s[24:25]
	global_load_lds_dwordx4 v[126:127], off
	v_mfma_f32_16x16x32_bf16 v[24:27], v[140:143], v[160:163], v[24:27]
	v_mfma_f32_16x16x32_bf16 v[28:31], v[140:143], v[164:167], v[28:31]
	v_mfma_f32_16x16x32_bf16 v[32:35], v[144:147], v[152:155], v[32:35]
	v_mfma_f32_16x16x32_bf16 v[36:39], v[144:147], v[156:159], v[36:39]
	v_mfma_f32_16x16x32_bf16 v[40:43], v[144:147], v[160:163], v[40:43]
	v_mfma_f32_16x16x32_bf16 v[44:47], v[144:147], v[164:167], v[44:47]
	v_mfma_f32_16x16x32_bf16 v[48:51], v[148:151], v[152:155], v[48:51]
	v_mfma_f32_16x16x32_bf16 v[52:55], v[148:151], v[156:159], v[52:55]
	v_mfma_f32_16x16x32_bf16 v[56:59], v[148:151], v[160:163], v[56:59]
	v_mfma_f32_16x16x32_bf16 v[60:63], v[148:151], v[164:167], v[60:63]
	ds_read_b128 v[136:139], v81
	ds_read_b128 v[140:143], v81 offset:2048
	ds_read_b128 v[144:147], v81 offset:4096
	ds_read_b128 v[148:151], v81 offset:6144
	ds_read_b128 v[152:155], v83
	ds_read_b128 v[156:159], v83 offset:2048
	ds_read_b128 v[160:163], v83 offset:4096
	ds_read_b128 v[164:167], v83 offset:6144
	s_waitcnt lgkmcnt(8)
;     ...
;   if (PART != 2) {
;     GEMM_ISSUE(0, 0);
;     if (nk > 1) GEMM_ISSUE(1, 1);
;   }
;   if (PART == 1) return;
;   int st = 0;
;   for (int kt = 0; kt < nk; ++kt) {
;     if (kt + 1 < nk) asm volatile("s_waitcnt vmcnt(6)" ::: "memory");
;     else asm volatile("s_waitcnt vmcnt(0)" ::: "memory");
;     __builtin_amdgcn_s_barrier();
;     asm volatile("" ::: "memory");
;     if (kt + 2 < nk) { const int st2 = (st >= 1) ? st - 1 : 2; GEMM_ISSUE(kt + 2, st2); }
;     const char* la = lds + st * STAGE_B;
;     const char* lb = la + 32768;
;     const unsigned sa_u = (unsigned)(size_t)la + arow_u, sb_u = (unsigned)(size_t)lb + brow_u;
;     const unsigned a0 = sa_u + co0, a1 = sa_u + co1, a2 = sa_u + co2, a3 = sa_u + co3;
;     const unsigned b0 = sb_u + co0, b1 = sb_u + co1, b2 = sb_u + co2, b3 = sb_u + co3;
;     {
;       bf16x8 p0, p1, q0, q1, u0, u1, w0, w1;
;       asm volatile(
;         "ds_read_b128 %4, %12\n\tds_read_b128 %5, %12 offset:4096\n\tds_read_b128 %6, %16\n\tds_read_b128 %7, %16 offset:4096\n\t"
;         "ds_read_b128 %8, %13\n\tds_read_b128 %9, %13 offset:4096\n\tds_read_b128 %10, %17\n\tds_read_b128 %11, %17 offset:4096\n\t"
;         "s_waitcnt lgkmcnt(4)\n\t"
;         "v_mfma_f32_32x32x16_bf16 %0, %4, %6, %0\n\tv_mfma_f32_32x32x16_bf16 %1, %4, %7, %1\n\tv_mfma_f32_32x32x16_bf16 %2, %5, %6, %2\n\tv_mfma_f32_32x32x16_bf16 %3, %5, %7, %3\n\t"
;         "ds_read_b128 %4, %14\n\tds_read_b128 %5, %14 offset:4096\n\tds_read_b128 %6, %18\n\tds_read_b128 %7, %18 offset:4096\n\t"
;         "s_waitcnt lgkmcnt(4)\n\t"
;         "v_mfma_f32_32x32x16_bf16 %0, %8, %10, %0\n\tv_mfma_f32_32x32x16_bf16 %1, %8, %11, %1\n\tv_mfma_f32_32x32x16_bf16 %2, %9, %10, %2\n\tv_mfma_f32_32x32x16_bf16 %3, %9, %11, %3\n\t"
;         "ds_read_b128 %8, %15\n\tds_read_b128 %9, %15 offset:4096\n\tds_read_b128 %10, %19\n\tds_read_b128 %11, %19 offset:4096\n\t"
;         "s_waitcnt lgkmcnt(4)\n\t"
;         "v_mfma_f32_32x32x16_bf16 %0, %4, %6, %0\n\tv_mfma_f32_32x32x16_bf16 %1, %4, %7, %1\n\tv_mfma_f32_32x32x16_bf16 %2, %5, %6, %2\n\tv_mfma_f32_32x32x16_bf16 %3, %5, %7, %3\n\t"
;         "s_waitcnt lgkmcnt(0)\n\t"
;         "v_mfma_f32_32x32x16_bf16 %0, %8, %10, %0\n\tv_mfma_f32_32x32x16_bf16 %1, %8, %11, %1\n\tv_mfma_f32_32x32x16_bf16 %2, %9, %10, %2\n\tv_mfma_f32_32x32x16_bf16 %3, %9, %11, %3"
	v_mfma_f32_16x16x32_bf16 v[0:3], v[84:87], v[100:103], v[0:3]
	v_mfma_f32_16x16x32_bf16 v[4:7], v[84:87], v[104:107], v[4:7]
	v_mfma_f32_16x16x32_bf16 v[8:11], v[84:87], v[108:111], v[8:11]
	v_mfma_f32_16x16x32_bf16 v[12:15], v[84:87], v[112:115], v[12:15]
	v_mfma_f32_16x16x32_bf16 v[16:19], v[88:91], v[100:103], v[16:19]
	v_mfma_f32_16x16x32_bf16 v[20:23], v[88:91], v[104:107], v[20:23]
	v_mfma_f32_16x16x32_bf16 v[24:27], v[88:91], v[108:111], v[24:27]
	v_mfma_f32_16x16x32_bf16 v[28:31], v[88:91], v[112:115], v[28:31]
	v_mfma_f32_16x16x32_bf16 v[32:35], v[92:95], v[100:103], v[32:35]
	v_mfma_f32_16x16x32_bf16 v[36:39], v[92:95], v[104:107], v[36:39]
	v_mfma_f32_16x16x32_bf16 v[40:43], v[92:95], v[108:111], v[40:43]
	v_mfma_f32_16x16x32_bf16 v[44:47], v[92:95], v[112:115], v[44:47]
	v_mfma_f32_16x16x32_bf16 v[48:51], v[96:99], v[100:103], v[48:51]
	v_mfma_f32_16x16x32_bf16 v[52:55], v[96:99], v[104:107], v[52:55]
	v_mfma_f32_16x16x32_bf16 v[56:59], v[96:99], v[108:111], v[56:59]
	v_mfma_f32_16x16x32_bf16 v[60:63], v[96:99], v[112:115], v[60:63]
	s_waitcnt vmcnt(6) lgkmcnt(0)
	s_barrier
	ds_read_b128 v[84:87], v76
	ds_read_b128 v[88:91], v76 offset:2048
	ds_read_b128 v[92:95], v76 offset:4096
	ds_read_b128 v[96:99], v76 offset:6144
	ds_read_b128 v[100:103], v78
	ds_read_b128 v[104:107], v78 offset:2048
	ds_read_b128 v[108:111], v78 offset:4096
	ds_read_b128 v[112:115], v78 offset:6144
	v_mfma_f32_16x16x32_bf16 v[0:3], v[136:139], v[152:155], v[0:3]
	s_mov_b32 s24, 0x300
	s_mov_b32 s25, 0
	s_add_u32 m0, s30, 0x18000
	v_lshl_add_u64 v[124:125], v[64:65], 0, s[24:25]
	global_load_lds_dwordx4 v[124:125], off
	v_mfma_f32_16x16x32_bf16 v[4:7], v[136:139], v[156:159], v[4:7]
	s_add_u32 m0, s30, 0x1a000
	v_lshl_add_u64 v[126:127], v[66:67], 0, s[24:25]
	global_load_lds_dwordx4 v[126:127], off
	v_mfma_f32_16x16x32_bf16 v[8:11], v[136:139], v[160:163], v[8:11]
	s_add_u32 m0, s30, 0x1c000
	v_lshl_add_u64 v[124:125], v[68:69], 0, s[24:25]
	global_load_lds_dwordx4 v[124:125], off
	v_mfma_f32_16x16x32_bf16 v[12:15], v[136:139], v[164:167], v[12:15]
	s_add_u32 m0, s30, 0x1e000
	v_lshl_add_u64 v[126:127], v[70:71], 0, s[24:25]
	global_load_lds_dwordx4 v[126:127], off
	v_mfma_f32_16x16x32_bf16 v[16:19], v[140:143], v[152:155], v[16:19]
	s_add_u32 m0, s30, 0x20000
	v_lshl_add_u64 v[124:125], v[72:73], 0, s[24:25]
	global_load_lds_dwordx4 v[124:125], off
	v_mfma_f32_16x16x32_bf16 v[20:23], v[140:143], v[156:159], v[20:23]
	s_add_u32 m0, s30, 0x22000
	v_lshl_add_u64 v[126:127], v[74:75], 0, s[24:25]
	global_load_lds_dwordx4 v[126:127], off
	v_mfma_f32_16x16x32_bf16 v[24:27], v[140:143], v[160:163], v[24:27]
	v_mfma_f32_16x16x32_bf16 v[28:31], v[140:143], v[164:167], v[28:31]
	v_mfma_f32_16x16x32_bf16 v[32:35], v[144:147], v[152:155], v[32:35]
	v_mfma_f32_16x16x32_bf16 v[36:39], v[144:147], v[156:159], v[36:39]
	v_mfma_f32_16x16x32_bf16 v[40:43], v[144:147], v[160:163], v[40:43]
	v_mfma_f32_16x16x32_bf16 v[44:47], v[144:147], v[164:167], v[44:47]
	v_mfma_f32_16x16x32_bf16 v[48:51], v[148:151], v[152:155], v[48:51]
	v_mfma_f32_16x16x32_bf16 v[52:55], v[148:151], v[156:159], v[52:55]
	v_mfma_f32_16x16x32_bf16 v[56:59], v[148:151], v[160:163], v[56:59]
	v_mfma_f32_16x16x32_bf16 v[60:63], v[148:151], v[164:167], v[60:63]
	ds_read_b128 v[136:139], v77
	ds_read_b128 v[140:143], v77 offset:2048
	ds_read_b128 v[144:147], v77 offset:4096
	ds_read_b128 v[148:151], v77 offset:6144
	ds_read_b128 v[152:155], v79
	ds_read_b128 v[156:159], v79 offset:2048
	ds_read_b128 v[160:163], v79 offset:4096
	ds_read_b128 v[164:167], v79 offset:6144
	s_waitcnt lgkmcnt(8)
	v_mfma_f32_16x16x32_bf16 v[0:3], v[84:87], v[100:103], v[0:3]
	v_mfma_f32_16x16x32_bf16 v[4:7], v[84:87], v[104:107], v[4:7]
	v_mfma_f32_16x16x32_bf16 v[8:11], v[84:87], v[108:111], v[8:11]
	v_mfma_f32_16x16x32_bf16 v[12:15], v[84:87], v[112:115], v[12:15]
	v_mfma_f32_16x16x32_bf16 v[16:19], v[88:91], v[100:103], v[16:19]
	v_mfma_f32_16x16x32_bf16 v[20:23], v[88:91], v[104:107], v[20:23]
	v_mfma_f32_16x16x32_bf16 v[24:27], v[88:91], v[108:111], v[24:27]
	v_mfma_f32_16x16x32_bf16 v[28:31], v[88:91], v[112:115], v[28:31]
	v_mfma_f32_16x16x32_bf16 v[32:35], v[92:95], v[100:103], v[32:35]
	v_mfma_f32_16x16x32_bf16 v[36:39], v[92:95], v[104:107], v[36:39]
	v_mfma_f32_16x16x32_bf16 v[40:43], v[92:95], v[108:111], v[40:43]
	v_mfma_f32_16x16x32_bf16 v[44:47], v[92:95], v[112:115], v[44:47]
	v_mfma_f32_16x16x32_bf16 v[48:51], v[96:99], v[100:103], v[48:51]
	v_mfma_f32_16x16x32_bf16 v[52:55], v[96:99], v[104:107], v[52:55]
	v_mfma_f32_16x16x32_bf16 v[56:59], v[96:99], v[108:111], v[56:59]
	v_mfma_f32_16x16x32_bf16 v[60:63], v[96:99], v[112:115], v[60:63]
	s_waitcnt vmcnt(6) lgkmcnt(0)
	s_barrier
;     ...
;   if (PART != 2) {
;     GEMM_ISSUE(0, 0);
;     if (nk > 1) GEMM_ISSUE(1, 1);
;   }
;   if (PART == 1) return;
;   int st = 0;
;   for (int kt = 0; kt < nk; ++kt) {
;     if (kt + 1 < nk) asm volatile("s_waitcnt vmcnt(6)" ::: "memory");
;     else asm volatile("s_waitcnt vmcnt(0)" ::: "memory");
;     __builtin_amdgcn_s_barrier();
;     asm volatile("" ::: "memory");
;     if (kt + 2 < nk) { const int st2 = (st >= 1) ? st - 1 : 2; GEMM_ISSUE(kt + 2, st2); }
;     const char* la = lds + st * STAGE_B;
;     const char* lb = la + 32768;
;     const unsigned sa_u = (unsigned)(size_t)la + arow_u, sb_u = (unsigned)(size_t)lb + brow_u;
;     const unsigned a0 = sa_u + co0, a1 = sa_u + co1, a2 = sa_u + co2, a3 = sa_u + co3;
;     const unsigned b0 = sb_u + co0, b1 = sb_u + co1, b2 = sb_u + co2, b3 = sb_u + co3;
;     {
;       bf16x8 p0, p1, q0, q1, u0, u1, w0, w1;
;       asm volatile(
;         "ds_read_b128 %4, %12\n\tds_read_b128 %5, %12 offset:4096\n\tds_read_b128 %6, %16\n\tds_read_b128 %7, %16 offset:4096\n\t"
;         "ds_read_b128 %8, %13\n\tds_read_b128 %9, %13 offset:4096\n\tds_read_b128 %10, %17\n\tds_read_b128 %11, %17 offset:4096\n\t"
;         "s_waitcnt lgkmcnt(4)\n\t"
;         "v_mfma_f32_32x32x16_bf16 %0, %4, %6, %0\n\tv_mfma_f32_32x32x16_bf16 %1, %4, %7, %1\n\tv_mfma_f32_32x32x16_bf16 %2, %5, %6, %2\n\tv_mfma_f32_32x32x16_bf16 %3, %5, %7, %3\n\t"
;         "ds_read_b128 %4, %14\n\tds_read_b128 %5, %14 offset:4096\n\tds_read_b128 %6, %18\n\tds_read_b128 %7, %18 offset:4096\n\t"
;         "s_waitcnt lgkmcnt(4)\n\t"
;         "v_mfma_f32_32x32x16_bf16 %0, %8, %10, %0\n\tv_mfma_f32_32x32x16_bf16 %1, %8, %11, %1\n\tv_mfma_f32_32x32x16_bf16 %2, %9, %10, %2\n\tv_mfma_f32_32x32x16_bf16 %3, %9, %11, %3\n\t"
;         "ds_read_b128 %8, %15\n\tds_read_b128 %9, %15 offset:4096\n\tds_read_b128 %10, %19\n\tds_read_b128 %11, %19 offset:4096\n\t"
;         "s_waitcnt lgkmcnt(4)\n\t"
;         "v_mfma_f32_32x32x16_bf16 %0, %4, %6, %0\n\tv_mfma_f32_32x32x16_bf16 %1, %4, %7, %1\n\tv_mfma_f32_32x32x16_bf16 %2, %5, %6, %2\n\tv_mfma_f32_32x32x16_bf16 %3, %5, %7, %3\n\t"
;         "s_waitcnt lgkmcnt(0)\n\t"
;         "v_mfma_f32_32x32x16_bf16 %0, %8, %10, %0\n\tv_mfma_f32_32x32x16_bf16 %1, %8, %11, %1\n\tv_mfma_f32_32x32x16_bf16 %2, %9, %10, %2\n\tv_mfma_f32_32x32x16_bf16 %3, %9, %11, %3"
	ds_read_b128 v[84:87], v76 offset:49152
	ds_read_b128 v[88:91], v76 offset:51200
	ds_read_b128 v[92:95], v76 offset:53248
	ds_read_b128 v[96:99], v76 offset:55296
	ds_read_b128 v[100:103], v78 offset:49152
	ds_read_b128 v[104:107], v78 offset:51200
	ds_read_b128 v[108:111], v78 offset:53248
	ds_read_b128 v[112:115], v78 offset:55296
	v_mfma_f32_16x16x32_bf16 v[0:3], v[136:139], v[152:155], v[0:3]
	s_mov_b32 s24, 0x380
	s_mov_b32 s25, 0
	s_mov_b32 m0, s30
	v_lshl_add_u64 v[124:125], v[64:65], 0, s[24:25]
	global_load_lds_dwordx4 v[124:125], off
	v_mfma_f32_16x16x32_bf16 v[4:7], v[136:139], v[156:159], v[4:7]
	s_add_u32 m0, s30, 0x2000
	v_lshl_add_u64 v[126:127], v[66:67], 0, s[24:25]
	global_load_lds_dwordx4 v[126:127], off
	v_mfma_f32_16x16x32_bf16 v[8:11], v[136:139], v[160:163], v[8:11]
	s_add_u32 m0, s30, 0x4000
	v_lshl_add_u64 v[124:125], v[68:69], 0, s[24:25]
	global_load_lds_dwordx4 v[124:125], off
	v_mfma_f32_16x16x32_bf16 v[12:15], v[136:139], v[164:167], v[12:15]
	s_add_u32 m0, s30, 0x6000
	v_lshl_add_u64 v[126:127], v[70:71], 0, s[24:25]
	global_load_lds_dwordx4 v[126:127], off
	v_mfma_f32_16x16x32_bf16 v[16:19], v[140:143], v[152:155], v[16:19]
	s_add_u32 m0, s30, 0x8000
	v_lshl_add_u64 v[124:125], v[72:73], 0, s[24:25]
	global_load_lds_dwordx4 v[124:125], off
	v_mfma_f32_16x16x32_bf16 v[20:23], v[140:143], v[156:159], v[20:23]
	s_add_u32 m0, s30, 0xa000
	v_lshl_add_u64 v[126:127], v[74:75], 0, s[24:25]
	global_load_lds_dwordx4 v[126:127], off
	v_mfma_f32_16x16x32_bf16 v[24:27], v[140:143], v[160:163], v[24:27]
	v_mfma_f32_16x16x32_bf16 v[28:31], v[140:143], v[164:167], v[28:31]
	v_mfma_f32_16x16x32_bf16 v[32:35], v[144:147], v[152:155], v[32:35]
	v_mfma_f32_16x16x32_bf16 v[36:39], v[144:147], v[156:159], v[36:39]
	v_mfma_f32_16x16x32_bf16 v[40:43], v[144:147], v[160:163], v[40:43]
	v_mfma_f32_16x16x32_bf16 v[44:47], v[144:147], v[164:167], v[44:47]
	v_mfma_f32_16x16x32_bf16 v[48:51], v[148:151], v[152:155], v[48:51]
	v_mfma_f32_16x16x32_bf16 v[52:55], v[148:151], v[156:159], v[52:55]
	v_mfma_f32_16x16x32_bf16 v[56:59], v[148:151], v[160:163], v[56:59]
	v_mfma_f32_16x16x32_bf16 v[60:63], v[148:151], v[164:167], v[60:63]
	ds_read_b128 v[136:139], v77 offset:49152
	ds_read_b128 v[140:143], v77 offset:51200
	ds_read_b128 v[144:147], v77 offset:53248
	ds_read_b128 v[148:151], v77 offset:55296
	ds_read_b128 v[152:155], v79 offset:49152
	ds_read_b128 v[156:159], v79 offset:51200
	ds_read_b128 v[160:163], v79 offset:53248
	ds_read_b128 v[164:167], v79 offset:55296
	s_waitcnt lgkmcnt(8)
	v_mfma_f32_16x16x32_bf16 v[0:3], v[84:87], v[100:103], v[0:3]
	v_mfma_f32_16x16x32_bf16 v[4:7], v[84:87], v[104:107], v[4:7]
	v_mfma_f32_16x16x32_bf16 v[8:11], v[84:87], v[108:111], v[8:11]
	v_mfma_f32_16x16x32_bf16 v[12:15], v[84:87], v[112:115], v[12:15]
	v_mfma_f32_16x16x32_bf16 v[16:19], v[88:91], v[100:103], v[16:19]
	v_mfma_f32_16x16x32_bf16 v[20:23], v[88:91], v[104:107], v[20:23]
	v_mfma_f32_16x16x32_bf16 v[24:27], v[88:91], v[108:111], v[24:27]
	v_mfma_f32_16x16x32_bf16 v[28:31], v[88:91], v[112:115], v[28:31]
	v_mfma_f32_16x16x32_bf16 v[32:35], v[92:95], v[100:103], v[32:35]
	v_mfma_f32_16x16x32_bf16 v[36:39], v[92:95], v[104:107], v[36:39]
	v_mfma_f32_16x16x32_bf16 v[40:43], v[92:95], v[108:111], v[40:43]
	v_mfma_f32_16x16x32_bf16 v[44:47], v[92:95], v[112:115], v[44:47]
	v_mfma_f32_16x16x32_bf16 v[48:51], v[96:99], v[100:103], v[48:51]
	v_mfma_f32_16x16x32_bf16 v[52:55], v[96:99], v[104:107], v[52:55]
	v_mfma_f32_16x16x32_bf16 v[56:59], v[96:99], v[108:111], v[56:59]
	v_mfma_f32_16x16x32_bf16 v[60:63], v[96:99], v[112:115], v[60:63]
	s_waitcnt vmcnt(6) lgkmcnt(0)
	s_barrier
	ds_read_b128 v[84:87], v80
	ds_read_b128 v[88:91], v80 offset:2048
	ds_read_b128 v[92:95], v80 offset:4096
	ds_read_b128 v[96:99], v80 offset:6144
	ds_read_b128 v[100:103], v82
	ds_read_b128 v[104:107], v82 offset:2048
	ds_read_b128 v[108:111], v82 offset:4096
	ds_read_b128 v[112:115], v82 offset:6144
	v_mfma_f32_16x16x32_bf16 v[0:3], v[136:139], v[152:155], v[0:3]
	s_mov_b32 s24, 0x400
	s_mov_b32 s25, 0
	s_add_u32 m0, s30, 0xc000
	v_lshl_add_u64 v[124:125], v[64:65], 0, s[24:25]
	global_load_lds_dwordx4 v[124:125], off
	v_mfma_f32_16x16x32_bf16 v[4:7], v[136:139], v[156:159], v[4:7]
	s_add_u32 m0, s30, 0xe000
	v_lshl_add_u64 v[126:127], v[66:67], 0, s[24:25]
	global_load_lds_dwordx4 v[126:127], off
	v_mfma_f32_16x16x32_bf16 v[8:11], v[136:139], v[160:163], v[8:11]
	s_add_u32 m0, s30, 0x10000
	v_lshl_add_u64 v[124:125], v[68:69], 0, s[24:25]
	global_load_lds_dwordx4 v[124:125], off
	v_mfma_f32_16x16x32_bf16 v[12:15], v[136:139], v[164:167], v[12:15]
	s_add_u32 m0, s30, 0x12000
	v_lshl_add_u64 v[126:127], v[70:71], 0, s[24:25]
	global_load_lds_dwordx4 v[126:127], off
	v_mfma_f32_16x16x32_bf16 v[16:19], v[140:143], v[152:155], v[16:19]
	s_add_u32 m0, s30, 0x14000
	v_lshl_add_u64 v[124:125], v[72:73], 0, s[24:25]
	global_load_lds_dwordx4 v[124:125], off
	v_mfma_f32_16x16x32_bf16 v[20:23], v[140:143], v[156:159], v[20:23]
	s_add_u32 m0, s30, 0x16000
	v_lshl_add_u64 v[126:127], v[74:75], 0, s[24:25]
	global_load_lds_dwordx4 v[126:127], off
	v_mfma_f32_16x16x32_bf16 v[24:27], v[140:143], v[160:163], v[24:27]
	v_mfma_f32_16x16x32_bf16 v[28:31], v[140:143], v[164:167], v[28:31]
	v_mfma_f32_16x16x32_bf16 v[32:35], v[144:147], v[152:155], v[32:35]
	v_mfma_f32_16x16x32_bf16 v[36:39], v[144:147], v[156:159], v[36:39]
	v_mfma_f32_16x16x32_bf16 v[40:43], v[144:147], v[160:163], v[40:43]
	v_mfma_f32_16x16x32_bf16 v[44:47], v[144:147], v[164:167], v[44:47]
	v_mfma_f32_16x16x32_bf16 v[48:51], v[148:151], v[152:155], v[48:51]
	v_mfma_f32_16x16x32_bf16 v[52:55], v[148:151], v[156:159], v[52:55]
	v_mfma_f32_16x16x32_bf16 v[56:59], v[148:151], v[160:163], v[56:59]
	v_mfma_f32_16x16x32_bf16 v[60:63], v[148:151], v[164:167], v[60:63]
	ds_read_b128 v[136:139], v81
	ds_read_b128 v[140:143], v81 offset:2048
	ds_read_b128 v[144:147], v81 offset:4096
	ds_read_b128 v[148:151], v81 offset:6144
	ds_read_b128 v[152:155], v83
	ds_read_b128 v[156:159], v83 offset:2048
	ds_read_b128 v[160:163], v83 offset:4096
	ds_read_b128 v[164:167], v83 offset:6144
	s_waitcnt lgkmcnt(8)
;     ...
;   if (PART != 2) {
;     GEMM_ISSUE(0, 0);
;     if (nk > 1) GEMM_ISSUE(1, 1);
;   }
;   if (PART == 1) return;
;   int st = 0;
;   for (int kt = 0; kt < nk; ++kt) {
;     if (kt + 1 < nk) asm volatile("s_waitcnt vmcnt(6)" ::: "memory");
;     else asm volatile("s_waitcnt vmcnt(0)" ::: "memory");
;     __builtin_amdgcn_s_barrier();
;     asm volatile("" ::: "memory");
;     if (kt + 2 < nk) { const int st2 = (st >= 1) ? st - 1 : 2; GEMM_ISSUE(kt + 2, st2); }
;     const char* la = lds + st * STAGE_B;
;     const char* lb = la + 32768;
;     const unsigned sa_u = (unsigned)(size_t)la + arow_u, sb_u = (unsigned)(size_t)lb + brow_u;
;     const unsigned a0 = sa_u + co0, a1 = sa_u + co1, a2 = sa_u + co2, a3 = sa_u + co3;
;     const unsigned b0 = sb_u + co0, b1 = sb_u + co1, b2 = sb_u + co2, b3 = sb_u + co3;
;     {
;       bf16x8 p0, p1, q0, q1, u0, u1, w0, w1;
;       asm volatile(
;         "ds_read_b128 %4, %12\n\tds_read_b128 %5, %12 offset:4096\n\tds_read_b128 %6, %16\n\tds_read_b128 %7, %16 offset:4096\n\t"
;         "ds_read_b128 %8, %13\n\tds_read_b128 %9, %13 offset:4096\n\tds_read_b128 %10, %17\n\tds_read_b128 %11, %17 offset:4096\n\t"
;         "s_waitcnt lgkmcnt(4)\n\t"
;         "v_mfma_f32_32x32x16_bf16 %0, %4, %6, %0\n\tv_mfma_f32_32x32x16_bf16 %1, %4, %7, %1\n\tv_mfma_f32_32x32x16_bf16 %2, %5, %6, %2\n\tv_mfma_f32_32x32x16_bf16 %3, %5, %7, %3\n\t"
;         "ds_read_b128 %4, %14\n\tds_read_b128 %5, %14 offset:4096\n\tds_read_b128 %6, %18\n\tds_read_b128 %7, %18 offset:4096\n\t"
;         "s_waitcnt lgkmcnt(4)\n\t"
;         "v_mfma_f32_32x32x16_bf16 %0, %8, %10, %0\n\tv_mfma_f32_32x32x16_bf16 %1, %8, %11, %1\n\tv_mfma_f32_32x32x16_bf16 %2, %9, %10, %2\n\tv_mfma_f32_32x32x16_bf16 %3, %9, %11, %3\n\t"
;         "ds_read_b128 %8, %15\n\tds_read_b128 %9, %15 offset:4096\n\tds_read_b128 %10, %19\n\tds_read_b128 %11, %19 offset:4096\n\t"
;         "s_waitcnt lgkmcnt(4)\n\t"
;         "v_mfma_f32_32x32x16_bf16 %0, %4, %6, %0\n\tv_mfma_f32_32x32x16_bf16 %1, %4, %7, %1\n\tv_mfma_f32_32x32x16_bf16 %2, %5, %6, %2\n\tv_mfma_f32_32x32x16_bf16 %3, %5, %7, %3\n\t"
;         "s_waitcnt lgkmcnt(0)\n\t"
;         "v_mfma_f32_32x32x16_bf16 %0, %8, %10, %0\n\tv_mfma_f32_32x32x16_bf16 %1, %8, %11, %1\n\tv_mfma_f32_32x32x16_bf16 %2, %9, %10, %2\n\tv_mfma_f32_32x32x16_bf16 %3, %9, %11, %3"
	v_mfma_f32_16x16x32_bf16 v[0:3], v[84:87], v[100:103], v[0:3]
	v_mfma_f32_16x16x32_bf16 v[4:7], v[84:87], v[104:107], v[4:7]
	v_mfma_f32_16x16x32_bf16 v[8:11], v[84:87], v[108:111], v[8:11]
	v_mfma_f32_16x16x32_bf16 v[12:15], v[84:87], v[112:115], v[12:15]
	v_mfma_f32_16x16x32_bf16 v[16:19], v[88:91], v[100:103], v[16:19]
	v_mfma_f32_16x16x32_bf16 v[20:23], v[88:91], v[104:107], v[20:23]
	v_mfma_f32_16x16x32_bf16 v[24:27], v[88:91], v[108:111], v[24:27]
	v_mfma_f32_16x16x32_bf16 v[28:31], v[88:91], v[112:115], v[28:31]
	v_mfma_f32_16x16x32_bf16 v[32:35], v[92:95], v[100:103], v[32:35]
	v_mfma_f32_16x16x32_bf16 v[36:39], v[92:95], v[104:107], v[36:39]
	v_mfma_f32_16x16x32_bf16 v[40:43], v[92:95], v[108:111], v[40:43]
	v_mfma_f32_16x16x32_bf16 v[44:47], v[92:95], v[112:115], v[44:47]
	v_mfma_f32_16x16x32_bf16 v[48:51], v[96:99], v[100:103], v[48:51]
	v_mfma_f32_16x16x32_bf16 v[52:55], v[96:99], v[104:107], v[52:55]
	v_mfma_f32_16x16x32_bf16 v[56:59], v[96:99], v[108:111], v[56:59]
	v_mfma_f32_16x16x32_bf16 v[60:63], v[96:99], v[112:115], v[60:63]
	s_waitcnt vmcnt(6) lgkmcnt(0)
	s_barrier
	ds_read_b128 v[84:87], v76
	ds_read_b128 v[88:91], v76 offset:2048
	ds_read_b128 v[92:95], v76 offset:4096
	ds_read_b128 v[96:99], v76 offset:6144
	ds_read_b128 v[100:103], v78
	ds_read_b128 v[104:107], v78 offset:2048
	ds_read_b128 v[108:111], v78 offset:4096
	ds_read_b128 v[112:115], v78 offset:6144
	v_mfma_f32_16x16x32_bf16 v[0:3], v[136:139], v[152:155], v[0:3]
	s_mov_b32 s24, 0x480
	s_mov_b32 s25, 0
	s_add_u32 m0, s30, 0x18000
	v_lshl_add_u64 v[124:125], v[64:65], 0, s[24:25]
	global_load_lds_dwordx4 v[124:125], off
	v_mfma_f32_16x16x32_bf16 v[4:7], v[136:139], v[156:159], v[4:7]
	s_add_u32 m0, s30, 0x1a000
	v_lshl_add_u64 v[126:127], v[66:67], 0, s[24:25]
	global_load_lds_dwordx4 v[126:127], off
	v_mfma_f32_16x16x32_bf16 v[8:11], v[136:139], v[160:163], v[8:11]
	s_add_u32 m0, s30, 0x1c000
	v_lshl_add_u64 v[124:125], v[68:69], 0, s[24:25]
	global_load_lds_dwordx4 v[124:125], off
	v_mfma_f32_16x16x32_bf16 v[12:15], v[136:139], v[164:167], v[12:15]
	s_add_u32 m0, s30, 0x1e000
	v_lshl_add_u64 v[126:127], v[70:71], 0, s[24:25]
	global_load_lds_dwordx4 v[126:127], off
	v_mfma_f32_16x16x32_bf16 v[16:19], v[140:143], v[152:155], v[16:19]
	s_add_u32 m0, s30, 0x20000
	v_lshl_add_u64 v[124:125], v[72:73], 0, s[24:25]
	global_load_lds_dwordx4 v[124:125], off
	v_mfma_f32_16x16x32_bf16 v[20:23], v[140:143], v[156:159], v[20:23]
	s_add_u32 m0, s30, 0x22000
	v_lshl_add_u64 v[126:127], v[74:75], 0, s[24:25]
	global_load_lds_dwordx4 v[126:127], off
	v_mfma_f32_16x16x32_bf16 v[24:27], v[140:143], v[160:163], v[24:27]
	v_mfma_f32_16x16x32_bf16 v[28:31], v[140:143], v[164:167], v[28:31]
	v_mfma_f32_16x16x32_bf16 v[32:35], v[144:147], v[152:155], v[32:35]
	v_mfma_f32_16x16x32_bf16 v[36:39], v[144:147], v[156:159], v[36:39]
	v_mfma_f32_16x16x32_bf16 v[40:43], v[144:147], v[160:163], v[40:43]
	v_mfma_f32_16x16x32_bf16 v[44:47], v[144:147], v[164:167], v[44:47]
	v_mfma_f32_16x16x32_bf16 v[48:51], v[148:151], v[152:155], v[48:51]
	v_mfma_f32_16x16x32_bf16 v[52:55], v[148:151], v[156:159], v[52:55]
	v_mfma_f32_16x16x32_bf16 v[56:59], v[148:151], v[160:163], v[56:59]
	v_mfma_f32_16x16x32_bf16 v[60:63], v[148:151], v[164:167], v[60:63]
	ds_read_b128 v[136:139], v77
	ds_read_b128 v[140:143], v77 offset:2048
	ds_read_b128 v[144:147], v77 offset:4096
	ds_read_b128 v[148:151], v77 offset:6144
	ds_read_b128 v[152:155], v79
	ds_read_b128 v[156:159], v79 offset:2048
	ds_read_b128 v[160:163], v79 offset:4096
	ds_read_b128 v[164:167], v79 offset:6144
	s_waitcnt lgkmcnt(8)
	v_mfma_f32_16x16x32_bf16 v[0:3], v[84:87], v[100:103], v[0:3]
	v_mfma_f32_16x16x32_bf16 v[4:7], v[84:87], v[104:107], v[4:7]
	v_mfma_f32_16x16x32_bf16 v[8:11], v[84:87], v[108:111], v[8:11]
	v_mfma_f32_16x16x32_bf16 v[12:15], v[84:87], v[112:115], v[12:15]
	v_mfma_f32_16x16x32_bf16 v[16:19], v[88:91], v[100:103], v[16:19]
	v_mfma_f32_16x16x32_bf16 v[20:23], v[88:91], v[104:107], v[20:23]
	v_mfma_f32_16x16x32_bf16 v[24:27], v[88:91], v[108:111], v[24:27]
	v_mfma_f32_16x16x32_bf16 v[28:31], v[88:91], v[112:115], v[28:31]
	v_mfma_f32_16x16x32_bf16 v[32:35], v[92:95], v[100:103], v[32:35]
	v_mfma_f32_16x16x32_bf16 v[36:39], v[92:95], v[104:107], v[36:39]
	v_mfma_f32_16x16x32_bf16 v[40:43], v[92:95], v[108:111], v[40:43]
	v_mfma_f32_16x16x32_bf16 v[44:47], v[92:95], v[112:115], v[44:47]
	v_mfma_f32_16x16x32_bf16 v[48:51], v[96:99], v[100:103], v[48:51]
	v_mfma_f32_16x16x32_bf16 v[52:55], v[96:99], v[104:107], v[52:55]
	v_mfma_f32_16x16x32_bf16 v[56:59], v[96:99], v[108:111], v[56:59]
	v_mfma_f32_16x16x32_bf16 v[60:63], v[96:99], v[112:115], v[60:63]
	s_waitcnt vmcnt(6) lgkmcnt(0)
	s_barrier
;     ...
;   if (PART != 2) {
;     GEMM_ISSUE(0, 0);
;     if (nk > 1) GEMM_ISSUE(1, 1);
;   }
;   if (PART == 1) return;
;   int st = 0;
;   for (int kt = 0; kt < nk; ++kt) {
;     if (kt + 1 < nk) asm volatile("s_waitcnt vmcnt(6)" ::: "memory");
;     else asm volatile("s_waitcnt vmcnt(0)" ::: "memory");
;     __builtin_amdgcn_s_barrier();
;     asm volatile("" ::: "memory");
;     if (kt + 2 < nk) { const int st2 = (st >= 1) ? st - 1 : 2; GEMM_ISSUE(kt + 2, st2); }
;     const char* la = lds + st * STAGE_B;
;     const char* lb = la + 32768;
;     const unsigned sa_u = (unsigned)(size_t)la + arow_u, sb_u = (unsigned)(size_t)lb + brow_u;
;     const unsigned a0 = sa_u + co0, a1 = sa_u + co1, a2 = sa_u + co2, a3 = sa_u + co3;
;     const unsigned b0 = sb_u + co0, b1 = sb_u + co1, b2 = sb_u + co2, b3 = sb_u + co3;
;     {
;       bf16x8 p0, p1, q0, q1, u0, u1, w0, w1;
;       asm volatile(
;         "ds_read_b128 %4, %12\n\tds_read_b128 %5, %12 offset:4096\n\tds_read_b128 %6, %16\n\tds_read_b128 %7, %16 offset:4096\n\t"
;         "ds_read_b128 %8, %13\n\tds_read_b128 %9, %13 offset:4096\n\tds_read_b128 %10, %17\n\tds_read_b128 %11, %17 offset:4096\n\t"
;         "s_waitcnt lgkmcnt(4)\n\t"
;         "v_mfma_f32_32x32x16_bf16 %0, %4, %6, %0\n\tv_mfma_f32_32x32x16_bf16 %1, %4, %7, %1\n\tv_mfma_f32_32x32x16_bf16 %2, %5, %6, %2\n\tv_mfma_f32_32x32x16_bf16 %3, %5, %7, %3\n\t"
;         "ds_read_b128 %4, %14\n\tds_read_b128 %5, %14 offset:4096\n\tds_read_b128 %6, %18\n\tds_read_b128 %7, %18 offset:4096\n\t"
;         "s_waitcnt lgkmcnt(4)\n\t"
;         "v_mfma_f32_32x32x16_bf16 %0, %8, %10, %0\n\tv_mfma_f32_32x32x16_bf16 %1, %8, %11, %1\n\tv_mfma_f32_32x32x16_bf16 %2, %9, %10, %2\n\tv_mfma_f32_32x32x16_bf16 %3, %9, %11, %3\n\t"
;         "ds_read_b128 %8, %15\n\tds_read_b128 %9, %15 offset:4096\n\tds_read_b128 %10, %19\n\tds_read_b128 %11, %19 offset:4096\n\t"
;         "s_waitcnt lgkmcnt(4)\n\t"
;         "v_mfma_f32_32x32x16_bf16 %0, %4, %6, %0\n\tv_mfma_f32_32x32x16_bf16 %1, %4, %7, %1\n\tv_mfma_f32_32x32x16_bf16 %2, %5, %6, %2\n\tv_mfma_f32_32x32x16_bf16 %3, %5, %7, %3\n\t"
;         "s_waitcnt lgkmcnt(0)\n\t"
;         "v_mfma_f32_32x32x16_bf16 %0, %8, %10, %0\n\tv_mfma_f32_32x32x16_bf16 %1, %8, %11, %1\n\tv_mfma_f32_32x32x16_bf16 %2, %9, %10, %2\n\tv_mfma_f32_32x32x16_bf16 %3, %9, %11, %3"
	ds_read_b128 v[84:87], v76 offset:49152
	ds_read_b128 v[88:91], v76 offset:51200
	ds_read_b128 v[92:95], v76 offset:53248
	ds_read_b128 v[96:99], v76 offset:55296
	ds_read_b128 v[100:103], v78 offset:49152
	ds_read_b128 v[104:107], v78 offset:51200
	ds_read_b128 v[108:111], v78 offset:53248
	ds_read_b128 v[112:115], v78 offset:55296
	v_mfma_f32_16x16x32_bf16 v[0:3], v[136:139], v[152:155], v[0:3]
	s_mov_b32 s24, 0x500
	s_mov_b32 s25, 0
	s_mov_b32 m0, s30
	v_lshl_add_u64 v[124:125], v[64:65], 0, s[24:25]
	global_load_lds_dwordx4 v[124:125], off
	v_mfma_f32_16x16x32_bf16 v[4:7], v[136:139], v[156:159], v[4:7]
	s_add_u32 m0, s30, 0x2000
	v_lshl_add_u64 v[126:127], v[66:67], 0, s[24:25]
	global_load_lds_dwordx4 v[126:127], off
	v_mfma_f32_16x16x32_bf16 v[8:11], v[136:139], v[160:163], v[8:11]
	s_add_u32 m0, s30, 0x4000
	v_lshl_add_u64 v[124:125], v[68:69], 0, s[24:25]
	global_load_lds_dwordx4 v[124:125], off
	v_mfma_f32_16x16x32_bf16 v[12:15], v[136:139], v[164:167], v[12:15]
	s_add_u32 m0, s30, 0x6000
	v_lshl_add_u64 v[126:127], v[70:71], 0, s[24:25]
	global_load_lds_dwordx4 v[126:127], off
	v_mfma_f32_16x16x32_bf16 v[16:19], v[140:143], v[152:155], v[16:19]
	s_add_u32 m0, s30, 0x8000
	v_lshl_add_u64 v[124:125], v[72:73], 0, s[24:25]
	global_load_lds_dwordx4 v[124:125], off
	v_mfma_f32_16x16x32_bf16 v[20:23], v[140:143], v[156:159], v[20:23]
	s_add_u32 m0, s30, 0xa000
	v_lshl_add_u64 v[126:127], v[74:75], 0, s[24:25]
	global_load_lds_dwordx4 v[126:127], off
	v_mfma_f32_16x16x32_bf16 v[24:27], v[140:143], v[160:163], v[24:27]
	v_mfma_f32_16x16x32_bf16 v[28:31], v[140:143], v[164:167], v[28:31]
	v_mfma_f32_16x16x32_bf16 v[32:35], v[144:147], v[152:155], v[32:35]
	v_mfma_f32_16x16x32_bf16 v[36:39], v[144:147], v[156:159], v[36:39]
	v_mfma_f32_16x16x32_bf16 v[40:43], v[144:147], v[160:163], v[40:43]
	v_mfma_f32_16x16x32_bf16 v[44:47], v[144:147], v[164:167], v[44:47]
	v_mfma_f32_16x16x32_bf16 v[48:51], v[148:151], v[152:155], v[48:51]
	v_mfma_f32_16x16x32_bf16 v[52:55], v[148:151], v[156:159], v[52:55]
	v_mfma_f32_16x16x32_bf16 v[56:59], v[148:151], v[160:163], v[56:59]
	v_mfma_f32_16x16x32_bf16 v[60:63], v[148:151], v[164:167], v[60:63]
	ds_read_b128 v[136:139], v77 offset:49152
	ds_read_b128 v[140:143], v77 offset:51200
	ds_read_b128 v[144:147], v77 offset:53248
	ds_read_b128 v[148:151], v77 offset:55296
	ds_read_b128 v[152:155], v79 offset:49152
	ds_read_b128 v[156:159], v79 offset:51200
	ds_read_b128 v[160:163], v79 offset:53248
	ds_read_b128 v[164:167], v79 offset:55296
	s_waitcnt lgkmcnt(8)
	v_mfma_f32_16x16x32_bf16 v[0:3], v[84:87], v[100:103], v[0:3]
	v_mfma_f32_16x16x32_bf16 v[4:7], v[84:87], v[104:107], v[4:7]
	v_mfma_f32_16x16x32_bf16 v[8:11], v[84:87], v[108:111], v[8:11]
	v_mfma_f32_16x16x32_bf16 v[12:15], v[84:87], v[112:115], v[12:15]
	v_mfma_f32_16x16x32_bf16 v[16:19], v[88:91], v[100:103], v[16:19]
	v_mfma_f32_16x16x32_bf16 v[20:23], v[88:91], v[104:107], v[20:23]
	v_mfma_f32_16x16x32_bf16 v[24:27], v[88:91], v[108:111], v[24:27]
	v_mfma_f32_16x16x32_bf16 v[28:31], v[88:91], v[112:115], v[28:31]
	v_mfma_f32_16x16x32_bf16 v[32:35], v[92:95], v[100:103], v[32:35]
	v_mfma_f32_16x16x32_bf16 v[36:39], v[92:95], v[104:107], v[36:39]
	v_mfma_f32_16x16x32_bf16 v[40:43], v[92:95], v[108:111], v[40:43]
	v_mfma_f32_16x16x32_bf16 v[44:47], v[92:95], v[112:115], v[44:47]
	v_mfma_f32_16x16x32_bf16 v[48:51], v[96:99], v[100:103], v[48:51]
	v_mfma_f32_16x16x32_bf16 v[52:55], v[96:99], v[104:107], v[52:55]
	v_mfma_f32_16x16x32_bf16 v[56:59], v[96:99], v[108:111], v[56:59]
	v_mfma_f32_16x16x32_bf16 v[60:63], v[96:99], v[112:115], v[60:63]
	s_waitcnt vmcnt(6) lgkmcnt(0)
	s_barrier
	ds_read_b128 v[84:87], v80
	ds_read_b128 v[88:91], v80 offset:2048
	ds_read_b128 v[92:95], v80 offset:4096
	ds_read_b128 v[96:99], v80 offset:6144
	ds_read_b128 v[100:103], v82
	ds_read_b128 v[104:107], v82 offset:2048
	ds_read_b128 v[108:111], v82 offset:4096
	ds_read_b128 v[112:115], v82 offset:6144
	v_mfma_f32_16x16x32_bf16 v[0:3], v[136:139], v[152:155], v[0:3]
	s_mov_b32 s24, 0x580
	s_mov_b32 s25, 0
	s_add_u32 m0, s30, 0xc000
	v_lshl_add_u64 v[124:125], v[64:65], 0, s[24:25]
	global_load_lds_dwordx4 v[124:125], off
	v_mfma_f32_16x16x32_bf16 v[4:7], v[136:139], v[156:159], v[4:7]
	s_add_u32 m0, s30, 0xe000
	v_lshl_add_u64 v[126:127], v[66:67], 0, s[24:25]
	global_load_lds_dwordx4 v[126:127], off
	v_mfma_f32_16x16x32_bf16 v[8:11], v[136:139], v[160:163], v[8:11]
	s_add_u32 m0, s30, 0x10000
	v_lshl_add_u64 v[124:125], v[68:69], 0, s[24:25]
	global_load_lds_dwordx4 v[124:125], off
	v_mfma_f32_16x16x32_bf16 v[12:15], v[136:139], v[164:167], v[12:15]
	s_add_u32 m0, s30, 0x12000
	v_lshl_add_u64 v[126:127], v[70:71], 0, s[24:25]
	global_load_lds_dwordx4 v[126:127], off
	v_mfma_f32_16x16x32_bf16 v[16:19], v[140:143], v[152:155], v[16:19]
	s_add_u32 m0, s30, 0x14000
	v_lshl_add_u64 v[124:125], v[72:73], 0, s[24:25]
	global_load_lds_dwordx4 v[124:125], off
	v_mfma_f32_16x16x32_bf16 v[20:23], v[140:143], v[156:159], v[20:23]
	s_add_u32 m0, s30, 0x16000
	v_lshl_add_u64 v[126:127], v[74:75], 0, s[24:25]
	global_load_lds_dwordx4 v[126:127], off
	v_mfma_f32_16x16x32_bf16 v[24:27], v[140:143], v[160:163], v[24:27]
	v_mfma_f32_16x16x32_bf16 v[28:31], v[140:143], v[164:167], v[28:31]
	v_mfma_f32_16x16x32_bf16 v[32:35], v[144:147], v[152:155], v[32:35]
	v_mfma_f32_16x16x32_bf16 v[36:39], v[144:147], v[156:159], v[36:39]
	v_mfma_f32_16x16x32_bf16 v[40:43], v[144:147], v[160:163], v[40:43]
	v_mfma_f32_16x16x32_bf16 v[44:47], v[144:147], v[164:167], v[44:47]
	v_mfma_f32_16x16x32_bf16 v[48:51], v[148:151], v[152:155], v[48:51]
	v_mfma_f32_16x16x32_bf16 v[52:55], v[148:151], v[156:159], v[52:55]
	v_mfma_f32_16x16x32_bf16 v[56:59], v[148:151], v[160:163], v[56:59]
	v_mfma_f32_16x16x32_bf16 v[60:63], v[148:151], v[164:167], v[60:63]
	ds_read_b128 v[136:139], v81
	ds_read_b128 v[140:143], v81 offset:2048
	ds_read_b128 v[144:147], v81 offset:4096
	ds_read_b128 v[148:151], v81 offset:6144
	ds_read_b128 v[152:155], v83
	ds_read_b128 v[156:159], v83 offset:2048
	ds_read_b128 v[160:163], v83 offset:4096
	ds_read_b128 v[164:167], v83 offset:6144
	s_waitcnt lgkmcnt(8)
;     ...
;   if (PART != 2) {
;     GEMM_ISSUE(0, 0);
;     if (nk > 1) GEMM_ISSUE(1, 1);
;   }
;   if (PART == 1) return;
;   int st = 0;
;   for (int kt = 0; kt < nk; ++kt) {
;     if (kt + 1 < nk) asm volatile("s_waitcnt vmcnt(6)" ::: "memory");
;     else asm volatile("s_waitcnt vmcnt(0)" ::: "memory");
;     __builtin_amdgcn_s_barrier();
;     asm volatile("" ::: "memory");
;     if (kt + 2 < nk) { const int st2 = (st >= 1) ? st - 1 : 2; GEMM_ISSUE(kt + 2, st2); }
;     const char* la = lds + st * STAGE_B;
;     const char* lb = la + 32768;
;     const unsigned sa_u = (unsigned)(size_t)la + arow_u, sb_u = (unsigned)(size_t)lb + brow_u;
;     const unsigned a0 = sa_u + co0, a1 = sa_u + co1, a2 = sa_u + co2, a3 = sa_u + co3;
;     const unsigned b0 = sb_u + co0, b1 = sb_u + co1, b2 = sb_u + co2, b3 = sb_u + co3;
;     {
;       bf16x8 p0, p1, q0, q1, u0, u1, w0, w1;
;       asm volatile(
;         "ds_read_b128 %4, %12\n\tds_read_b128 %5, %12 offset:4096\n\tds_read_b128 %6, %16\n\tds_read_b128 %7, %16 offset:4096\n\t"
;         "ds_read_b128 %8, %13\n\tds_read_b128 %9, %13 offset:4096\n\tds_read_b128 %10, %17\n\tds_read_b128 %11, %17 offset:4096\n\t"
;         "s_waitcnt lgkmcnt(4)\n\t"
;         "v_mfma_f32_32x32x16_bf16 %0, %4, %6, %0\n\tv_mfma_f32_32x32x16_bf16 %1, %4, %7, %1\n\tv_mfma_f32_32x32x16_bf16 %2, %5, %6, %2\n\tv_mfma_f32_32x32x16_bf16 %3, %5, %7, %3\n\t"
;         "ds_read_b128 %4, %14\n\tds_read_b128 %5, %14 offset:4096\n\tds_read_b128 %6, %18\n\tds_read_b128 %7, %18 offset:4096\n\t"
;         "s_waitcnt lgkmcnt(4)\n\t"
;         "v_mfma_f32_32x32x16_bf16 %0, %8, %10, %0\n\tv_mfma_f32_32x32x16_bf16 %1, %8, %11, %1\n\tv_mfma_f32_32x32x16_bf16 %2, %9, %10, %2\n\tv_mfma_f32_32x32x16_bf16 %3, %9, %11, %3\n\t"
;         "ds_read_b128 %8, %15\n\tds_read_b128 %9, %15 offset:4096\n\tds_read_b128 %10, %19\n\tds_read_b128 %11, %19 offset:4096\n\t"
;         "s_waitcnt lgkmcnt(4)\n\t"
;         "v_mfma_f32_32x32x16_bf16 %0, %4, %6, %0\n\tv_mfma_f32_32x32x16_bf16 %1, %4, %7, %1\n\tv_mfma_f32_32x32x16_bf16 %2, %5, %6, %2\n\tv_mfma_f32_32x32x16_bf16 %3, %5, %7, %3\n\t"
;         "s_waitcnt lgkmcnt(0)\n\t"
;         "v_mfma_f32_32x32x16_bf16 %0, %8, %10, %0\n\tv_mfma_f32_32x32x16_bf16 %1, %8, %11, %1\n\tv_mfma_f32_32x32x16_bf16 %2, %9, %10, %2\n\tv_mfma_f32_32x32x16_bf16 %3, %9, %11, %3"
	v_mfma_f32_16x16x32_bf16 v[0:3], v[84:87], v[100:103], v[0:3]
	v_mfma_f32_16x16x32_bf16 v[4:7], v[84:87], v[104:107], v[4:7]
	v_mfma_f32_16x16x32_bf16 v[8:11], v[84:87], v[108:111], v[8:11]
	v_mfma_f32_16x16x32_bf16 v[12:15], v[84:87], v[112:115], v[12:15]
	v_mfma_f32_16x16x32_bf16 v[16:19], v[88:91], v[100:103], v[16:19]
	v_mfma_f32_16x16x32_bf16 v[20:23], v[88:91], v[104:107], v[20:23]
	v_mfma_f32_16x16x32_bf16 v[24:27], v[88:91], v[108:111], v[24:27]
	v_mfma_f32_16x16x32_bf16 v[28:31], v[88:91], v[112:115], v[28:31]
	v_mfma_f32_16x16x32_bf16 v[32:35], v[92:95], v[100:103], v[32:35]
	v_mfma_f32_16x16x32_bf16 v[36:39], v[92:95], v[104:107], v[36:39]
	v_mfma_f32_16x16x32_bf16 v[40:43], v[92:95], v[108:111], v[40:43]
	v_mfma_f32_16x16x32_bf16 v[44:47], v[92:95], v[112:115], v[44:47]
	v_mfma_f32_16x16x32_bf16 v[48:51], v[96:99], v[100:103], v[48:51]
	v_mfma_f32_16x16x32_bf16 v[52:55], v[96:99], v[104:107], v[52:55]
	v_mfma_f32_16x16x32_bf16 v[56:59], v[96:99], v[108:111], v[56:59]
	v_mfma_f32_16x16x32_bf16 v[60:63], v[96:99], v[112:115], v[60:63]
	s_waitcnt vmcnt(6) lgkmcnt(0)
	s_barrier
	ds_read_b128 v[84:87], v76
	ds_read_b128 v[88:91], v76 offset:2048
	ds_read_b128 v[92:95], v76 offset:4096
	ds_read_b128 v[96:99], v76 offset:6144
	ds_read_b128 v[100:103], v78
	ds_read_b128 v[104:107], v78 offset:2048
	ds_read_b128 v[108:111], v78 offset:4096
	ds_read_b128 v[112:115], v78 offset:6144
	v_mfma_f32_16x16x32_bf16 v[0:3], v[136:139], v[152:155], v[0:3]
	s_mov_b32 s24, 0x600
	s_mov_b32 s25, 0
	s_add_u32 m0, s30, 0x18000
	v_lshl_add_u64 v[124:125], v[64:65], 0, s[24:25]
	global_load_lds_dwordx4 v[124:125], off
	v_mfma_f32_16x16x32_bf16 v[4:7], v[136:139], v[156:159], v[4:7]
	s_add_u32 m0, s30, 0x1a000
	v_lshl_add_u64 v[126:127], v[66:67], 0, s[24:25]
	global_load_lds_dwordx4 v[126:127], off
	v_mfma_f32_16x16x32_bf16 v[8:11], v[136:139], v[160:163], v[8:11]
	s_add_u32 m0, s30, 0x1c000
	v_lshl_add_u64 v[124:125], v[68:69], 0, s[24:25]
	global_load_lds_dwordx4 v[124:125], off
	v_mfma_f32_16x16x32_bf16 v[12:15], v[136:139], v[164:167], v[12:15]
	s_add_u32 m0, s30, 0x1e000
	v_lshl_add_u64 v[126:127], v[70:71], 0, s[24:25]
	global_load_lds_dwordx4 v[126:127], off
	v_mfma_f32_16x16x32_bf16 v[16:19], v[140:143], v[152:155], v[16:19]
	s_add_u32 m0, s30, 0x20000
	v_lshl_add_u64 v[124:125], v[72:73], 0, s[24:25]
	global_load_lds_dwordx4 v[124:125], off
	v_mfma_f32_16x16x32_bf16 v[20:23], v[140:143], v[156:159], v[20:23]
	s_add_u32 m0, s30, 0x22000
	v_lshl_add_u64 v[126:127], v[74:75], 0, s[24:25]
	global_load_lds_dwordx4 v[126:127], off
	v_mfma_f32_16x16x32_bf16 v[24:27], v[140:143], v[160:163], v[24:27]
	v_mfma_f32_16x16x32_bf16 v[28:31], v[140:143], v[164:167], v[28:31]
	v_mfma_f32_16x16x32_bf16 v[32:35], v[144:147], v[152:155], v[32:35]
	v_mfma_f32_16x16x32_bf16 v[36:39], v[144:147], v[156:159], v[36:39]
	v_mfma_f32_16x16x32_bf16 v[40:43], v[144:147], v[160:163], v[40:43]
	v_mfma_f32_16x16x32_bf16 v[44:47], v[144:147], v[164:167], v[44:47]
	v_mfma_f32_16x16x32_bf16 v[48:51], v[148:151], v[152:155], v[48:51]
	v_mfma_f32_16x16x32_bf16 v[52:55], v[148:151], v[156:159], v[52:55]
	v_mfma_f32_16x16x32_bf16 v[56:59], v[148:151], v[160:163], v[56:59]
	v_mfma_f32_16x16x32_bf16 v[60:63], v[148:151], v[164:167], v[60:63]
	ds_read_b128 v[136:139], v77
	ds_read_b128 v[140:143], v77 offset:2048
	ds_read_b128 v[144:147], v77 offset:4096
	ds_read_b128 v[148:151], v77 offset:6144
	ds_read_b128 v[152:155], v79
	ds_read_b128 v[156:159], v79 offset:2048
	ds_read_b128 v[160:163], v79 offset:4096
	ds_read_b128 v[164:167], v79 offset:6144
	s_waitcnt lgkmcnt(8)
	v_mfma_f32_16x16x32_bf16 v[0:3], v[84:87], v[100:103], v[0:3]
	v_mfma_f32_16x16x32_bf16 v[4:7], v[84:87], v[104:107], v[4:7]
	v_mfma_f32_16x16x32_bf16 v[8:11], v[84:87], v[108:111], v[8:11]
	v_mfma_f32_16x16x32_bf16 v[12:15], v[84:87], v[112:115], v[12:15]
	v_mfma_f32_16x16x32_bf16 v[16:19], v[88:91], v[100:103], v[16:19]
	v_mfma_f32_16x16x32_bf16 v[20:23], v[88:91], v[104:107], v[20:23]
	v_mfma_f32_16x16x32_bf16 v[24:27], v[88:91], v[108:111], v[24:27]
	v_mfma_f32_16x16x32_bf16 v[28:31], v[88:91], v[112:115], v[28:31]
	v_mfma_f32_16x16x32_bf16 v[32:35], v[92:95], v[100:103], v[32:35]
	v_mfma_f32_16x16x32_bf16 v[36:39], v[92:95], v[104:107], v[36:39]
	v_mfma_f32_16x16x32_bf16 v[40:43], v[92:95], v[108:111], v[40:43]
	v_mfma_f32_16x16x32_bf16 v[44:47], v[92:95], v[112:115], v[44:47]
	v_mfma_f32_16x16x32_bf16 v[48:51], v[96:99], v[100:103], v[48:51]
	v_mfma_f32_16x16x32_bf16 v[52:55], v[96:99], v[104:107], v[52:55]
	v_mfma_f32_16x16x32_bf16 v[56:59], v[96:99], v[108:111], v[56:59]
	v_mfma_f32_16x16x32_bf16 v[60:63], v[96:99], v[112:115], v[60:63]
	s_waitcnt vmcnt(6) lgkmcnt(0)
	s_barrier
;     ...
;   if (PART != 2) {
;     GEMM_ISSUE(0, 0);
;     if (nk > 1) GEMM_ISSUE(1, 1);
;   }
;   if (PART == 1) return;
;   int st = 0;
;   for (int kt = 0; kt < nk; ++kt) {
;     if (kt + 1 < nk) asm volatile("s_waitcnt vmcnt(6)" ::: "memory");
;     else asm volatile("s_waitcnt vmcnt(0)" ::: "memory");
;     __builtin_amdgcn_s_barrier();
;     asm volatile("" ::: "memory");
;     if (kt + 2 < nk) { const int st2 = (st >= 1) ? st - 1 : 2; GEMM_ISSUE(kt + 2, st2); }
;     const char* la = lds + st * STAGE_B;
;     const char* lb = la + 32768;
;     const unsigned sa_u = (unsigned)(size_t)la + arow_u, sb_u = (unsigned)(size_t)lb + brow_u;
;     const unsigned a0 = sa_u + co0, a1 = sa_u + co1, a2 = sa_u + co2, a3 = sa_u + co3;
;     const unsigned b0 = sb_u + co0, b1 = sb_u + co1, b2 = sb_u + co2, b3 = sb_u + co3;
;     {
;       bf16x8 p0, p1, q0, q1, u0, u1, w0, w1;
;       asm volatile(
;         "ds_read_b128 %4, %12\n\tds_read_b128 %5, %12 offset:4096\n\tds_read_b128 %6, %16\n\tds_read_b128 %7, %16 offset:4096\n\t"
;         "ds_read_b128 %8, %13\n\tds_read_b128 %9, %13 offset:4096\n\tds_read_b128 %10, %17\n\tds_read_b128 %11, %17 offset:4096\n\t"
;         "s_waitcnt lgkmcnt(4)\n\t"
;         "v_mfma_f32_32x32x16_bf16 %0, %4, %6, %0\n\tv_mfma_f32_32x32x16_bf16 %1, %4, %7, %1\n\tv_mfma_f32_32x32x16_bf16 %2, %5, %6, %2\n\tv_mfma_f32_32x32x16_bf16 %3, %5, %7, %3\n\t"
;         "ds_read_b128 %4, %14\n\tds_read_b128 %5, %14 offset:4096\n\tds_read_b128 %6, %18\n\tds_read_b128 %7, %18 offset:4096\n\t"
;         "s_waitcnt lgkmcnt(4)\n\t"
;         "v_mfma_f32_32x32x16_bf16 %0, %8, %10, %0\n\tv_mfma_f32_32x32x16_bf16 %1, %8, %11, %1\n\tv_mfma_f32_32x32x16_bf16 %2, %9, %10, %2\n\tv_mfma_f32_32x32x16_bf16 %3, %9, %11, %3\n\t"
;         "ds_read_b128 %8, %15\n\tds_read_b128 %9, %15 offset:4096\n\tds_read_b128 %10, %19\n\tds_read_b128 %11, %19 offset:4096\n\t"
;         "s_waitcnt lgkmcnt(4)\n\t"
;         "v_mfma_f32_32x32x16_bf16 %0, %4, %6, %0\n\tv_mfma_f32_32x32x16_bf16 %1, %4, %7, %1\n\tv_mfma_f32_32x32x16_bf16 %2, %5, %6, %2\n\tv_mfma_f32_32x32x16_bf16 %3, %5, %7, %3\n\t"
;         "s_waitcnt lgkmcnt(0)\n\t"
;         "v_mfma_f32_32x32x16_bf16 %0, %8, %10, %0\n\tv_mfma_f32_32x32x16_bf16 %1, %8, %11, %1\n\tv_mfma_f32_32x32x16_bf16 %2, %9, %10, %2\n\tv_mfma_f32_32x32x16_bf16 %3, %9, %11, %3"
	ds_read_b128 v[84:87], v76 offset:49152
	ds_read_b128 v[88:91], v76 offset:51200
	ds_read_b128 v[92:95], v76 offset:53248
	ds_read_b128 v[96:99], v76 offset:55296
	ds_read_b128 v[100:103], v78 offset:49152
	ds_read_b128 v[104:107], v78 offset:51200
	ds_read_b128 v[108:111], v78 offset:53248
	ds_read_b128 v[112:115], v78 offset:55296
	v_mfma_f32_16x16x32_bf16 v[0:3], v[136:139], v[152:155], v[0:3]
	s_mov_b32 s24, 0x680
	s_mov_b32 s25, 0
	s_mov_b32 m0, s30
	v_lshl_add_u64 v[124:125], v[64:65], 0, s[24:25]
	global_load_lds_dwordx4 v[124:125], off
	v_mfma_f32_16x16x32_bf16 v[4:7], v[136:139], v[156:159], v[4:7]
	s_add_u32 m0, s30, 0x2000
	v_lshl_add_u64 v[126:127], v[66:67], 0, s[24:25]
	global_load_lds_dwordx4 v[126:127], off
	v_mfma_f32_16x16x32_bf16 v[8:11], v[136:139], v[160:163], v[8:11]
	s_add_u32 m0, s30, 0x4000
	v_lshl_add_u64 v[124:125], v[68:69], 0, s[24:25]
	global_load_lds_dwordx4 v[124:125], off
	v_mfma_f32_16x16x32_bf16 v[12:15], v[136:139], v[164:167], v[12:15]
	s_add_u32 m0, s30, 0x6000
	v_lshl_add_u64 v[126:127], v[70:71], 0, s[24:25]
	global_load_lds_dwordx4 v[126:127], off
	v_mfma_f32_16x16x32_bf16 v[16:19], v[140:143], v[152:155], v[16:19]
	s_add_u32 m0, s30, 0x8000
	v_lshl_add_u64 v[124:125], v[72:73], 0, s[24:25]
	global_load_lds_dwordx4 v[124:125], off
	v_mfma_f32_16x16x32_bf16 v[20:23], v[140:143], v[156:159], v[20:23]
	s_add_u32 m0, s30, 0xa000
	v_lshl_add_u64 v[126:127], v[74:75], 0, s[24:25]
	global_load_lds_dwordx4 v[126:127], off
	v_mfma_f32_16x16x32_bf16 v[24:27], v[140:143], v[160:163], v[24:27]
	v_mfma_f32_16x16x32_bf16 v[28:31], v[140:143], v[164:167], v[28:31]
	v_mfma_f32_16x16x32_bf16 v[32:35], v[144:147], v[152:155], v[32:35]
	v_mfma_f32_16x16x32_bf16 v[36:39], v[144:147], v[156:159], v[36:39]
	v_mfma_f32_16x16x32_bf16 v[40:43], v[144:147], v[160:163], v[40:43]
	v_mfma_f32_16x16x32_bf16 v[44:47], v[144:147], v[164:167], v[44:47]
	v_mfma_f32_16x16x32_bf16 v[48:51], v[148:151], v[152:155], v[48:51]
	v_mfma_f32_16x16x32_bf16 v[52:55], v[148:151], v[156:159], v[52:55]
	v_mfma_f32_16x16x32_bf16 v[56:59], v[148:151], v[160:163], v[56:59]
	v_mfma_f32_16x16x32_bf16 v[60:63], v[148:151], v[164:167], v[60:63]
	ds_read_b128 v[136:139], v77 offset:49152
	ds_read_b128 v[140:143], v77 offset:51200
	ds_read_b128 v[144:147], v77 offset:53248
	ds_read_b128 v[148:151], v77 offset:55296
	ds_read_b128 v[152:155], v79 offset:49152
	ds_read_b128 v[156:159], v79 offset:51200
	ds_read_b128 v[160:163], v79 offset:53248
	ds_read_b128 v[164:167], v79 offset:55296
	s_waitcnt lgkmcnt(8)
	v_mfma_f32_16x16x32_bf16 v[0:3], v[84:87], v[100:103], v[0:3]
	v_mfma_f32_16x16x32_bf16 v[4:7], v[84:87], v[104:107], v[4:7]
	v_mfma_f32_16x16x32_bf16 v[8:11], v[84:87], v[108:111], v[8:11]
	v_mfma_f32_16x16x32_bf16 v[12:15], v[84:87], v[112:115], v[12:15]
	v_mfma_f32_16x16x32_bf16 v[16:19], v[88:91], v[100:103], v[16:19]
	v_mfma_f32_16x16x32_bf16 v[20:23], v[88:91], v[104:107], v[20:23]
	v_mfma_f32_16x16x32_bf16 v[24:27], v[88:91], v[108:111], v[24:27]
	v_mfma_f32_16x16x32_bf16 v[28:31], v[88:91], v[112:115], v[28:31]
	v_mfma_f32_16x16x32_bf16 v[32:35], v[92:95], v[100:103], v[32:35]
	v_mfma_f32_16x16x32_bf16 v[36:39], v[92:95], v[104:107], v[36:39]
	v_mfma_f32_16x16x32_bf16 v[40:43], v[92:95], v[108:111], v[40:43]
	v_mfma_f32_16x16x32_bf16 v[44:47], v[92:95], v[112:115], v[44:47]
	v_mfma_f32_16x16x32_bf16 v[48:51], v[96:99], v[100:103], v[48:51]
	v_mfma_f32_16x16x32_bf16 v[52:55], v[96:99], v[104:107], v[52:55]
	v_mfma_f32_16x16x32_bf16 v[56:59], v[96:99], v[108:111], v[56:59]
	v_mfma_f32_16x16x32_bf16 v[60:63], v[96:99], v[112:115], v[60:63]
	s_waitcnt vmcnt(6) lgkmcnt(0)
	s_barrier
	ds_read_b128 v[84:87], v80
	ds_read_b128 v[88:91], v80 offset:2048
	ds_read_b128 v[92:95], v80 offset:4096
	ds_read_b128 v[96:99], v80 offset:6144
	ds_read_b128 v[100:103], v82
	ds_read_b128 v[104:107], v82 offset:2048
	ds_read_b128 v[108:111], v82 offset:4096
	ds_read_b128 v[112:115], v82 offset:6144
	v_mfma_f32_16x16x32_bf16 v[0:3], v[136:139], v[152:155], v[0:3]
	s_mov_b32 s24, 0x700
	s_mov_b32 s25, 0
	s_add_u32 m0, s30, 0xc000
	v_lshl_add_u64 v[124:125], v[64:65], 0, s[24:25]
	global_load_lds_dwordx4 v[124:125], off
	v_mfma_f32_16x16x32_bf16 v[4:7], v[136:139], v[156:159], v[4:7]
	s_add_u32 m0, s30, 0xe000
	v_lshl_add_u64 v[126:127], v[66:67], 0, s[24:25]
	global_load_lds_dwordx4 v[126:127], off
	v_mfma_f32_16x16x32_bf16 v[8:11], v[136:139], v[160:163], v[8:11]
	s_add_u32 m0, s30, 0x10000
	v_lshl_add_u64 v[124:125], v[68:69], 0, s[24:25]
	global_load_lds_dwordx4 v[124:125], off
	v_mfma_f32_16x16x32_bf16 v[12:15], v[136:139], v[164:167], v[12:15]
	s_add_u32 m0, s30, 0x12000
	v_lshl_add_u64 v[126:127], v[70:71], 0, s[24:25]
	global_load_lds_dwordx4 v[126:127], off
	v_mfma_f32_16x16x32_bf16 v[16:19], v[140:143], v[152:155], v[16:19]
	s_add_u32 m0, s30, 0x14000
	v_lshl_add_u64 v[124:125], v[72:73], 0, s[24:25]
	global_load_lds_dwordx4 v[124:125], off
	v_mfma_f32_16x16x32_bf16 v[20:23], v[140:143], v[156:159], v[20:23]
	s_add_u32 m0, s30, 0x16000
	v_lshl_add_u64 v[126:127], v[74:75], 0, s[24:25]
	global_load_lds_dwordx4 v[126:127], off
	v_mfma_f32_16x16x32_bf16 v[24:27], v[140:143], v[160:163], v[24:27]
	v_mfma_f32_16x16x32_bf16 v[28:31], v[140:143], v[164:167], v[28:31]
	v_mfma_f32_16x16x32_bf16 v[32:35], v[144:147], v[152:155], v[32:35]
	v_mfma_f32_16x16x32_bf16 v[36:39], v[144:147], v[156:159], v[36:39]
	v_mfma_f32_16x16x32_bf16 v[40:43], v[144:147], v[160:163], v[40:43]
	v_mfma_f32_16x16x32_bf16 v[44:47], v[144:147], v[164:167], v[44:47]
	v_mfma_f32_16x16x32_bf16 v[48:51], v[148:151], v[152:155], v[48:51]
	v_mfma_f32_16x16x32_bf16 v[52:55], v[148:151], v[156:159], v[52:55]
	v_mfma_f32_16x16x32_bf16 v[56:59], v[148:151], v[160:163], v[56:59]
	v_mfma_f32_16x16x32_bf16 v[60:63], v[148:151], v[164:167], v[60:63]
	ds_read_b128 v[136:139], v81
	ds_read_b128 v[140:143], v81 offset:2048
	ds_read_b128 v[144:147], v81 offset:4096
	ds_read_b128 v[148:151], v81 offset:6144
	ds_read_b128 v[152:155], v83
	ds_read_b128 v[156:159], v83 offset:2048
	ds_read_b128 v[160:163], v83 offset:4096
	ds_read_b128 v[164:167], v83 offset:6144
	s_waitcnt lgkmcnt(8)
;     ...
;   if (PART != 2) {
;     GEMM_ISSUE(0, 0);
;     if (nk > 1) GEMM_ISSUE(1, 1);
;   }
;   if (PART == 1) return;
;   int st = 0;
;   for (int kt = 0; kt < nk; ++kt) {
;     if (kt + 1 < nk) asm volatile("s_waitcnt vmcnt(6)" ::: "memory");
;     else asm volatile("s_waitcnt vmcnt(0)" ::: "memory");
;     __builtin_amdgcn_s_barrier();
;     asm volatile("" ::: "memory");
;     if (kt + 2 < nk) { const int st2 = (st >= 1) ? st - 1 : 2; GEMM_ISSUE(kt + 2, st2); }
;     const char* la = lds + st * STAGE_B;
;     const char* lb = la + 32768;
;     const unsigned sa_u = (unsigned)(size_t)la + arow_u, sb_u = (unsigned)(size_t)lb + brow_u;
;     const unsigned a0 = sa_u + co0, a1 = sa_u + co1, a2 = sa_u + co2, a3 = sa_u + co3;
;     const unsigned b0 = sb_u + co0, b1 = sb_u + co1, b2 = sb_u + co2, b3 = sb_u + co3;
;     {
;       bf16x8 p0, p1, q0, q1, u0, u1, w0, w1;
;       asm volatile(
;         "ds_read_b128 %4, %12\n\tds_read_b128 %5, %12 offset:4096\n\tds_read_b128 %6, %16\n\tds_read_b128 %7, %16 offset:4096\n\t"
;         "ds_read_b128 %8, %13\n\tds_read_b128 %9, %13 offset:4096\n\tds_read_b128 %10, %17\n\tds_read_b128 %11, %17 offset:4096\n\t"
;         "s_waitcnt lgkmcnt(4)\n\t"
;         "v_mfma_f32_32x32x16_bf16 %0, %4, %6, %0\n\tv_mfma_f32_32x32x16_bf16 %1, %4, %7, %1\n\tv_mfma_f32_32x32x16_bf16 %2, %5, %6, %2\n\tv_mfma_f32_32x32x16_bf16 %3, %5, %7, %3\n\t"
;         "ds_read_b128 %4, %14\n\tds_read_b128 %5, %14 offset:4096\n\tds_read_b128 %6, %18\n\tds_read_b128 %7, %18 offset:4096\n\t"
;         "s_waitcnt lgkmcnt(4)\n\t"
;         "v_mfma_f32_32x32x16_bf16 %0, %8, %10, %0\n\tv_mfma_f32_32x32x16_bf16 %1, %8, %11, %1\n\tv_mfma_f32_32x32x16_bf16 %2, %9, %10, %2\n\tv_mfma_f32_32x32x16_bf16 %3, %9, %11, %3\n\t"
;         "ds_read_b128 %8, %15\n\tds_read_b128 %9, %15 offset:4096\n\tds_read_b128 %10, %19\n\tds_read_b128 %11, %19 offset:4096\n\t"
;         "s_waitcnt lgkmcnt(4)\n\t"
;         "v_mfma_f32_32x32x16_bf16 %0, %4, %6, %0\n\tv_mfma_f32_32x32x16_bf16 %1, %4, %7, %1\n\tv_mfma_f32_32x32x16_bf16 %2, %5, %6, %2\n\tv_mfma_f32_32x32x16_bf16 %3, %5, %7, %3\n\t"
;         "s_waitcnt lgkmcnt(0)\n\t"
;         "v_mfma_f32_32x32x16_bf16 %0, %8, %10, %0\n\tv_mfma_f32_32x32x16_bf16 %1, %8, %11, %1\n\tv_mfma_f32_32x32x16_bf16 %2, %9, %10, %2\n\tv_mfma_f32_32x32x16_bf16 %3, %9, %11, %3"
	v_mfma_f32_16x16x32_bf16 v[0:3], v[84:87], v[100:103], v[0:3]
	v_mfma_f32_16x16x32_bf16 v[4:7], v[84:87], v[104:107], v[4:7]
	v_mfma_f32_16x16x32_bf16 v[8:11], v[84:87], v[108:111], v[8:11]
	v_mfma_f32_16x16x32_bf16 v[12:15], v[84:87], v[112:115], v[12:15]
	v_mfma_f32_16x16x32_bf16 v[16:19], v[88:91], v[100:103], v[16:19]
	v_mfma_f32_16x16x32_bf16 v[20:23], v[88:91], v[104:107], v[20:23]
	v_mfma_f32_16x16x32_bf16 v[24:27], v[88:91], v[108:111], v[24:27]
	v_mfma_f32_16x16x32_bf16 v[28:31], v[88:91], v[112:115], v[28:31]
	v_mfma_f32_16x16x32_bf16 v[32:35], v[92:95], v[100:103], v[32:35]
	v_mfma_f32_16x16x32_bf16 v[36:39], v[92:95], v[104:107], v[36:39]
	v_mfma_f32_16x16x32_bf16 v[40:43], v[92:95], v[108:111], v[40:43]
	v_mfma_f32_16x16x32_bf16 v[44:47], v[92:95], v[112:115], v[44:47]
	v_mfma_f32_16x16x32_bf16 v[48:51], v[96:99], v[100:103], v[48:51]
	v_mfma_f32_16x16x32_bf16 v[52:55], v[96:99], v[104:107], v[52:55]
	v_mfma_f32_16x16x32_bf16 v[56:59], v[96:99], v[108:111], v[56:59]
	v_mfma_f32_16x16x32_bf16 v[60:63], v[96:99], v[112:115], v[60:63]
	s_waitcnt vmcnt(6) lgkmcnt(0)
	s_barrier
	ds_read_b128 v[84:87], v76
	ds_read_b128 v[88:91], v76 offset:2048
	ds_read_b128 v[92:95], v76 offset:4096
	ds_read_b128 v[96:99], v76 offset:6144
	ds_read_b128 v[100:103], v78
	ds_read_b128 v[104:107], v78 offset:2048
	ds_read_b128 v[108:111], v78 offset:4096
	ds_read_b128 v[112:115], v78 offset:6144
	v_mfma_f32_16x16x32_bf16 v[0:3], v[136:139], v[152:155], v[0:3]
	s_mov_b32 s24, 0x780
	s_mov_b32 s25, 0
	s_add_u32 m0, s30, 0x18000
	v_lshl_add_u64 v[124:125], v[64:65], 0, s[24:25]
	global_load_lds_dwordx4 v[124:125], off
	v_mfma_f32_16x16x32_bf16 v[4:7], v[136:139], v[156:159], v[4:7]
	s_add_u32 m0, s30, 0x1a000
	v_lshl_add_u64 v[126:127], v[66:67], 0, s[24:25]
	global_load_lds_dwordx4 v[126:127], off
	v_mfma_f32_16x16x32_bf16 v[8:11], v[136:139], v[160:163], v[8:11]
	s_add_u32 m0, s30, 0x1c000
	v_lshl_add_u64 v[124:125], v[68:69], 0, s[24:25]
	global_load_lds_dwordx4 v[124:125], off
	v_mfma_f32_16x16x32_bf16 v[12:15], v[136:139], v[164:167], v[12:15]
	s_add_u32 m0, s30, 0x1e000
	v_lshl_add_u64 v[126:127], v[70:71], 0, s[24:25]
	global_load_lds_dwordx4 v[126:127], off
	v_mfma_f32_16x16x32_bf16 v[16:19], v[140:143], v[152:155], v[16:19]
	s_add_u32 m0, s30, 0x20000
	v_lshl_add_u64 v[124:125], v[72:73], 0, s[24:25]
	global_load_lds_dwordx4 v[124:125], off
	v_mfma_f32_16x16x32_bf16 v[20:23], v[140:143], v[156:159], v[20:23]
	s_add_u32 m0, s30, 0x22000
	v_lshl_add_u64 v[126:127], v[74:75], 0, s[24:25]
	global_load_lds_dwordx4 v[126:127], off
	v_mfma_f32_16x16x32_bf16 v[24:27], v[140:143], v[160:163], v[24:27]
	v_mfma_f32_16x16x32_bf16 v[28:31], v[140:143], v[164:167], v[28:31]
	v_mfma_f32_16x16x32_bf16 v[32:35], v[144:147], v[152:155], v[32:35]
	v_mfma_f32_16x16x32_bf16 v[36:39], v[144:147], v[156:159], v[36:39]
	v_mfma_f32_16x16x32_bf16 v[40:43], v[144:147], v[160:163], v[40:43]
	v_mfma_f32_16x16x32_bf16 v[44:47], v[144:147], v[164:167], v[44:47]
	v_mfma_f32_16x16x32_bf16 v[48:51], v[148:151], v[152:155], v[48:51]
	v_mfma_f32_16x16x32_bf16 v[52:55], v[148:151], v[156:159], v[52:55]
	v_mfma_f32_16x16x32_bf16 v[56:59], v[148:151], v[160:163], v[56:59]
	v_mfma_f32_16x16x32_bf16 v[60:63], v[148:151], v[164:167], v[60:63]
	ds_read_b128 v[136:139], v77
	ds_read_b128 v[140:143], v77 offset:2048
	ds_read_b128 v[144:147], v77 offset:4096
	ds_read_b128 v[148:151], v77 offset:6144
	ds_read_b128 v[152:155], v79
	ds_read_b128 v[156:159], v79 offset:2048
	ds_read_b128 v[160:163], v79 offset:4096
	ds_read_b128 v[164:167], v79 offset:6144
	s_waitcnt lgkmcnt(8)
	v_mfma_f32_16x16x32_bf16 v[0:3], v[84:87], v[100:103], v[0:3]
	v_mfma_f32_16x16x32_bf16 v[4:7], v[84:87], v[104:107], v[4:7]
	v_mfma_f32_16x16x32_bf16 v[8:11], v[84:87], v[108:111], v[8:11]
	v_mfma_f32_16x16x32_bf16 v[12:15], v[84:87], v[112:115], v[12:15]
	v_mfma_f32_16x16x32_bf16 v[16:19], v[88:91], v[100:103], v[16:19]
	v_mfma_f32_16x16x32_bf16 v[20:23], v[88:91], v[104:107], v[20:23]
	v_mfma_f32_16x16x32_bf16 v[24:27], v[88:91], v[108:111], v[24:27]
	v_mfma_f32_16x16x32_bf16 v[28:31], v[88:91], v[112:115], v[28:31]
	v_mfma_f32_16x16x32_bf16 v[32:35], v[92:95], v[100:103], v[32:35]
	v_mfma_f32_16x16x32_bf16 v[36:39], v[92:95], v[104:107], v[36:39]
	v_mfma_f32_16x16x32_bf16 v[40:43], v[92:95], v[108:111], v[40:43]
	v_mfma_f32_16x16x32_bf16 v[44:47], v[92:95], v[112:115], v[44:47]
	v_mfma_f32_16x16x32_bf16 v[48:51], v[96:99], v[100:103], v[48:51]
	v_mfma_f32_16x16x32_bf16 v[52:55], v[96:99], v[104:107], v[52:55]
	v_mfma_f32_16x16x32_bf16 v[56:59], v[96:99], v[108:111], v[56:59]
	v_mfma_f32_16x16x32_bf16 v[60:63], v[96:99], v[112:115], v[60:63]
	s_waitcnt vmcnt(6) lgkmcnt(0)
	s_barrier
;     ...
;   if (PART != 2) {
;     GEMM_ISSUE(0, 0);
;     if (nk > 1) GEMM_ISSUE(1, 1);
;   }
;   if (PART == 1) return;
;   int st = 0;
;   for (int kt = 0; kt < nk; ++kt) {
;     if (kt + 1 < nk) asm volatile("s_waitcnt vmcnt(6)" ::: "memory");
;     else asm volatile("s_waitcnt vmcnt(0)" ::: "memory");
;     __builtin_amdgcn_s_barrier();
;     asm volatile("" ::: "memory");
;     if (kt + 2 < nk) { const int st2 = (st >= 1) ? st - 1 : 2; GEMM_ISSUE(kt + 2, st2); }
;     const char* la = lds + st * STAGE_B;
;     const char* lb = la + 32768;
;     const unsigned sa_u = (unsigned)(size_t)la + arow_u, sb_u = (unsigned)(size_t)lb + brow_u;
;     const unsigned a0 = sa_u + co0, a1 = sa_u + co1, a2 = sa_u + co2, a3 = sa_u + co3;
;     const unsigned b0 = sb_u + co0, b1 = sb_u + co1, b2 = sb_u + co2, b3 = sb_u + co3;
;     {
;       bf16x8 p0, p1, q0, q1, u0, u1, w0, w1;
;       asm volatile(
;         "ds_read_b128 %4, %12\n\tds_read_b128 %5, %12 offset:4096\n\tds_read_b128 %6, %16\n\tds_read_b128 %7, %16 offset:4096\n\t"
;         "ds_read_b128 %8, %13\n\tds_read_b128 %9, %13 offset:4096\n\tds_read_b128 %10, %17\n\tds_read_b128 %11, %17 offset:4096\n\t"
;         "s_waitcnt lgkmcnt(4)\n\t"
;         "v_mfma_f32_32x32x16_bf16 %0, %4, %6, %0\n\tv_mfma_f32_32x32x16_bf16 %1, %4, %7, %1\n\tv_mfma_f32_32x32x16_bf16 %2, %5, %6, %2\n\tv_mfma_f32_32x32x16_bf16 %3, %5, %7, %3\n\t"
;         "ds_read_b128 %4, %14\n\tds_read_b128 %5, %14 offset:4096\n\tds_read_b128 %6, %18\n\tds_read_b128 %7, %18 offset:4096\n\t"
;         "s_waitcnt lgkmcnt(4)\n\t"
;         "v_mfma_f32_32x32x16_bf16 %0, %8, %10, %0\n\tv_mfma_f32_32x32x16_bf16 %1, %8, %11, %1\n\tv_mfma_f32_32x32x16_bf16 %2, %9, %10, %2\n\tv_mfma_f32_32x32x16_bf16 %3, %9, %11, %3\n\t"
;         "ds_read_b128 %8, %15\n\tds_read_b128 %9, %15 offset:4096\n\tds_read_b128 %10, %19\n\tds_read_b128 %11, %19 offset:4096\n\t"
;         "s_waitcnt lgkmcnt(4)\n\t"
;         "v_mfma_f32_32x32x16_bf16 %0, %4, %6, %0\n\tv_mfma_f32_32x32x16_bf16 %1, %4, %7, %1\n\tv_mfma_f32_32x32x16_bf16 %2, %5, %6, %2\n\tv_mfma_f32_32x32x16_bf16 %3, %5, %7, %3\n\t"
;         "s_waitcnt lgkmcnt(0)\n\t"
;         "v_mfma_f32_32x32x16_bf16 %0, %8, %10, %0\n\tv_mfma_f32_32x32x16_bf16 %1, %8, %11, %1\n\tv_mfma_f32_32x32x16_bf16 %2, %9, %10, %2\n\tv_mfma_f32_32x32x16_bf16 %3, %9, %11, %3"
	ds_read_b128 v[84:87], v76 offset:49152
	ds_read_b128 v[88:91], v76 offset:51200
	ds_read_b128 v[92:95], v76 offset:53248
	ds_read_b128 v[96:99], v76 offset:55296
	ds_read_b128 v[100:103], v78 offset:49152
	ds_read_b128 v[104:107], v78 offset:51200
	ds_read_b128 v[108:111], v78 offset:53248
	ds_read_b128 v[112:115], v78 offset:55296
	v_mfma_f32_16x16x32_bf16 v[0:3], v[136:139], v[152:155], v[0:3]
	s_add_u32 s24, s56, 0x0
	s_addc_u32 s25, s57, 0
	s_mov_b32 m0, s30
	v_lshl_add_u64 v[124:125], v[64:65], 0, s[24:25]
	global_load_lds_dwordx4 v[124:125], off
	v_mfma_f32_16x16x32_bf16 v[4:7], v[136:139], v[156:159], v[4:7]
	s_add_u32 m0, s30, 0x2000
	v_lshl_add_u64 v[126:127], v[66:67], 0, s[24:25]
	global_load_lds_dwordx4 v[126:127], off
	v_mfma_f32_16x16x32_bf16 v[8:11], v[136:139], v[160:163], v[8:11]
	s_add_u32 m0, s30, 0x4000
	v_lshl_add_u64 v[124:125], v[68:69], 0, s[24:25]
	global_load_lds_dwordx4 v[124:125], off
	v_mfma_f32_16x16x32_bf16 v[12:15], v[136:139], v[164:167], v[12:15]
	s_add_u32 m0, s30, 0x6000
	v_lshl_add_u64 v[126:127], v[70:71], 0, s[24:25]
	global_load_lds_dwordx4 v[126:127], off
	v_mfma_f32_16x16x32_bf16 v[16:19], v[140:143], v[152:155], v[16:19]
	s_add_u32 s24, s58, 0x0
	s_addc_u32 s25, s59, 0
	s_add_u32 m0, s30, 0x8000
	v_lshl_add_u64 v[124:125], v[72:73], 0, s[24:25]
	global_load_lds_dwordx4 v[124:125], off
	v_mfma_f32_16x16x32_bf16 v[20:23], v[140:143], v[156:159], v[20:23]
	s_add_u32 m0, s30, 0xa000
	v_lshl_add_u64 v[126:127], v[74:75], 0, s[24:25]
	global_load_lds_dwordx4 v[126:127], off
	v_mfma_f32_16x16x32_bf16 v[24:27], v[140:143], v[160:163], v[24:27]
	v_mfma_f32_16x16x32_bf16 v[28:31], v[140:143], v[164:167], v[28:31]
	v_mfma_f32_16x16x32_bf16 v[32:35], v[144:147], v[152:155], v[32:35]
	v_mfma_f32_16x16x32_bf16 v[36:39], v[144:147], v[156:159], v[36:39]
	v_mfma_f32_16x16x32_bf16 v[40:43], v[144:147], v[160:163], v[40:43]
	v_mfma_f32_16x16x32_bf16 v[44:47], v[144:147], v[164:167], v[44:47]
	v_mfma_f32_16x16x32_bf16 v[48:51], v[148:151], v[152:155], v[48:51]
	v_mfma_f32_16x16x32_bf16 v[52:55], v[148:151], v[156:159], v[52:55]
	v_mfma_f32_16x16x32_bf16 v[56:59], v[148:151], v[160:163], v[56:59]
	v_mfma_f32_16x16x32_bf16 v[60:63], v[148:151], v[164:167], v[60:63]
	ds_read_b128 v[136:139], v77 offset:49152
	ds_read_b128 v[140:143], v77 offset:51200
	ds_read_b128 v[144:147], v77 offset:53248
	ds_read_b128 v[148:151], v77 offset:55296
	ds_read_b128 v[152:155], v79 offset:49152
	ds_read_b128 v[156:159], v79 offset:51200
	ds_read_b128 v[160:163], v79 offset:53248
	ds_read_b128 v[164:167], v79 offset:55296
	s_waitcnt lgkmcnt(8)
	v_mfma_f32_16x16x32_bf16 v[0:3], v[84:87], v[100:103], v[0:3]
	v_mfma_f32_16x16x32_bf16 v[4:7], v[84:87], v[104:107], v[4:7]
	v_mfma_f32_16x16x32_bf16 v[8:11], v[84:87], v[108:111], v[8:11]
	v_mfma_f32_16x16x32_bf16 v[12:15], v[84:87], v[112:115], v[12:15]
	v_mfma_f32_16x16x32_bf16 v[16:19], v[88:91], v[100:103], v[16:19]
	v_mfma_f32_16x16x32_bf16 v[20:23], v[88:91], v[104:107], v[20:23]
	v_mfma_f32_16x16x32_bf16 v[24:27], v[88:91], v[108:111], v[24:27]
	v_mfma_f32_16x16x32_bf16 v[28:31], v[88:91], v[112:115], v[28:31]
	v_mfma_f32_16x16x32_bf16 v[32:35], v[92:95], v[100:103], v[32:35]
	v_mfma_f32_16x16x32_bf16 v[36:39], v[92:95], v[104:107], v[36:39]
	v_mfma_f32_16x16x32_bf16 v[40:43], v[92:95], v[108:111], v[40:43]
	v_mfma_f32_16x16x32_bf16 v[44:47], v[92:95], v[112:115], v[44:47]
	v_mfma_f32_16x16x32_bf16 v[48:51], v[96:99], v[100:103], v[48:51]
	v_mfma_f32_16x16x32_bf16 v[52:55], v[96:99], v[104:107], v[52:55]
	v_mfma_f32_16x16x32_bf16 v[56:59], v[96:99], v[108:111], v[56:59]
	v_mfma_f32_16x16x32_bf16 v[60:63], v[96:99], v[112:115], v[60:63]
	s_waitcnt vmcnt(6) lgkmcnt(0)
	s_barrier
;     ...
;   if (PART != 2) {
;     GEMM_ISSUE(0, 0);
;     if (nk > 1) GEMM_ISSUE(1, 1);
;   }
;   if (PART == 1) return;
;   int st = 0;
;   for (int kt = 0; kt < nk; ++kt) {
;     if (kt + 1 < nk) asm volatile("s_waitcnt vmcnt(6)" ::: "memory");
;     else asm volatile("s_waitcnt vmcnt(0)" ::: "memory");
;     __builtin_amdgcn_s_barrier();
;     asm volatile("" ::: "memory");
;     if (kt + 2 < nk) { const int st2 = (st >= 1) ? st - 1 : 2; GEMM_ISSUE(kt + 2, st2); }
;     const char* la = lds + st * STAGE_B;
;     const char* lb = la + 32768;
;     const unsigned sa_u = (unsigned)(size_t)la + arow_u, sb_u = (unsigned)(size_t)lb + brow_u;
;     const unsigned a0 = sa_u + co0, a1 = sa_u + co1, a2 = sa_u + co2, a3 = sa_u + co3;
;     const unsigned b0 = sb_u + co0, b1 = sb_u + co1, b2 = sb_u + co2, b3 = sb_u + co3;
;     {
;       bf16x8 p0, p1, q0, q1, u0, u1, w0, w1;
;       asm volatile(
;         "ds_read_b128 %4, %12\n\tds_read_b128 %5, %12 offset:4096\n\tds_read_b128 %6, %16\n\tds_read_b128 %7, %16 offset:4096\n\t"
;         "ds_read_b128 %8, %13\n\tds_read_b128 %9, %13 offset:4096\n\tds_read_b128 %10, %17\n\tds_read_b128 %11, %17 offset:4096\n\t"
;         "s_waitcnt lgkmcnt(4)\n\t"
;         "v_mfma_f32_32x32x16_bf16 %0, %4, %6, %0\n\tv_mfma_f32_32x32x16_bf16 %1, %4, %7, %1\n\tv_mfma_f32_32x32x16_bf16 %2, %5, %6, %2\n\tv_mfma_f32_32x32x16_bf16 %3, %5, %7, %3\n\t"
;         "ds_read_b128 %4, %14\n\tds_read_b128 %5, %14 offset:4096\n\tds_read_b128 %6, %18\n\tds_read_b128 %7, %18 offset:4096\n\t"
;         "s_waitcnt lgkmcnt(4)\n\t"
;         "v_mfma_f32_32x32x16_bf16 %0, %8, %10, %0\n\tv_mfma_f32_32x32x16_bf16 %1, %8, %11, %1\n\tv_mfma_f32_32x32x16_bf16 %2, %9, %10, %2\n\tv_mfma_f32_32x32x16_bf16 %3, %9, %11, %3\n\t"
;         "ds_read_b128 %8, %15\n\tds_read_b128 %9, %15 offset:4096\n\tds_read_b128 %10, %19\n\tds_read_b128 %11, %19 offset:4096\n\t"
;         "s_waitcnt lgkmcnt(4)\n\t"
;         "v_mfma_f32_32x32x16_bf16 %0, %4, %6, %0\n\tv_mfma_f32_32x32x16_bf16 %1, %4, %7, %1\n\tv_mfma_f32_32x32x16_bf16 %2, %5, %6, %2\n\tv_mfma_f32_32x32x16_bf16 %3, %5, %7, %3\n\t"
;         "s_waitcnt lgkmcnt(0)\n\t"
;         "v_mfma_f32_32x32x16_bf16 %0, %8, %10, %0\n\tv_mfma_f32_32x32x16_bf16 %1, %8, %11, %1\n\tv_mfma_f32_32x32x16_bf16 %2, %9, %10, %2\n\tv_mfma_f32_32x32x16_bf16 %3, %9, %11, %3"
	ds_read_b128 v[84:87], v80
	ds_read_b128 v[88:91], v80 offset:2048
	ds_read_b128 v[92:95], v80 offset:4096
	ds_read_b128 v[96:99], v80 offset:6144
	ds_read_b128 v[100:103], v82
	ds_read_b128 v[104:107], v82 offset:2048
	ds_read_b128 v[108:111], v82 offset:4096
	ds_read_b128 v[112:115], v82 offset:6144
	v_mfma_f32_16x16x32_bf16 v[0:3], v[136:139], v[152:155], v[0:3]
	s_add_u32 s24, s56, 0x80
	s_addc_u32 s25, s57, 0
	s_add_u32 m0, s30, 0xc000
	v_lshl_add_u64 v[124:125], v[64:65], 0, s[24:25]
	global_load_lds_dwordx4 v[124:125], off
	v_mfma_f32_16x16x32_bf16 v[4:7], v[136:139], v[156:159], v[4:7]
	s_add_u32 m0, s30, 0xe000
	v_lshl_add_u64 v[126:127], v[66:67], 0, s[24:25]
	global_load_lds_dwordx4 v[126:127], off
	v_mfma_f32_16x16x32_bf16 v[8:11], v[136:139], v[160:163], v[8:11]
	s_add_u32 m0, s30, 0x10000
	v_lshl_add_u64 v[124:125], v[68:69], 0, s[24:25]
	global_load_lds_dwordx4 v[124:125], off
	v_mfma_f32_16x16x32_bf16 v[12:15], v[136:139], v[164:167], v[12:15]
	s_add_u32 m0, s30, 0x12000
	v_lshl_add_u64 v[126:127], v[70:71], 0, s[24:25]
	global_load_lds_dwordx4 v[126:127], off
	v_mfma_f32_16x16x32_bf16 v[16:19], v[140:143], v[152:155], v[16:19]
	s_add_u32 s24, s58, 0x80
	s_addc_u32 s25, s59, 0
	s_add_u32 m0, s30, 0x14000
	v_lshl_add_u64 v[124:125], v[72:73], 0, s[24:25]
	global_load_lds_dwordx4 v[124:125], off
	v_mfma_f32_16x16x32_bf16 v[20:23], v[140:143], v[156:159], v[20:23]
	s_add_u32 m0, s30, 0x16000
	v_lshl_add_u64 v[126:127], v[74:75], 0, s[24:25]
	global_load_lds_dwordx4 v[126:127], off
	v_mfma_f32_16x16x32_bf16 v[24:27], v[140:143], v[160:163], v[24:27]
	v_mfma_f32_16x16x32_bf16 v[28:31], v[140:143], v[164:167], v[28:31]
	v_mfma_f32_16x16x32_bf16 v[32:35], v[144:147], v[152:155], v[32:35]
	v_mfma_f32_16x16x32_bf16 v[36:39], v[144:147], v[156:159], v[36:39]
	v_mfma_f32_16x16x32_bf16 v[40:43], v[144:147], v[160:163], v[40:43]
	v_mfma_f32_16x16x32_bf16 v[44:47], v[144:147], v[164:167], v[44:47]
	v_mfma_f32_16x16x32_bf16 v[48:51], v[148:151], v[152:155], v[48:51]
	v_mfma_f32_16x16x32_bf16 v[52:55], v[148:151], v[156:159], v[52:55]
	v_mfma_f32_16x16x32_bf16 v[56:59], v[148:151], v[160:163], v[56:59]
	v_mfma_f32_16x16x32_bf16 v[60:63], v[148:151], v[164:167], v[60:63]
	ds_read_b128 v[136:139], v81
	ds_read_b128 v[140:143], v81 offset:2048
	ds_read_b128 v[144:147], v81 offset:4096
	ds_read_b128 v[148:151], v81 offset:6144
	ds_read_b128 v[152:155], v83
	ds_read_b128 v[156:159], v83 offset:2048
	ds_read_b128 v[160:163], v83 offset:4096
	ds_read_b128 v[164:167], v83 offset:6144
	s_waitcnt lgkmcnt(8)
	v_mfma_f32_16x16x32_bf16 v[0:3], v[84:87], v[100:103], v[0:3]
	v_mfma_f32_16x16x32_bf16 v[4:7], v[84:87], v[104:107], v[4:7]
	v_mfma_f32_16x16x32_bf16 v[8:11], v[84:87], v[108:111], v[8:11]
	v_mfma_f32_16x16x32_bf16 v[12:15], v[84:87], v[112:115], v[12:15]
	v_mfma_f32_16x16x32_bf16 v[16:19], v[88:91], v[100:103], v[16:19]
	v_mfma_f32_16x16x32_bf16 v[20:23], v[88:91], v[104:107], v[20:23]
	v_mfma_f32_16x16x32_bf16 v[24:27], v[88:91], v[108:111], v[24:27]
	v_mfma_f32_16x16x32_bf16 v[28:31], v[88:91], v[112:115], v[28:31]
	v_mfma_f32_16x16x32_bf16 v[32:35], v[92:95], v[100:103], v[32:35]
	v_mfma_f32_16x16x32_bf16 v[36:39], v[92:95], v[104:107], v[36:39]
	v_mfma_f32_16x16x32_bf16 v[40:43], v[92:95], v[108:111], v[40:43]
	v_mfma_f32_16x16x32_bf16 v[44:47], v[92:95], v[112:115], v[44:47]
	v_mfma_f32_16x16x32_bf16 v[48:51], v[96:99], v[100:103], v[48:51]
	v_mfma_f32_16x16x32_bf16 v[52:55], v[96:99], v[104:107], v[52:55]
	v_mfma_f32_16x16x32_bf16 v[56:59], v[96:99], v[108:111], v[56:59]
	v_mfma_f32_16x16x32_bf16 v[60:63], v[96:99], v[112:115], v[60:63]
	s_waitcnt lgkmcnt(0)
	v_mfma_f32_16x16x32_bf16 v[0:3], v[136:139], v[152:155], v[0:3]
	v_mfma_f32_16x16x32_bf16 v[4:7], v[136:139], v[156:159], v[4:7]
	v_mfma_f32_16x16x32_bf16 v[8:11], v[136:139], v[160:163], v[8:11]
	v_mfma_f32_16x16x32_bf16 v[12:15], v[136:139], v[164:167], v[12:15]
	v_mfma_f32_16x16x32_bf16 v[16:19], v[140:143], v[152:155], v[16:19]
	v_mfma_f32_16x16x32_bf16 v[20:23], v[140:143], v[156:159], v[20:23]
	v_mfma_f32_16x16x32_bf16 v[24:27], v[140:143], v[160:163], v[24:27]
	v_mfma_f32_16x16x32_bf16 v[28:31], v[140:143], v[164:167], v[28:31]
	v_mfma_f32_16x16x32_bf16 v[32:35], v[144:147], v[152:155], v[32:35]
	v_mfma_f32_16x16x32_bf16 v[36:39], v[144:147], v[156:159], v[36:39]
	v_mfma_f32_16x16x32_bf16 v[40:43], v[144:147], v[160:163], v[40:43]
	v_mfma_f32_16x16x32_bf16 v[44:47], v[144:147], v[164:167], v[44:47]
	v_mfma_f32_16x16x32_bf16 v[48:51], v[148:151], v[152:155], v[48:51]
	v_mfma_f32_16x16x32_bf16 v[52:55], v[148:151], v[156:159], v[52:55]
	v_mfma_f32_16x16x32_bf16 v[56:59], v[148:151], v[160:163], v[56:59]
	v_mfma_f32_16x16x32_bf16 v[60:63], v[148:151], v[164:167], v[60:63]
